# K-loops: mid-block s_setprio 0/1 flip pairs removed (on top of barrier and epilogue-table changes)
# speedup vs baseline: 1.0015x; 1.0005x over previous
.LBB0_150:
	ds_read_b128 v[48:51], v214
	ds_read_b128 v[52:55], v214 offset:1024
	ds_read_b128 v[56:59], v214 offset:2048
	ds_read_b128 v[60:63], v214 offset:3072
	ds_read_b128 v[168:171], v215
	ds_read_b128 v[172:175], v215 offset:1024
	ds_read_b128 v[176:179], v215 offset:2048
	ds_read_b128 v[180:183], v215 offset:3072
	s_add_u32 s4, s2, 0xfffc0080
	s_addc_u32 s5, s3, -1
	s_cmp_eq_u32 s89, 12
	s_cselect_b32 s7, s8, s5
	s_cselect_b32 s6, s9, s4
	s_cselect_b32 s5, s79, s88
	s_cselect_b32 s4, s81, s87
	v_lshl_add_u64 v[212:213], s[2:3], 0, v[158:159]
	s_add_i32 m0, s68, 0xc000
	ds_read_b128 v[184:187], v216
	ds_read_b128 v[188:191], v216 offset:1024
	ds_read_b128 v[192:195], v216 offset:2048
	ds_read_b128 v[196:199], v216 offset:3072
	ds_read_b128 v[200:203], v216 offset:4096
	ds_read_b128 v[204:207], v216 offset:5120
	ds_read_b128 v[208:211], v216 offset:6144
	ds_read_b128 v[220:223], v216 offset:7168
	global_load_lds_dwordx4 v[212:213], off
	v_lshl_add_u64 v[212:213], s[2:3], 0, v[160:161]
	s_add_i32 m0, s68, 0xe000
	s_nop 0
	global_load_lds_dwordx4 v[212:213], off
	s_waitcnt vmcnt(8)
	s_waitcnt lgkmcnt(0)
	s_barrier
	s_setprio 1
	s_waitcnt lgkmcnt(0)
	v_mfma_f32_16x16x32_bf16 v[140:143], v[48:51], v[184:187], v[140:143]
	v_mfma_f32_16x16x32_bf16 v[136:139], v[56:59], v[184:187], v[136:139]
	v_mfma_f32_16x16x32_bf16 v[124:127], v[48:51], v[192:195], v[124:127]
	v_mfma_f32_16x16x32_bf16 v[120:123], v[56:59], v[192:195], v[120:123]
	v_mfma_f32_16x16x32_bf16 v[108:111], v[48:51], v[200:203], v[108:111]
	v_mfma_f32_16x16x32_bf16 v[104:107], v[56:59], v[200:203], v[104:107]
	v_mfma_f32_16x16x32_bf16 v[92:95], v[48:51], v[208:211], v[92:95]
	v_mfma_f32_16x16x32_bf16 v[88:91], v[56:59], v[208:211], v[88:91]
	v_mfma_f32_16x16x32_bf16 v[140:143], v[52:55], v[188:191], v[140:143]
	v_mfma_f32_16x16x32_bf16 v[136:139], v[60:63], v[188:191], v[136:139]
	v_mfma_f32_16x16x32_bf16 v[124:127], v[52:55], v[196:199], v[124:127]
	v_mfma_f32_16x16x32_bf16 v[120:123], v[60:63], v[196:199], v[120:123]
	v_mfma_f32_16x16x32_bf16 v[108:111], v[52:55], v[204:207], v[108:111]
	v_mfma_f32_16x16x32_bf16 v[104:107], v[60:63], v[204:207], v[104:107]
	v_mfma_f32_16x16x32_bf16 v[92:95], v[52:55], v[220:223], v[92:95]
	v_mfma_f32_16x16x32_bf16 v[88:91], v[60:63], v[220:223], v[88:91]
	v_mfma_f32_16x16x32_bf16 v[132:135], v[168:171], v[184:187], v[132:135]
	v_mfma_f32_16x16x32_bf16 v[128:131], v[176:179], v[184:187], v[128:131]
	v_mfma_f32_16x16x32_bf16 v[116:119], v[168:171], v[192:195], v[116:119]
	v_mfma_f32_16x16x32_bf16 v[112:115], v[176:179], v[192:195], v[112:115]
	v_mfma_f32_16x16x32_bf16 v[100:103], v[168:171], v[200:203], v[100:103]
	v_mfma_f32_16x16x32_bf16 v[96:99], v[176:179], v[200:203], v[96:99]
	v_mfma_f32_16x16x32_bf16 v[84:87], v[168:171], v[208:211], v[84:87]
	v_mfma_f32_16x16x32_bf16 v[80:83], v[176:179], v[208:211], v[80:83]
	v_mfma_f32_16x16x32_bf16 v[132:135], v[172:175], v[188:191], v[132:135]
	v_mfma_f32_16x16x32_bf16 v[128:131], v[180:183], v[188:191], v[128:131]
	v_mfma_f32_16x16x32_bf16 v[116:119], v[172:175], v[196:199], v[116:119]
	v_mfma_f32_16x16x32_bf16 v[112:115], v[180:183], v[196:199], v[112:115]
	v_mfma_f32_16x16x32_bf16 v[100:103], v[172:175], v[204:207], v[100:103]
	v_mfma_f32_16x16x32_bf16 v[96:99], v[180:183], v[204:207], v[96:99]
	v_mfma_f32_16x16x32_bf16 v[84:87], v[172:175], v[220:223], v[84:87]
	v_mfma_f32_16x16x32_bf16 v[80:83], v[180:183], v[220:223], v[80:83]
	s_setprio 0
	s_barrier
	s_add_i32 s90, s72, s61
	v_lshl_add_u64 v[212:213], s[4:5], 0, v[146:147]
	s_mov_b32 m0, s90
	ds_read_b128 v[184:187], v216 offset:16384
	ds_read_b128 v[188:191], v216 offset:17408
	ds_read_b128 v[192:195], v216 offset:18432
	ds_read_b128 v[196:199], v216 offset:19456
	ds_read_b128 v[200:203], v216 offset:20480
	ds_read_b128 v[204:207], v216 offset:21504
	ds_read_b128 v[208:211], v216 offset:22528
	ds_read_b128 v[220:223], v216 offset:23552
	global_load_lds_dwordx4 v[212:213], off
	s_add_i32 m0, s90, 0x2000
	s_add_u32 s90, s4, 0x40000
	v_lshl_add_u64 v[224:225], s[4:5], 0, v[150:151]
	s_addc_u32 s91, s5, 0
	s_add_i32 s93, s73, s61
	global_load_lds_dwordx4 v[224:225], off
	v_lshl_add_u64 v[226:227], s[90:91], 0, v[146:147]
	s_mov_b32 m0, s93
	v_lshl_add_u64 v[228:229], s[6:7], 0, v[148:149]
	global_load_lds_dwordx4 v[226:227], off
	v_lshl_add_u64 v[226:227], s[90:91], 0, v[150:151]
	s_add_i32 m0, s93, 0x2000
	s_nop 0
	global_load_lds_dwordx4 v[226:227], off
	v_lshl_add_u64 v[226:227], s[6:7], 0, v[144:145]
	s_mov_b32 m0, s68
	s_nop 0
	global_load_lds_dwordx4 v[226:227], off
	s_mov_b32 m0, s69
	s_nop 0
	global_load_lds_dwordx4 v[228:229], off
	s_waitcnt vmcnt(8)
	s_waitcnt lgkmcnt(0)
	s_barrier
	s_setprio 1
	s_waitcnt lgkmcnt(0)
	v_mfma_f32_16x16x32_bf16 v[76:79], v[48:51], v[184:187], v[76:79]
	v_mfma_f32_16x16x32_bf16 v[72:75], v[56:59], v[184:187], v[72:75]
	v_mfma_f32_16x16x32_bf16 v[44:47], v[48:51], v[192:195], v[44:47]
	v_mfma_f32_16x16x32_bf16 v[40:43], v[56:59], v[192:195], v[40:43]
	v_mfma_f32_16x16x32_bf16 v[28:31], v[48:51], v[200:203], v[28:31]
	v_mfma_f32_16x16x32_bf16 v[24:27], v[56:59], v[200:203], v[24:27]
	v_mfma_f32_16x16x32_bf16 v[12:15], v[48:51], v[208:211], v[12:15]
	v_mfma_f32_16x16x32_bf16 v[8:11], v[56:59], v[208:211], v[8:11]
	v_mfma_f32_16x16x32_bf16 v[76:79], v[52:55], v[188:191], v[76:79]
	v_mfma_f32_16x16x32_bf16 v[72:75], v[60:63], v[188:191], v[72:75]
	v_mfma_f32_16x16x32_bf16 v[44:47], v[52:55], v[196:199], v[44:47]
	v_mfma_f32_16x16x32_bf16 v[40:43], v[60:63], v[196:199], v[40:43]
	v_mfma_f32_16x16x32_bf16 v[28:31], v[52:55], v[204:207], v[28:31]
	v_mfma_f32_16x16x32_bf16 v[24:27], v[60:63], v[204:207], v[24:27]
	v_mfma_f32_16x16x32_bf16 v[12:15], v[52:55], v[220:223], v[12:15]
	v_mfma_f32_16x16x32_bf16 v[8:11], v[60:63], v[220:223], v[8:11]
	v_mfma_f32_16x16x32_bf16 v[36:39], v[168:171], v[192:195], v[36:39]
	v_mfma_f32_16x16x32_bf16 v[32:35], v[176:179], v[192:195], v[32:35]
	v_mfma_f32_16x16x32_bf16 v[20:23], v[168:171], v[200:203], v[20:23]
	v_mfma_f32_16x16x32_bf16 v[16:19], v[176:179], v[200:203], v[16:19]
	v_mfma_f32_16x16x32_bf16 v[4:7], v[168:171], v[208:211], v[4:7]
	v_mfma_f32_16x16x32_bf16 v[0:3], v[176:179], v[208:211], v[0:3]
	v_mfma_f32_16x16x32_bf16 v[48:51], v[168:171], v[184:187], v[68:71]
	v_mfma_f32_16x16x32_bf16 v[52:55], v[176:179], v[184:187], v[64:67]
	v_mfma_f32_16x16x32_bf16 v[36:39], v[172:175], v[196:199], v[36:39]
	v_mfma_f32_16x16x32_bf16 v[32:35], v[180:183], v[196:199], v[32:35]
	v_mfma_f32_16x16x32_bf16 v[20:23], v[172:175], v[204:207], v[20:23]
	v_mfma_f32_16x16x32_bf16 v[16:19], v[180:183], v[204:207], v[16:19]
	v_mfma_f32_16x16x32_bf16 v[4:7], v[172:175], v[220:223], v[4:7]
	v_mfma_f32_16x16x32_bf16 v[0:3], v[180:183], v[220:223], v[0:3]
	v_mfma_f32_16x16x32_bf16 v[48:51], v[172:175], v[188:191], v[48:51]
	v_mfma_f32_16x16x32_bf16 v[52:55], v[180:183], v[188:191], v[52:55]
	s_setprio 0
	s_barrier
	s_add_i32 s90, 0, 0x18000
	s_add_i32 s91, 0, 0x1c000
	v_add_u32_e32 v68, s90, v167
	v_add_u32_e32 v154, s91, v167
	ds_read_b128 v[56:59], v68
	ds_read_b128 v[60:63], v68 offset:1024
	ds_read_b128 v[64:67], v68 offset:2048
	ds_read_b128 v[68:71], v68 offset:3072
	ds_read_b128 v[168:171], v154
	ds_read_b128 v[172:175], v154 offset:1024
	ds_read_b128 v[176:179], v154 offset:2048
	ds_read_b128 v[180:183], v154 offset:3072
	s_add_u32 s6, s6, 0x40000
	s_addc_u32 s7, s7, 0
	s_mov_b32 m0, s70
	v_lshl_add_u64 v[230:231], s[6:7], 0, v[144:145]
	ds_read_b128 v[184:187], v216 offset:32768
	ds_read_b128 v[188:191], v216 offset:33792
	ds_read_b128 v[192:195], v216 offset:34816
	ds_read_b128 v[196:199], v216 offset:35840
	ds_read_b128 v[200:203], v216 offset:36864
	ds_read_b128 v[204:207], v216 offset:37888
	ds_read_b128 v[208:211], v216 offset:38912
	ds_read_b128 v[220:223], v216 offset:39936
	global_load_lds_dwordx4 v[230:231], off
	v_lshl_add_u64 v[230:231], s[6:7], 0, v[148:149]
	s_mov_b32 m0, s77
	s_nop 0
	global_load_lds_dwordx4 v[230:231], off
	s_waitcnt vmcnt(8)
	s_waitcnt lgkmcnt(0)
	s_barrier
	s_setprio 1
	s_waitcnt lgkmcnt(0)
	v_mfma_f32_16x16x32_bf16 v[140:143], v[56:59], v[184:187], v[140:143]
	v_mfma_f32_16x16x32_bf16 v[136:139], v[64:67], v[184:187], v[136:139]
	v_mfma_f32_16x16x32_bf16 v[124:127], v[56:59], v[192:195], v[124:127]
	v_mfma_f32_16x16x32_bf16 v[120:123], v[64:67], v[192:195], v[120:123]
	v_mfma_f32_16x16x32_bf16 v[108:111], v[56:59], v[200:203], v[108:111]
	v_mfma_f32_16x16x32_bf16 v[104:107], v[64:67], v[200:203], v[104:107]
	v_mfma_f32_16x16x32_bf16 v[92:95], v[56:59], v[208:211], v[92:95]
	v_mfma_f32_16x16x32_bf16 v[88:91], v[64:67], v[208:211], v[88:91]
	v_mfma_f32_16x16x32_bf16 v[140:143], v[60:63], v[188:191], v[140:143]
	v_mfma_f32_16x16x32_bf16 v[136:139], v[68:71], v[188:191], v[136:139]
	v_mfma_f32_16x16x32_bf16 v[124:127], v[60:63], v[196:199], v[124:127]
	v_mfma_f32_16x16x32_bf16 v[120:123], v[68:71], v[196:199], v[120:123]
	v_mfma_f32_16x16x32_bf16 v[108:111], v[60:63], v[204:207], v[108:111]
	v_mfma_f32_16x16x32_bf16 v[104:107], v[68:71], v[204:207], v[104:107]
	v_mfma_f32_16x16x32_bf16 v[92:95], v[60:63], v[220:223], v[92:95]
	v_mfma_f32_16x16x32_bf16 v[88:91], v[68:71], v[220:223], v[88:91]
	v_mfma_f32_16x16x32_bf16 v[132:135], v[168:171], v[184:187], v[132:135]
	v_mfma_f32_16x16x32_bf16 v[128:131], v[176:179], v[184:187], v[128:131]
	v_mfma_f32_16x16x32_bf16 v[116:119], v[168:171], v[192:195], v[116:119]
	v_mfma_f32_16x16x32_bf16 v[112:115], v[176:179], v[192:195], v[112:115]
	v_mfma_f32_16x16x32_bf16 v[100:103], v[168:171], v[200:203], v[100:103]
	v_mfma_f32_16x16x32_bf16 v[96:99], v[176:179], v[200:203], v[96:99]
	v_mfma_f32_16x16x32_bf16 v[84:87], v[168:171], v[208:211], v[84:87]
	v_mfma_f32_16x16x32_bf16 v[80:83], v[176:179], v[208:211], v[80:83]
	v_mfma_f32_16x16x32_bf16 v[132:135], v[172:175], v[188:191], v[132:135]
	v_mfma_f32_16x16x32_bf16 v[128:131], v[180:183], v[188:191], v[128:131]
	v_mfma_f32_16x16x32_bf16 v[116:119], v[172:175], v[196:199], v[116:119]
	v_mfma_f32_16x16x32_bf16 v[112:115], v[180:183], v[196:199], v[112:115]
	v_mfma_f32_16x16x32_bf16 v[100:103], v[172:175], v[204:207], v[100:103]
	v_mfma_f32_16x16x32_bf16 v[96:99], v[180:183], v[204:207], v[96:99]
	v_mfma_f32_16x16x32_bf16 v[84:87], v[172:175], v[220:223], v[84:87]
	v_mfma_f32_16x16x32_bf16 v[80:83], v[180:183], v[220:223], v[80:83]
	s_setprio 0
	s_barrier
	s_add_i32 s6, s90, s61
	v_lshl_add_u64 v[212:213], v[212:213], 0, s[56:57]
	s_mov_b32 m0, s6
	ds_read_b128 v[184:187], v216 offset:49152
	ds_read_b128 v[188:191], v216 offset:50176
	ds_read_b128 v[192:195], v216 offset:51200
	ds_read_b128 v[196:199], v216 offset:52224
	ds_read_b128 v[200:203], v216 offset:53248
	ds_read_b128 v[204:207], v216 offset:54272
	ds_read_b128 v[208:211], v216 offset:55296
	ds_read_b128 v[220:223], v216 offset:56320
	global_load_lds_dwordx4 v[212:213], off
	s_add_i32 m0, s6, 0x2000
	s_add_u32 s4, s4, 0x40080
	v_lshl_add_u64 v[212:213], v[224:225], 0, s[56:57]
	s_addc_u32 s5, s5, 0
	s_add_i32 s6, s91, s61
	global_load_lds_dwordx4 v[212:213], off
	v_lshl_add_u64 v[212:213], s[4:5], 0, v[146:147]
	s_mov_b32 m0, s6
	s_nop 0
	global_load_lds_dwordx4 v[212:213], off
	v_lshl_add_u64 v[212:213], s[4:5], 0, v[150:151]
	s_add_i32 m0, s6, 0x2000
	s_nop 0
	global_load_lds_dwordx4 v[212:213], off
	v_lshl_add_u64 v[212:213], v[226:227], 0, s[56:57]
	s_mov_b32 m0, s96
	s_nop 0
	global_load_lds_dwordx4 v[212:213], off
	v_lshl_add_u64 v[212:213], v[228:229], 0, s[56:57]
	s_mov_b32 m0, s71
	s_nop 0
	global_load_lds_dwordx4 v[212:213], off
	s_waitcnt vmcnt(8)
	s_waitcnt lgkmcnt(0)
	s_barrier
	s_setprio 1
	s_waitcnt lgkmcnt(0)
	v_mfma_f32_16x16x32_bf16 v[76:79], v[56:59], v[184:187], v[76:79]
	v_mfma_f32_16x16x32_bf16 v[72:75], v[64:67], v[184:187], v[72:75]
	v_mfma_f32_16x16x32_bf16 v[44:47], v[56:59], v[192:195], v[44:47]
	v_mfma_f32_16x16x32_bf16 v[40:43], v[64:67], v[192:195], v[40:43]
	v_mfma_f32_16x16x32_bf16 v[28:31], v[56:59], v[200:203], v[28:31]
	v_mfma_f32_16x16x32_bf16 v[24:27], v[64:67], v[200:203], v[24:27]
	v_mfma_f32_16x16x32_bf16 v[12:15], v[56:59], v[208:211], v[12:15]
	v_mfma_f32_16x16x32_bf16 v[8:11], v[64:67], v[208:211], v[8:11]
	v_mfma_f32_16x16x32_bf16 v[76:79], v[60:63], v[188:191], v[76:79]
	v_mfma_f32_16x16x32_bf16 v[72:75], v[68:71], v[188:191], v[72:75]
	v_mfma_f32_16x16x32_bf16 v[44:47], v[60:63], v[196:199], v[44:47]
	v_mfma_f32_16x16x32_bf16 v[40:43], v[68:71], v[196:199], v[40:43]
	v_mfma_f32_16x16x32_bf16 v[28:31], v[60:63], v[204:207], v[28:31]
	v_mfma_f32_16x16x32_bf16 v[24:27], v[68:71], v[204:207], v[24:27]
	v_mfma_f32_16x16x32_bf16 v[12:15], v[60:63], v[220:223], v[12:15]
	v_mfma_f32_16x16x32_bf16 v[8:11], v[68:71], v[220:223], v[8:11]
	v_mfma_f32_16x16x32_bf16 v[48:51], v[168:171], v[184:187], v[48:51]
	v_mfma_f32_16x16x32_bf16 v[68:71], v[172:175], v[188:191], v[48:51]
	v_mfma_f32_16x16x32_bf16 v[48:51], v[176:179], v[184:187], v[52:55]
	v_mfma_f32_16x16x32_bf16 v[36:39], v[168:171], v[192:195], v[36:39]
	v_mfma_f32_16x16x32_bf16 v[32:35], v[176:179], v[192:195], v[32:35]
	v_mfma_f32_16x16x32_bf16 v[20:23], v[168:171], v[200:203], v[20:23]
	v_mfma_f32_16x16x32_bf16 v[16:19], v[176:179], v[200:203], v[16:19]
	v_mfma_f32_16x16x32_bf16 v[4:7], v[168:171], v[208:211], v[4:7]
	v_mfma_f32_16x16x32_bf16 v[0:3], v[176:179], v[208:211], v[0:3]
	v_mfma_f32_16x16x32_bf16 v[64:67], v[180:183], v[188:191], v[48:51]
	v_mfma_f32_16x16x32_bf16 v[36:39], v[172:175], v[196:199], v[36:39]
	v_mfma_f32_16x16x32_bf16 v[32:35], v[180:183], v[196:199], v[32:35]
	v_mfma_f32_16x16x32_bf16 v[20:23], v[172:175], v[204:207], v[20:23]
	v_mfma_f32_16x16x32_bf16 v[16:19], v[180:183], v[204:207], v[16:19]
	v_mfma_f32_16x16x32_bf16 v[4:7], v[172:175], v[220:223], v[4:7]
	v_mfma_f32_16x16x32_bf16 v[0:3], v[180:183], v[220:223], v[0:3]
	s_setprio 0
	s_barrier
	s_add_i32 s89, s89, 2
	s_add_u32 s2, s2, 0x100
	s_addc_u32 s3, s3, 0
	s_add_u32 s87, s87, 0x100
	s_addc_u32 s88, s88, 0
	s_cmp_gt_u32 s89, 13
	s_cbranch_scc0 .LBB0_150
	s_and_b64 vcc, exec, s[58:59]
	s_cbranch_vccz .LBB0_153
	s_barrier

.LBB0_741:
	ds_read_b128 v[128:131], v187
	ds_read_b128 v[132:135], v187 offset:1024
	ds_read_b128 v[136:139], v187 offset:2048
	ds_read_b128 v[140:143], v187 offset:3072
	ds_read_b128 v[144:147], v188
	ds_read_b128 v[148:151], v188 offset:1024
	ds_read_b128 v[168:171], v188 offset:2048
	ds_read_b128 v[172:175], v188 offset:3072
	s_add_u32 s58, s52, 0xfffc0080
	s_addc_u32 s59, s53, -1
	s_cmp_eq_u32 s83, 12
	s_cselect_b32 s61, s6, s59
	s_cselect_b32 s60, s11, s58
	s_cselect_b32 s59, s13, s82
	s_cselect_b32 s58, s80, s81
	v_lshl_add_u64 v[216:217], s[52:53], 0, v[160:161]
	s_add_i32 m0, s62, 0xc000
	ds_read_b128 v[176:179], v189
	ds_read_b128 v[180:183], v189 offset:1024
	ds_read_b128 v[192:195], v189 offset:2048
	ds_read_b128 v[196:199], v189 offset:3072
	ds_read_b128 v[200:203], v189 offset:4096
	ds_read_b128 v[204:207], v189 offset:5120
	ds_read_b128 v[208:211], v189 offset:6144
	ds_read_b128 v[212:215], v189 offset:7168
	global_load_lds_dwordx4 v[216:217], off
	v_lshl_add_u64 v[216:217], s[52:53], 0, v[162:163]
	s_add_i32 m0, s62, 0xe000
	s_nop 0
	global_load_lds_dwordx4 v[216:217], off
	s_waitcnt vmcnt(8)
	s_waitcnt lgkmcnt(0)
	s_barrier
	s_setprio 1
	s_waitcnt lgkmcnt(0)
	v_mfma_f32_16x16x32_bf16 v[124:127], v[128:131], v[176:179], v[124:127]
	v_mfma_f32_16x16x32_bf16 v[120:123], v[136:139], v[176:179], v[120:123]
	v_mfma_f32_16x16x32_bf16 v[108:111], v[128:131], v[192:195], v[108:111]
	v_mfma_f32_16x16x32_bf16 v[104:107], v[136:139], v[192:195], v[104:107]
	v_mfma_f32_16x16x32_bf16 v[92:95], v[128:131], v[200:203], v[92:95]
	v_mfma_f32_16x16x32_bf16 v[88:91], v[136:139], v[200:203], v[88:91]
	v_mfma_f32_16x16x32_bf16 v[76:79], v[128:131], v[208:211], v[76:79]
	v_mfma_f32_16x16x32_bf16 v[72:75], v[136:139], v[208:211], v[72:75]
	v_mfma_f32_16x16x32_bf16 v[124:127], v[132:135], v[180:183], v[124:127]
	v_mfma_f32_16x16x32_bf16 v[120:123], v[140:143], v[180:183], v[120:123]
	v_mfma_f32_16x16x32_bf16 v[108:111], v[132:135], v[196:199], v[108:111]
	v_mfma_f32_16x16x32_bf16 v[104:107], v[140:143], v[196:199], v[104:107]
	v_mfma_f32_16x16x32_bf16 v[92:95], v[132:135], v[204:207], v[92:95]
	v_mfma_f32_16x16x32_bf16 v[88:91], v[140:143], v[204:207], v[88:91]
	v_mfma_f32_16x16x32_bf16 v[76:79], v[132:135], v[212:215], v[76:79]
	v_mfma_f32_16x16x32_bf16 v[72:75], v[140:143], v[212:215], v[72:75]
	v_mfma_f32_16x16x32_bf16 v[116:119], v[144:147], v[176:179], v[116:119]
	v_mfma_f32_16x16x32_bf16 v[112:115], v[168:171], v[176:179], v[112:115]
	v_mfma_f32_16x16x32_bf16 v[100:103], v[144:147], v[192:195], v[100:103]
	v_mfma_f32_16x16x32_bf16 v[96:99], v[168:171], v[192:195], v[96:99]
	v_mfma_f32_16x16x32_bf16 v[84:87], v[144:147], v[200:203], v[84:87]
	v_mfma_f32_16x16x32_bf16 v[80:83], v[168:171], v[200:203], v[80:83]
	v_mfma_f32_16x16x32_bf16 v[68:71], v[144:147], v[208:211], v[68:71]
	v_mfma_f32_16x16x32_bf16 v[64:67], v[168:171], v[208:211], v[64:67]
	v_mfma_f32_16x16x32_bf16 v[116:119], v[148:151], v[180:183], v[116:119]
	v_mfma_f32_16x16x32_bf16 v[112:115], v[172:175], v[180:183], v[112:115]
	v_mfma_f32_16x16x32_bf16 v[100:103], v[148:151], v[196:199], v[100:103]
	v_mfma_f32_16x16x32_bf16 v[96:99], v[172:175], v[196:199], v[96:99]
	v_mfma_f32_16x16x32_bf16 v[84:87], v[148:151], v[204:207], v[84:87]
	v_mfma_f32_16x16x32_bf16 v[80:83], v[172:175], v[204:207], v[80:83]
	v_mfma_f32_16x16x32_bf16 v[68:71], v[148:151], v[212:215], v[68:71]
	v_mfma_f32_16x16x32_bf16 v[64:67], v[172:175], v[212:215], v[64:67]
	s_setprio 0
	s_barrier
	s_add_i32 s84, s71, s57
	v_lshl_add_u64 v[216:217], s[58:59], 0, v[154:155]
	s_mov_b32 m0, s84
	ds_read_b128 v[176:179], v189 offset:16384
	ds_read_b128 v[180:183], v189 offset:17408
	ds_read_b128 v[192:195], v189 offset:18432
	ds_read_b128 v[196:199], v189 offset:19456
	ds_read_b128 v[200:203], v189 offset:20480
	ds_read_b128 v[204:207], v189 offset:21504
	ds_read_b128 v[208:211], v189 offset:22528
	ds_read_b128 v[212:215], v189 offset:23552
	global_load_lds_dwordx4 v[216:217], off
	s_add_i32 m0, s84, 0x2000
	s_add_u32 s84, s58, 0x40000
	v_lshl_add_u64 v[218:219], s[58:59], 0, v[158:159]
	s_addc_u32 s85, s59, 0
	s_add_i32 s86, s72, s57
	global_load_lds_dwordx4 v[218:219], off
	v_lshl_add_u64 v[220:221], s[84:85], 0, v[154:155]
	s_mov_b32 m0, s86
	v_lshl_add_u64 v[222:223], s[60:61], 0, v[156:157]
	global_load_lds_dwordx4 v[220:221], off
	v_lshl_add_u64 v[220:221], s[84:85], 0, v[158:159]
	s_add_i32 m0, s86, 0x2000
	s_nop 0
	global_load_lds_dwordx4 v[220:221], off
	v_lshl_add_u64 v[220:221], s[60:61], 0, v[152:153]
	s_mov_b32 m0, s62
	s_nop 0
	global_load_lds_dwordx4 v[220:221], off
	s_mov_b32 m0, s63
	s_nop 0
	global_load_lds_dwordx4 v[222:223], off
	s_waitcnt vmcnt(8)
	s_waitcnt lgkmcnt(0)
	s_barrier
	s_setprio 1
	s_waitcnt lgkmcnt(0)
	v_mfma_f32_16x16x32_bf16 v[60:63], v[128:131], v[176:179], v[60:63]
	v_mfma_f32_16x16x32_bf16 v[56:59], v[136:139], v[176:179], v[56:59]
	v_mfma_f32_16x16x32_bf16 v[44:47], v[128:131], v[192:195], v[44:47]
	v_mfma_f32_16x16x32_bf16 v[40:43], v[136:139], v[192:195], v[40:43]
	v_mfma_f32_16x16x32_bf16 v[28:31], v[128:131], v[200:203], v[28:31]
	v_mfma_f32_16x16x32_bf16 v[24:27], v[136:139], v[200:203], v[24:27]
	v_mfma_f32_16x16x32_bf16 v[12:15], v[128:131], v[208:211], v[12:15]
	v_mfma_f32_16x16x32_bf16 v[8:11], v[136:139], v[208:211], v[8:11]
	v_mfma_f32_16x16x32_bf16 v[60:63], v[132:135], v[180:183], v[60:63]
	v_mfma_f32_16x16x32_bf16 v[56:59], v[140:143], v[180:183], v[56:59]
	v_mfma_f32_16x16x32_bf16 v[44:47], v[132:135], v[196:199], v[44:47]
	v_mfma_f32_16x16x32_bf16 v[40:43], v[140:143], v[196:199], v[40:43]
	v_mfma_f32_16x16x32_bf16 v[28:31], v[132:135], v[204:207], v[28:31]
	v_mfma_f32_16x16x32_bf16 v[24:27], v[140:143], v[204:207], v[24:27]
	v_mfma_f32_16x16x32_bf16 v[12:15], v[132:135], v[212:215], v[12:15]
	v_mfma_f32_16x16x32_bf16 v[8:11], v[140:143], v[212:215], v[8:11]
	v_mfma_f32_16x16x32_bf16 v[52:55], v[144:147], v[176:179], v[52:55]
	v_mfma_f32_16x16x32_bf16 v[48:51], v[168:171], v[176:179], v[48:51]
	v_mfma_f32_16x16x32_bf16 v[36:39], v[144:147], v[192:195], v[36:39]
	v_mfma_f32_16x16x32_bf16 v[32:35], v[168:171], v[192:195], v[32:35]
	v_mfma_f32_16x16x32_bf16 v[20:23], v[144:147], v[200:203], v[20:23]
	v_mfma_f32_16x16x32_bf16 v[16:19], v[168:171], v[200:203], v[16:19]
	v_mfma_f32_16x16x32_bf16 v[4:7], v[144:147], v[208:211], v[4:7]
	v_mfma_f32_16x16x32_bf16 v[0:3], v[168:171], v[208:211], v[0:3]
	v_mfma_f32_16x16x32_bf16 v[52:55], v[148:151], v[180:183], v[52:55]
	v_mfma_f32_16x16x32_bf16 v[48:51], v[172:175], v[180:183], v[48:51]
	v_mfma_f32_16x16x32_bf16 v[36:39], v[148:151], v[196:199], v[36:39]
	v_mfma_f32_16x16x32_bf16 v[32:35], v[172:175], v[196:199], v[32:35]
	v_mfma_f32_16x16x32_bf16 v[20:23], v[148:151], v[204:207], v[20:23]
	v_mfma_f32_16x16x32_bf16 v[16:19], v[172:175], v[204:207], v[16:19]
	v_mfma_f32_16x16x32_bf16 v[4:7], v[148:151], v[212:215], v[4:7]
	v_mfma_f32_16x16x32_bf16 v[0:3], v[172:175], v[212:215], v[0:3]
	s_setprio 0
	s_barrier
	s_add_i32 s84, 0, 0x18000
	s_add_i32 s85, 0, 0x1c000
	v_add_u32_e32 v140, s84, v185
	v_add_u32_e32 v172, s85, v185
	ds_read_b128 v[128:131], v140
	ds_read_b128 v[132:135], v140 offset:1024
	ds_read_b128 v[136:139], v140 offset:2048
	ds_read_b128 v[140:143], v140 offset:3072
	ds_read_b128 v[144:147], v172
	ds_read_b128 v[148:151], v172 offset:1024
	ds_read_b128 v[168:171], v172 offset:2048
	ds_read_b128 v[172:175], v172 offset:3072
	s_add_u32 s60, s60, 0x40000
	s_addc_u32 s61, s61, 0
	s_mov_b32 m0, s64
	v_lshl_add_u64 v[224:225], s[60:61], 0, v[152:153]
	ds_read_b128 v[176:179], v189 offset:32768
	ds_read_b128 v[180:183], v189 offset:33792
	ds_read_b128 v[192:195], v189 offset:34816
	ds_read_b128 v[196:199], v189 offset:35840
	ds_read_b128 v[200:203], v189 offset:36864
	ds_read_b128 v[204:207], v189 offset:37888
	ds_read_b128 v[208:211], v189 offset:38912
	ds_read_b128 v[212:215], v189 offset:39936
	global_load_lds_dwordx4 v[224:225], off
	v_lshl_add_u64 v[224:225], s[60:61], 0, v[156:157]
	s_mov_b32 m0, s65
	s_nop 0
	global_load_lds_dwordx4 v[224:225], off
	s_waitcnt vmcnt(8)
	s_waitcnt lgkmcnt(0)
	s_barrier
	s_setprio 1
	s_waitcnt lgkmcnt(0)
	v_mfma_f32_16x16x32_bf16 v[124:127], v[128:131], v[176:179], v[124:127]
	v_mfma_f32_16x16x32_bf16 v[120:123], v[136:139], v[176:179], v[120:123]
	v_mfma_f32_16x16x32_bf16 v[108:111], v[128:131], v[192:195], v[108:111]
	v_mfma_f32_16x16x32_bf16 v[104:107], v[136:139], v[192:195], v[104:107]
	v_mfma_f32_16x16x32_bf16 v[92:95], v[128:131], v[200:203], v[92:95]
	v_mfma_f32_16x16x32_bf16 v[88:91], v[136:139], v[200:203], v[88:91]
	v_mfma_f32_16x16x32_bf16 v[76:79], v[128:131], v[208:211], v[76:79]
	v_mfma_f32_16x16x32_bf16 v[72:75], v[136:139], v[208:211], v[72:75]
	v_mfma_f32_16x16x32_bf16 v[124:127], v[132:135], v[180:183], v[124:127]
	v_mfma_f32_16x16x32_bf16 v[120:123], v[140:143], v[180:183], v[120:123]
	v_mfma_f32_16x16x32_bf16 v[108:111], v[132:135], v[196:199], v[108:111]
	v_mfma_f32_16x16x32_bf16 v[104:107], v[140:143], v[196:199], v[104:107]
	v_mfma_f32_16x16x32_bf16 v[92:95], v[132:135], v[204:207], v[92:95]
	v_mfma_f32_16x16x32_bf16 v[88:91], v[140:143], v[204:207], v[88:91]
	v_mfma_f32_16x16x32_bf16 v[76:79], v[132:135], v[212:215], v[76:79]
	v_mfma_f32_16x16x32_bf16 v[72:75], v[140:143], v[212:215], v[72:75]
	v_mfma_f32_16x16x32_bf16 v[116:119], v[144:147], v[176:179], v[116:119]
	v_mfma_f32_16x16x32_bf16 v[112:115], v[168:171], v[176:179], v[112:115]
	v_mfma_f32_16x16x32_bf16 v[100:103], v[144:147], v[192:195], v[100:103]
	v_mfma_f32_16x16x32_bf16 v[96:99], v[168:171], v[192:195], v[96:99]
	v_mfma_f32_16x16x32_bf16 v[84:87], v[144:147], v[200:203], v[84:87]
	v_mfma_f32_16x16x32_bf16 v[80:83], v[168:171], v[200:203], v[80:83]
	v_mfma_f32_16x16x32_bf16 v[68:71], v[144:147], v[208:211], v[68:71]
	v_mfma_f32_16x16x32_bf16 v[64:67], v[168:171], v[208:211], v[64:67]
	v_mfma_f32_16x16x32_bf16 v[116:119], v[148:151], v[180:183], v[116:119]
	v_mfma_f32_16x16x32_bf16 v[112:115], v[172:175], v[180:183], v[112:115]
	v_mfma_f32_16x16x32_bf16 v[100:103], v[148:151], v[196:199], v[100:103]
	v_mfma_f32_16x16x32_bf16 v[96:99], v[172:175], v[196:199], v[96:99]
	v_mfma_f32_16x16x32_bf16 v[84:87], v[148:151], v[204:207], v[84:87]
	v_mfma_f32_16x16x32_bf16 v[80:83], v[172:175], v[204:207], v[80:83]
	v_mfma_f32_16x16x32_bf16 v[68:71], v[148:151], v[212:215], v[68:71]
	v_mfma_f32_16x16x32_bf16 v[64:67], v[172:175], v[212:215], v[64:67]
	s_setprio 0
	s_barrier
	s_add_i32 s60, s84, s57
	v_lshl_add_u64 v[216:217], v[216:217], 0, s[8:9]
	s_mov_b32 m0, s60
	ds_read_b128 v[176:179], v189 offset:49152
	ds_read_b128 v[180:183], v189 offset:50176
	ds_read_b128 v[192:195], v189 offset:51200
	ds_read_b128 v[196:199], v189 offset:52224
	ds_read_b128 v[200:203], v189 offset:53248
	ds_read_b128 v[204:207], v189 offset:54272
	ds_read_b128 v[208:211], v189 offset:55296
	ds_read_b128 v[212:215], v189 offset:56320
	global_load_lds_dwordx4 v[216:217], off
	s_add_i32 m0, s60, 0x2000
	s_add_u32 s58, s58, 0x40080
	v_lshl_add_u64 v[216:217], v[218:219], 0, s[8:9]
	s_addc_u32 s59, s59, 0
	s_add_i32 s60, s85, s57
	global_load_lds_dwordx4 v[216:217], off
	v_lshl_add_u64 v[216:217], s[58:59], 0, v[154:155]
	s_mov_b32 m0, s60
	s_nop 0
	global_load_lds_dwordx4 v[216:217], off
	v_lshl_add_u64 v[216:217], s[58:59], 0, v[158:159]
	s_add_i32 m0, s60, 0x2000
	s_nop 0
	global_load_lds_dwordx4 v[216:217], off
	v_lshl_add_u64 v[216:217], v[220:221], 0, s[8:9]
	s_mov_b32 m0, s67
	s_nop 0
	global_load_lds_dwordx4 v[216:217], off
	v_lshl_add_u64 v[216:217], v[222:223], 0, s[8:9]
	s_mov_b32 m0, s68
	s_nop 0
	global_load_lds_dwordx4 v[216:217], off
	s_waitcnt vmcnt(8)
	s_waitcnt lgkmcnt(0)
	s_barrier
	s_setprio 1
	s_waitcnt lgkmcnt(0)
	v_mfma_f32_16x16x32_bf16 v[60:63], v[128:131], v[176:179], v[60:63]
	v_mfma_f32_16x16x32_bf16 v[56:59], v[136:139], v[176:179], v[56:59]
	v_mfma_f32_16x16x32_bf16 v[44:47], v[128:131], v[192:195], v[44:47]
	v_mfma_f32_16x16x32_bf16 v[40:43], v[136:139], v[192:195], v[40:43]
	v_mfma_f32_16x16x32_bf16 v[28:31], v[128:131], v[200:203], v[28:31]
	v_mfma_f32_16x16x32_bf16 v[24:27], v[136:139], v[200:203], v[24:27]
	v_mfma_f32_16x16x32_bf16 v[12:15], v[128:131], v[208:211], v[12:15]
	v_mfma_f32_16x16x32_bf16 v[8:11], v[136:139], v[208:211], v[8:11]
	v_mfma_f32_16x16x32_bf16 v[60:63], v[132:135], v[180:183], v[60:63]
	v_mfma_f32_16x16x32_bf16 v[56:59], v[140:143], v[180:183], v[56:59]
	v_mfma_f32_16x16x32_bf16 v[44:47], v[132:135], v[196:199], v[44:47]
	v_mfma_f32_16x16x32_bf16 v[40:43], v[140:143], v[196:199], v[40:43]
	v_mfma_f32_16x16x32_bf16 v[28:31], v[132:135], v[204:207], v[28:31]
	v_mfma_f32_16x16x32_bf16 v[24:27], v[140:143], v[204:207], v[24:27]
	v_mfma_f32_16x16x32_bf16 v[12:15], v[132:135], v[212:215], v[12:15]
	v_mfma_f32_16x16x32_bf16 v[8:11], v[140:143], v[212:215], v[8:11]
	v_mfma_f32_16x16x32_bf16 v[52:55], v[144:147], v[176:179], v[52:55]
	v_mfma_f32_16x16x32_bf16 v[48:51], v[168:171], v[176:179], v[48:51]
	v_mfma_f32_16x16x32_bf16 v[36:39], v[144:147], v[192:195], v[36:39]
	v_mfma_f32_16x16x32_bf16 v[32:35], v[168:171], v[192:195], v[32:35]
	v_mfma_f32_16x16x32_bf16 v[20:23], v[144:147], v[200:203], v[20:23]
	v_mfma_f32_16x16x32_bf16 v[16:19], v[168:171], v[200:203], v[16:19]
	v_mfma_f32_16x16x32_bf16 v[4:7], v[144:147], v[208:211], v[4:7]
	v_mfma_f32_16x16x32_bf16 v[0:3], v[168:171], v[208:211], v[0:3]
	v_mfma_f32_16x16x32_bf16 v[52:55], v[148:151], v[180:183], v[52:55]
	v_mfma_f32_16x16x32_bf16 v[48:51], v[172:175], v[180:183], v[48:51]
	v_mfma_f32_16x16x32_bf16 v[36:39], v[148:151], v[196:199], v[36:39]
	v_mfma_f32_16x16x32_bf16 v[32:35], v[172:175], v[196:199], v[32:35]
	v_mfma_f32_16x16x32_bf16 v[20:23], v[148:151], v[204:207], v[20:23]
	v_mfma_f32_16x16x32_bf16 v[16:19], v[172:175], v[204:207], v[16:19]
	v_mfma_f32_16x16x32_bf16 v[4:7], v[148:151], v[212:215], v[4:7]
	v_mfma_f32_16x16x32_bf16 v[0:3], v[172:175], v[212:215], v[0:3]
	s_setprio 0
	s_barrier
	s_add_i32 s83, s83, 2
	s_add_u32 s52, s52, 0x100
	s_addc_u32 s53, s53, 0
	s_add_u32 s81, s81, 0x100
	s_addc_u32 s82, s82, 0
	s_cmp_gt_u32 s83, 13
	s_cbranch_scc0 .LBB0_741
	v_lshl_add_u32 v168, s79, 8, v184
	v_lshl_or_b32 v128, s78, 8, v186
	v_ashrrev_i32_e32 v169, 31, v168
	v_ashrrev_i32_e32 v129, 31, v128
	v_lshlrev_b64 v[130:131], 11, v[168:169]
	v_lshl_add_u64 v[130:131], s[34:35], 0, v[130:131]
	v_lshlrev_b64 v[170:171], 1, v[128:129]
	v_lshl_add_u64 v[200:201], v[130:131], 0, v[170:171]
	global_load_dwordx4 v[192:195], v[200:201], off
	global_load_dwordx4 v[196:199], v[200:201], off offset:256
	v_or_b32_e32 v180, 16, v168
	v_or_b32_e32 v176, 32, v168
	v_or_b32_e32 v172, 48, v168
	v_ashrrev_i32_e32 v181, 31, v180
	v_ashrrev_i32_e32 v177, 31, v176
	v_ashrrev_i32_e32 v173, 31, v172
	v_lshlrev_b64 v[128:129], 11, v[180:181]
	v_lshlrev_b64 v[130:131], 11, v[176:177]
	v_lshlrev_b64 v[132:133], 11, v[172:173]
	v_lshl_add_u64 v[128:129], s[34:35], 0, v[128:129]
	v_lshl_add_u64 v[130:131], s[34:35], 0, v[130:131]
	v_lshl_add_u64 v[132:133], s[34:35], 0, v[132:133]
	v_lshl_add_u64 v[182:183], v[128:129], 0, v[170:171]
	v_lshl_add_u64 v[178:179], v[130:131], 0, v[170:171]
	v_lshl_add_u64 v[174:175], v[132:133], 0, v[170:171]
	global_load_dwordx4 v[148:151], v[182:183], off
	global_load_dwordx4 v[144:147], v[182:183], off offset:256
	global_load_dwordx4 v[140:143], v[178:179], off
	global_load_dwordx4 v[136:139], v[178:179], off offset:256
	global_load_dwordx4 v[132:135], v[174:175], off
	global_load_dwordx4 v[128:131], v[174:175], off offset:256
	v_and_b32_e32 v202, 64, v190
	v_xor_b32_e32 v191, 16, v190
	v_add_u32_e32 v202, 64, v202
	v_xor_b32_e32 v203, 32, v190
	v_cmp_lt_i32_e32 vcc, v191, v202
	s_lshl_b32 s52, s78, 2
	s_ashr_i32 s53, s52, 31
	v_cndmask_b32_e32 v191, v190, v191, vcc
	v_cmp_lt_i32_e32 vcc, v203, v202
	v_lshlrev_b32_e32 v191, 2, v191
	s_waitcnt vmcnt(0)
	v_lshlrev_b32_e32 v202, 16, v192
	v_cndmask_b32_e32 v210, v190, v203, vcc
	v_and_b32_e32 v203, 0xffff0000, v192
	v_lshlrev_b32_e32 v192, 16, v193
	v_and_b32_e32 v193, 0xffff0000, v193
	v_lshlrev_b32_e32 v204, 16, v194
	v_and_b32_e32 v205, 0xffff0000, v194
	v_lshlrev_b32_e32 v194, 16, v195
	v_and_b32_e32 v195, 0xffff0000, v195
	v_lshlrev_b32_e32 v206, 16, v196
	v_and_b32_e32 v207, 0xffff0000, v196
	v_lshlrev_b32_e32 v196, 16, v197
	v_and_b32_e32 v197, 0xffff0000, v197
	v_lshlrev_b32_e32 v208, 16, v198
	v_and_b32_e32 v209, 0xffff0000, v198
	v_lshlrev_b32_e32 v198, 16, v199
	v_and_b32_e32 v199, 0xffff0000, v199
	v_pk_add_f32 v[126:127], v[126:127], v[192:193]
	v_pk_add_f32 v[124:125], v[124:125], v[202:203]
	v_pk_add_f32 v[122:123], v[122:123], v[194:195]
	v_pk_add_f32 v[120:121], v[120:121], v[204:205]
	v_pk_add_f32 v[118:119], v[118:119], v[196:197]
	v_pk_add_f32 v[116:117], v[116:117], v[206:207]
	v_pk_add_f32 v[192:193], v[114:115], v[198:199]
	v_pk_add_f32 v[194:195], v[112:113], v[208:209]
	v_cvt_pk_bf16_f32 v112, v124, v125
	v_cvt_pk_bf16_f32 v113, v126, v127
	v_mul_f32_e32 v114, v125, v125
	v_mul_f32_e32 v115, v127, v127
	v_mul_f32_e32 v125, v121, v121
	v_mul_f32_e32 v127, v123, v123
	v_mul_f32_e32 v196, v117, v117
	v_mul_f32_e32 v197, v119, v119
	v_mul_f32_e32 v198, v195, v195
	v_mul_f32_e32 v199, v193, v193
	v_fmac_f32_e32 v114, v124, v124
	v_fmac_f32_e32 v115, v126, v126
	v_fmac_f32_e32 v125, v120, v120
	v_fmac_f32_e32 v127, v122, v122
	v_fmac_f32_e32 v196, v116, v116
	v_fmac_f32_e32 v197, v118, v118
	v_fmac_f32_e32 v198, v194, v194
	v_fmac_f32_e32 v199, v192, v192
	v_add_f32_e32 v114, v114, v115
	v_add_f32_e32 v115, v125, v127
	v_add_f32_e32 v124, v196, v197
	v_add_f32_e32 v125, v198, v199
	v_add_f32_e32 v114, v114, v115
	v_add_f32_e32 v115, v124, v125
	v_add_f32_e32 v124, v114, v115
	ds_bpermute_b32 v125, v191, v124
	v_cvt_pk_bf16_f32 v114, v120, v121
	v_cvt_pk_bf16_f32 v115, v122, v123
	global_store_dwordx4 v[200:201], v[112:115], off
	v_cvt_pk_bf16_f32 v116, v116, v117
	v_cvt_pk_bf16_f32 v117, v118, v119
	s_waitcnt lgkmcnt(0)
	v_add_f32_e32 v113, v124, v125
	v_lshlrev_b32_e32 v112, 2, v210
	ds_bpermute_b32 v114, v112, v113
	v_cvt_pk_bf16_f32 v118, v194, v195
	v_cvt_pk_bf16_f32 v119, v192, v193
	global_store_dwordx4 v[200:201], v[116:119], off offset:256
	s_and_saveexec_b64 s[58:59], s[0:1]
	s_cbranch_execz .LBB0_744
	s_waitcnt lgkmcnt(0)
	v_add_f32_e32 v113, v113, v114
	v_lshlrev_b64 v[114:115], 6, v[168:169]
	v_lshl_add_u64 v[114:115], s[74:75], 0, v[114:115]
	v_lshl_add_u64 v[114:115], s[52:53], 2, v[114:115]
	s_lshl_b32 s6, s66, 2
	v_lshl_add_u64 v[114:115], v[114:115], 0, s[6:7]
	global_store_dword v[114:115], v113, off

.LBB0_876:
	ds_read_b128 v[96:99], v182
	ds_read_b128 v[100:103], v182 offset:1024
	ds_read_b128 v[104:107], v182 offset:2048
	ds_read_b128 v[108:111], v182 offset:3072
	ds_read_b128 v[112:115], v183
	ds_read_b128 v[116:119], v183 offset:1024
	ds_read_b128 v[120:123], v183 offset:2048
	ds_read_b128 v[124:127], v183 offset:3072
	s_add_u32 s88, s86, 0xfff80080
	s_addc_u32 s89, s87, -1
	s_cmp_eq_u32 s68, 12
	s_cselect_b32 s91, s3, s5
	s_cselect_b32 s90, s61, s4
	s_cselect_b32 s89, s65, s89
	s_cselect_b32 s88, s73, s88
	v_lshl_add_u64 v[168:169], s[86:87], 0, v[142:143]
	s_add_i32 m0, s41, 0xc000
	ds_read_b128 v[128:131], v184
	ds_read_b128 v[150:153], v184 offset:1024
	ds_read_b128 v[154:157], v184 offset:2048
	ds_read_b128 v[158:161], v184 offset:3072
	ds_read_b128 v[162:165], v184 offset:4096
	ds_read_b128 v[176:179], v184 offset:5120
	ds_read_b128 v[188:191], v184 offset:6144
	ds_read_b128 v[192:195], v184 offset:7168
	global_load_lds_dwordx4 v[168:169], off
	v_lshl_add_u64 v[168:169], s[86:87], 0, v[144:145]
	s_add_i32 m0, s41, 0xe000
	s_nop 0
	global_load_lds_dwordx4 v[168:169], off
	s_waitcnt vmcnt(8)
	s_waitcnt lgkmcnt(0)
	s_barrier
	s_setprio 1
	s_waitcnt lgkmcnt(0)
	v_mfma_f32_16x16x32_bf16 v[92:95], v[96:99], v[128:131], v[92:95]
	v_mfma_f32_16x16x32_bf16 v[88:91], v[104:107], v[128:131], v[88:91]
	v_mfma_f32_16x16x32_bf16 v[84:87], v[96:99], v[154:157], v[84:87]
	v_mfma_f32_16x16x32_bf16 v[80:83], v[104:107], v[154:157], v[80:83]
	v_mfma_f32_16x16x32_bf16 v[68:71], v[96:99], v[162:165], v[68:71]
	v_mfma_f32_16x16x32_bf16 v[64:67], v[104:107], v[162:165], v[64:67]
	v_mfma_f32_16x16x32_bf16 v[52:55], v[96:99], v[188:191], v[52:55]
	v_mfma_f32_16x16x32_bf16 v[48:51], v[104:107], v[188:191], v[48:51]
	v_mfma_f32_16x16x32_bf16 v[92:95], v[100:103], v[150:153], v[92:95]
	v_mfma_f32_16x16x32_bf16 v[88:91], v[108:111], v[150:153], v[88:91]
	v_mfma_f32_16x16x32_bf16 v[84:87], v[100:103], v[158:161], v[84:87]
	v_mfma_f32_16x16x32_bf16 v[80:83], v[108:111], v[158:161], v[80:83]
	v_mfma_f32_16x16x32_bf16 v[68:71], v[100:103], v[176:179], v[68:71]
	v_mfma_f32_16x16x32_bf16 v[64:67], v[108:111], v[176:179], v[64:67]
	v_mfma_f32_16x16x32_bf16 v[52:55], v[100:103], v[192:195], v[52:55]
	v_mfma_f32_16x16x32_bf16 v[48:51], v[108:111], v[192:195], v[48:51]
	v_mfma_f32_16x16x32_bf16 v[76:79], v[112:115], v[128:131], v[76:79]
	v_mfma_f32_16x16x32_bf16 v[72:75], v[120:123], v[128:131], v[72:75]
	v_mfma_f32_16x16x32_bf16 v[60:63], v[112:115], v[154:157], v[60:63]
	v_mfma_f32_16x16x32_bf16 v[56:59], v[120:123], v[154:157], v[56:59]
	v_mfma_f32_16x16x32_bf16 v[44:47], v[112:115], v[162:165], v[44:47]
	v_mfma_f32_16x16x32_bf16 v[40:43], v[120:123], v[162:165], v[40:43]
	v_mfma_f32_16x16x32_bf16 v[36:39], v[112:115], v[188:191], v[36:39]
	v_mfma_f32_16x16x32_bf16 v[32:35], v[120:123], v[188:191], v[32:35]
	v_mfma_f32_16x16x32_bf16 v[76:79], v[116:119], v[150:153], v[76:79]
	v_mfma_f32_16x16x32_bf16 v[72:75], v[124:127], v[150:153], v[72:75]
	v_mfma_f32_16x16x32_bf16 v[60:63], v[116:119], v[158:161], v[60:63]
	v_mfma_f32_16x16x32_bf16 v[56:59], v[124:127], v[158:161], v[56:59]
	v_mfma_f32_16x16x32_bf16 v[44:47], v[116:119], v[176:179], v[44:47]
	v_mfma_f32_16x16x32_bf16 v[40:43], v[124:127], v[176:179], v[40:43]
	v_mfma_f32_16x16x32_bf16 v[36:39], v[116:119], v[192:195], v[36:39]
	v_mfma_f32_16x16x32_bf16 v[32:35], v[124:127], v[192:195], v[32:35]
	s_setprio 0
	s_barrier
	s_add_i32 s92, s76, s15
	v_lshl_add_u64 v[168:169], s[88:89], 0, v[134:135]
	s_mov_b32 m0, s92
	ds_read_b128 v[96:99], v185 offset:16384
	ds_read_b128 v[100:103], v185 offset:17408
	ds_read_b128 v[104:107], v185 offset:18432
	ds_read_b128 v[108:111], v185 offset:19456
	global_load_lds_dwordx4 v[168:169], off
	s_add_i32 m0, s92, 0x2000
	s_add_u32 s92, s88, 0x40000
	v_lshl_add_u64 v[172:173], s[88:89], 0, v[138:139]
	s_addc_u32 s93, s89, 0
	s_add_i32 vcc_lo, s77, s15
	global_load_lds_dwordx4 v[172:173], off
	v_lshl_add_u64 v[112:113], s[92:93], 0, v[134:135]
	s_mov_b32 m0, vcc_lo
	v_lshl_add_u64 v[180:181], s[90:91], 0, v[132:133]
	global_load_lds_dwordx4 v[112:113], off
	v_lshl_add_u64 v[112:113], s[92:93], 0, v[138:139]
	s_add_i32 m0, vcc_lo, 0x2000
	v_lshl_add_u64 v[196:197], s[90:91], 0, v[136:137]
	global_load_lds_dwordx4 v[112:113], off
	s_mov_b32 m0, s41
	s_nop 0
	global_load_lds_dwordx4 v[180:181], off
	s_mov_b32 m0, s52
	s_nop 0
	global_load_lds_dwordx4 v[196:197], off
	s_waitcnt vmcnt(8)
	s_waitcnt lgkmcnt(0)
	s_barrier
	s_setprio 1
	s_waitcnt lgkmcnt(0)
	v_mfma_f32_16x16x32_bf16 v[28:31], v[96:99], v[128:131], v[28:31]
	v_mfma_f32_16x16x32_bf16 v[24:27], v[104:107], v[128:131], v[24:27]
	v_mfma_f32_16x16x32_bf16 v[20:23], v[96:99], v[154:157], v[20:23]
	v_mfma_f32_16x16x32_bf16 v[16:19], v[104:107], v[154:157], v[16:19]
	v_mfma_f32_16x16x32_bf16 v[12:15], v[96:99], v[162:165], v[12:15]
	v_mfma_f32_16x16x32_bf16 v[8:11], v[104:107], v[162:165], v[8:11]
	v_mfma_f32_16x16x32_bf16 v[4:7], v[96:99], v[188:191], v[4:7]
	v_mfma_f32_16x16x32_bf16 v[0:3], v[104:107], v[188:191], v[0:3]
	v_mfma_f32_16x16x32_bf16 v[28:31], v[100:103], v[150:153], v[28:31]
	v_mfma_f32_16x16x32_bf16 v[24:27], v[108:111], v[150:153], v[24:27]
	v_mfma_f32_16x16x32_bf16 v[20:23], v[100:103], v[158:161], v[20:23]
	v_mfma_f32_16x16x32_bf16 v[16:19], v[108:111], v[158:161], v[16:19]
	v_mfma_f32_16x16x32_bf16 v[12:15], v[100:103], v[176:179], v[12:15]
	v_mfma_f32_16x16x32_bf16 v[8:11], v[108:111], v[176:179], v[8:11]
	v_mfma_f32_16x16x32_bf16 v[4:7], v[100:103], v[192:195], v[4:7]
	v_mfma_f32_16x16x32_bf16 v[0:3], v[108:111], v[192:195], v[0:3]
	s_setprio 0
	s_barrier
	s_add_i32 s92, 0, 0x18000
	s_add_i32 s93, 0, 0x1c000
	v_add_u32_e32 v108, s92, v171
	v_add_u32_e32 v124, s93, v171
	ds_read_b128 v[96:99], v108
	ds_read_b128 v[100:103], v108 offset:1024
	ds_read_b128 v[104:107], v108 offset:2048
	ds_read_b128 v[108:111], v108 offset:3072
	ds_read_b128 v[112:115], v124
	ds_read_b128 v[116:119], v124 offset:1024
	ds_read_b128 v[120:123], v124 offset:2048
	ds_read_b128 v[124:127], v124 offset:3072
	s_add_u32 s90, s88, 0x80000
	s_addc_u32 s91, s89, 0
	s_mov_b32 m0, s53
	v_lshl_add_u64 v[198:199], s[90:91], 0, v[134:135]
	ds_read_b128 v[128:131], v184 offset:32768
	ds_read_b128 v[150:153], v184 offset:33792
	ds_read_b128 v[154:157], v184 offset:34816
	ds_read_b128 v[158:161], v184 offset:35840
	ds_read_b128 v[162:165], v184 offset:36864
	ds_read_b128 v[176:179], v184 offset:37888
	ds_read_b128 v[188:191], v184 offset:38912
	ds_read_b128 v[192:195], v184 offset:39936
	global_load_lds_dwordx4 v[198:199], off
	v_lshl_add_u64 v[198:199], s[90:91], 0, v[138:139]
	s_mov_b32 m0, s54
	s_nop 0
	global_load_lds_dwordx4 v[198:199], off
	s_waitcnt vmcnt(8)
	s_waitcnt lgkmcnt(0)
	s_barrier
	s_setprio 1
	s_waitcnt lgkmcnt(0)
	v_mfma_f32_16x16x32_bf16 v[92:95], v[96:99], v[128:131], v[92:95]
	v_mfma_f32_16x16x32_bf16 v[88:91], v[104:107], v[128:131], v[88:91]
	v_mfma_f32_16x16x32_bf16 v[84:87], v[96:99], v[154:157], v[84:87]
	v_mfma_f32_16x16x32_bf16 v[80:83], v[104:107], v[154:157], v[80:83]
	v_mfma_f32_16x16x32_bf16 v[68:71], v[96:99], v[162:165], v[68:71]
	v_mfma_f32_16x16x32_bf16 v[64:67], v[104:107], v[162:165], v[64:67]
	v_mfma_f32_16x16x32_bf16 v[52:55], v[96:99], v[188:191], v[52:55]
	v_mfma_f32_16x16x32_bf16 v[48:51], v[104:107], v[188:191], v[48:51]
	v_mfma_f32_16x16x32_bf16 v[92:95], v[100:103], v[150:153], v[92:95]
	v_mfma_f32_16x16x32_bf16 v[88:91], v[108:111], v[150:153], v[88:91]
	v_mfma_f32_16x16x32_bf16 v[84:87], v[100:103], v[158:161], v[84:87]
	v_mfma_f32_16x16x32_bf16 v[80:83], v[108:111], v[158:161], v[80:83]
	v_mfma_f32_16x16x32_bf16 v[68:71], v[100:103], v[176:179], v[68:71]
	v_mfma_f32_16x16x32_bf16 v[64:67], v[108:111], v[176:179], v[64:67]
	v_mfma_f32_16x16x32_bf16 v[52:55], v[100:103], v[192:195], v[52:55]
	v_mfma_f32_16x16x32_bf16 v[48:51], v[108:111], v[192:195], v[48:51]
	v_mfma_f32_16x16x32_bf16 v[76:79], v[112:115], v[128:131], v[76:79]
	v_mfma_f32_16x16x32_bf16 v[72:75], v[120:123], v[128:131], v[72:75]
	v_mfma_f32_16x16x32_bf16 v[60:63], v[112:115], v[154:157], v[60:63]
	v_mfma_f32_16x16x32_bf16 v[56:59], v[120:123], v[154:157], v[56:59]
	v_mfma_f32_16x16x32_bf16 v[44:47], v[112:115], v[162:165], v[44:47]
	v_mfma_f32_16x16x32_bf16 v[40:43], v[120:123], v[162:165], v[40:43]
	v_mfma_f32_16x16x32_bf16 v[36:39], v[112:115], v[188:191], v[36:39]
	v_mfma_f32_16x16x32_bf16 v[32:35], v[120:123], v[188:191], v[32:35]
	v_mfma_f32_16x16x32_bf16 v[76:79], v[116:119], v[150:153], v[76:79]
	v_mfma_f32_16x16x32_bf16 v[72:75], v[124:127], v[150:153], v[72:75]
	v_mfma_f32_16x16x32_bf16 v[60:63], v[116:119], v[158:161], v[60:63]
	v_mfma_f32_16x16x32_bf16 v[56:59], v[124:127], v[158:161], v[56:59]
	v_mfma_f32_16x16x32_bf16 v[44:47], v[116:119], v[176:179], v[44:47]
	v_mfma_f32_16x16x32_bf16 v[40:43], v[124:127], v[176:179], v[40:43]
	v_mfma_f32_16x16x32_bf16 v[36:39], v[116:119], v[192:195], v[36:39]
	v_mfma_f32_16x16x32_bf16 v[32:35], v[124:127], v[192:195], v[32:35]
	s_setprio 0
	s_barrier
	s_add_i32 s90, s92, s15
	v_lshl_add_u64 v[112:113], v[168:169], 0, s[10:11]
	s_mov_b32 m0, s90
	ds_read_b128 v[96:99], v185 offset:49152
	ds_read_b128 v[100:103], v185 offset:50176
	ds_read_b128 v[104:107], v185 offset:51200
	ds_read_b128 v[108:111], v185 offset:52224
	global_load_lds_dwordx4 v[112:113], off
	s_add_i32 m0, s90, 0x2000
	s_add_u32 s88, s88, 0x40080
	v_lshl_add_u64 v[112:113], v[172:173], 0, s[10:11]
	s_addc_u32 s89, s89, 0
	s_add_i32 s90, s93, s15
	global_load_lds_dwordx4 v[112:113], off
	v_lshl_add_u64 v[112:113], s[88:89], 0, v[134:135]
	s_mov_b32 m0, s90
	s_nop 0
	global_load_lds_dwordx4 v[112:113], off
	v_lshl_add_u64 v[112:113], s[88:89], 0, v[138:139]
	s_add_i32 m0, s90, 0x2000
	s_nop 0
	global_load_lds_dwordx4 v[112:113], off
	v_lshl_add_u64 v[112:113], v[180:181], 0, s[10:11]
	s_mov_b32 m0, s55
	s_nop 0
	global_load_lds_dwordx4 v[112:113], off
	v_lshl_add_u64 v[112:113], v[196:197], 0, s[10:11]
	s_mov_b32 m0, s56
	s_nop 0
	global_load_lds_dwordx4 v[112:113], off
	s_waitcnt vmcnt(8)
	s_waitcnt lgkmcnt(0)
	s_barrier
	s_setprio 1
	s_waitcnt lgkmcnt(0)
	v_mfma_f32_16x16x32_bf16 v[28:31], v[96:99], v[128:131], v[28:31]
	v_mfma_f32_16x16x32_bf16 v[24:27], v[104:107], v[128:131], v[24:27]
	v_mfma_f32_16x16x32_bf16 v[20:23], v[96:99], v[154:157], v[20:23]
	v_mfma_f32_16x16x32_bf16 v[16:19], v[104:107], v[154:157], v[16:19]
	v_mfma_f32_16x16x32_bf16 v[12:15], v[96:99], v[162:165], v[12:15]
	v_mfma_f32_16x16x32_bf16 v[8:11], v[104:107], v[162:165], v[8:11]
	v_mfma_f32_16x16x32_bf16 v[4:7], v[96:99], v[188:191], v[4:7]
	v_mfma_f32_16x16x32_bf16 v[0:3], v[104:107], v[188:191], v[0:3]
	v_mfma_f32_16x16x32_bf16 v[28:31], v[100:103], v[150:153], v[28:31]
	v_mfma_f32_16x16x32_bf16 v[24:27], v[108:111], v[150:153], v[24:27]
	v_mfma_f32_16x16x32_bf16 v[20:23], v[100:103], v[158:161], v[20:23]
	v_mfma_f32_16x16x32_bf16 v[16:19], v[108:111], v[158:161], v[16:19]
	v_mfma_f32_16x16x32_bf16 v[12:15], v[100:103], v[176:179], v[12:15]
	v_mfma_f32_16x16x32_bf16 v[8:11], v[108:111], v[176:179], v[8:11]
	v_mfma_f32_16x16x32_bf16 v[4:7], v[100:103], v[192:195], v[4:7]
	v_mfma_f32_16x16x32_bf16 v[0:3], v[108:111], v[192:195], v[0:3]
	s_setprio 0
	s_barrier
	s_add_i32 s68, s68, 2
	s_add_u32 s4, s4, 0x100
	s_addc_u32 s5, s5, 0
	s_add_u32 s86, s86, 0x100
	s_addc_u32 s87, s87, 0
	s_cmp_gt_u32 s68, 13
	s_cbranch_scc0 .LBB0_876
	s_mov_b64 s[86:87], 0
	s_branch .LBB0_879

.LBB0_881:
	ds_read_b128 v[128:131], v182
	ds_read_b128 v[150:153], v182 offset:1024
	ds_read_b128 v[154:157], v182 offset:2048
	ds_read_b128 v[158:161], v182 offset:3072
	ds_read_b128 v[162:165], v183
	ds_read_b128 v[176:179], v183 offset:1024
	ds_read_b128 v[188:191], v183 offset:2048
	ds_read_b128 v[192:195], v183 offset:3072
	s_add_u32 s92, s84, 0xfffc0080
	s_addc_u32 s93, s85, -1
	s_cmp_eq_u32 s5, 12
	s_cselect_b64 s[90:91], -1, 0
	s_and_b64 s[88:89], s[90:91], exec
	s_cselect_b32 s89, s65, s71
	s_cselect_b32 s88, s73, s69
	s_cselect_b32 s93, s3, s93
	s_cselect_b32 s92, s61, s92
	v_lshl_add_u64 v[168:169], s[84:85], 0, v[146:147]
	s_add_i32 m0, s41, 0xc000
	ds_read_b128 v[196:199], v184
	ds_read_b128 v[200:203], v184 offset:1024
	ds_read_b128 v[204:207], v184 offset:2048
	ds_read_b128 v[208:211], v184 offset:3072
	ds_read_b128 v[212:215], v184 offset:4096
	ds_read_b128 v[216:219], v184 offset:5120
	ds_read_b128 v[220:223], v184 offset:6144
	ds_read_b128 v[224:227], v184 offset:7168
	global_load_lds_dwordx4 v[168:169], off
	v_lshl_add_u64 v[168:169], s[84:85], 0, v[136:137]
	s_add_i32 m0, s41, 0xe000
	s_nop 0
	global_load_lds_dwordx4 v[168:169], off
	s_waitcnt vmcnt(8)
	s_waitcnt lgkmcnt(0)
	s_barrier
	s_setprio 1
	s_waitcnt lgkmcnt(0)
	v_mfma_f32_16x16x32_bf16 v[92:95], v[128:131], v[196:199], v[92:95]
	v_mfma_f32_16x16x32_bf16 v[88:91], v[154:157], v[196:199], v[88:91]
	v_mfma_f32_16x16x32_bf16 v[84:87], v[128:131], v[204:207], v[84:87]
	v_mfma_f32_16x16x32_bf16 v[80:83], v[154:157], v[204:207], v[80:83]
	v_mfma_f32_16x16x32_bf16 v[68:71], v[128:131], v[212:215], v[68:71]
	v_mfma_f32_16x16x32_bf16 v[64:67], v[154:157], v[212:215], v[64:67]
	v_mfma_f32_16x16x32_bf16 v[52:55], v[128:131], v[220:223], v[52:55]
	v_mfma_f32_16x16x32_bf16 v[48:51], v[154:157], v[220:223], v[48:51]
	v_mfma_f32_16x16x32_bf16 v[92:95], v[150:153], v[200:203], v[92:95]
	v_mfma_f32_16x16x32_bf16 v[88:91], v[158:161], v[200:203], v[88:91]
	v_mfma_f32_16x16x32_bf16 v[84:87], v[150:153], v[208:211], v[84:87]
	v_mfma_f32_16x16x32_bf16 v[80:83], v[158:161], v[208:211], v[80:83]
	v_mfma_f32_16x16x32_bf16 v[68:71], v[150:153], v[216:219], v[68:71]
	v_mfma_f32_16x16x32_bf16 v[64:67], v[158:161], v[216:219], v[64:67]
	v_mfma_f32_16x16x32_bf16 v[52:55], v[150:153], v[224:227], v[52:55]
	v_mfma_f32_16x16x32_bf16 v[48:51], v[158:161], v[224:227], v[48:51]
	v_mfma_f32_16x16x32_bf16 v[76:79], v[162:165], v[196:199], v[76:79]
	v_mfma_f32_16x16x32_bf16 v[72:75], v[188:191], v[196:199], v[72:75]
	v_mfma_f32_16x16x32_bf16 v[60:63], v[162:165], v[204:207], v[60:63]
	v_mfma_f32_16x16x32_bf16 v[56:59], v[188:191], v[204:207], v[56:59]
	v_mfma_f32_16x16x32_bf16 v[44:47], v[162:165], v[212:215], v[44:47]
	v_mfma_f32_16x16x32_bf16 v[40:43], v[188:191], v[212:215], v[40:43]
	v_mfma_f32_16x16x32_bf16 v[36:39], v[162:165], v[220:223], v[36:39]
	v_mfma_f32_16x16x32_bf16 v[32:35], v[188:191], v[220:223], v[32:35]
	v_mfma_f32_16x16x32_bf16 v[76:79], v[176:179], v[200:203], v[76:79]
	v_mfma_f32_16x16x32_bf16 v[72:75], v[192:195], v[200:203], v[72:75]
	v_mfma_f32_16x16x32_bf16 v[60:63], v[176:179], v[208:211], v[60:63]
	v_mfma_f32_16x16x32_bf16 v[56:59], v[192:195], v[208:211], v[56:59]
	v_mfma_f32_16x16x32_bf16 v[44:47], v[176:179], v[216:219], v[44:47]
	v_mfma_f32_16x16x32_bf16 v[40:43], v[192:195], v[216:219], v[40:43]
	v_mfma_f32_16x16x32_bf16 v[36:39], v[176:179], v[224:227], v[36:39]
	v_mfma_f32_16x16x32_bf16 v[32:35], v[192:195], v[224:227], v[32:35]
	s_setprio 0
	s_barrier
	s_add_i32 vcc_lo, s76, s15
	v_lshl_add_u64 v[168:169], s[88:89], 0, v[134:135]
	s_mov_b32 m0, vcc_lo
	ds_read_b128 v[196:199], v184 offset:16384
	ds_read_b128 v[200:203], v184 offset:17408
	ds_read_b128 v[204:207], v184 offset:18432
	ds_read_b128 v[208:211], v184 offset:19456
	ds_read_b128 v[212:215], v184 offset:20480
	ds_read_b128 v[216:219], v184 offset:21504
	ds_read_b128 v[220:223], v184 offset:22528
	ds_read_b128 v[224:227], v184 offset:23552
	global_load_lds_dwordx4 v[168:169], off
	s_add_i32 m0, vcc_lo, 0x2000
	s_add_u32 vcc_lo, s88, 0x40000
	v_lshl_add_u64 v[172:173], s[88:89], 0, v[138:139]
	s_addc_u32 vcc_hi, s89, 0
	s_add_i32 s6, s77, s15
	global_load_lds_dwordx4 v[172:173], off
	v_lshl_add_u64 v[180:181], vcc, 0, v[134:135]
	s_mov_b32 m0, s6
	v_lshl_add_u64 v[228:229], s[92:93], 0, v[136:137]
	global_load_lds_dwordx4 v[180:181], off
	v_lshl_add_u64 v[180:181], vcc, 0, v[138:139]
	s_add_i32 m0, s6, 0x2000
	s_nop 0
	global_load_lds_dwordx4 v[180:181], off
	v_lshl_add_u64 v[180:181], s[92:93], 0, v[132:133]
	s_mov_b32 m0, s41
	s_nop 0
	global_load_lds_dwordx4 v[180:181], off
	s_mov_b32 m0, s52
	s_nop 0
	global_load_lds_dwordx4 v[228:229], off
	s_waitcnt vmcnt(8)
	s_waitcnt lgkmcnt(0)
	s_barrier
	s_setprio 1
	s_waitcnt lgkmcnt(0)
	v_mfma_f32_16x16x32_bf16 v[28:31], v[128:131], v[196:199], v[28:31]
	v_mfma_f32_16x16x32_bf16 v[24:27], v[154:157], v[196:199], v[24:27]
	v_mfma_f32_16x16x32_bf16 v[20:23], v[128:131], v[204:207], v[20:23]
	v_mfma_f32_16x16x32_bf16 v[16:19], v[154:157], v[204:207], v[16:19]
	v_mfma_f32_16x16x32_bf16 v[12:15], v[128:131], v[212:215], v[12:15]
	v_mfma_f32_16x16x32_bf16 v[8:11], v[154:157], v[212:215], v[8:11]
	v_mfma_f32_16x16x32_bf16 v[4:7], v[128:131], v[220:223], v[4:7]
	v_mfma_f32_16x16x32_bf16 v[0:3], v[154:157], v[220:223], v[0:3]
	v_mfma_f32_16x16x32_bf16 v[28:31], v[150:153], v[200:203], v[28:31]
	v_mfma_f32_16x16x32_bf16 v[24:27], v[158:161], v[200:203], v[24:27]
	v_mfma_f32_16x16x32_bf16 v[20:23], v[150:153], v[208:211], v[20:23]
	v_mfma_f32_16x16x32_bf16 v[16:19], v[158:161], v[208:211], v[16:19]
	v_mfma_f32_16x16x32_bf16 v[12:15], v[150:153], v[216:219], v[12:15]
	v_mfma_f32_16x16x32_bf16 v[8:11], v[158:161], v[216:219], v[8:11]
	v_mfma_f32_16x16x32_bf16 v[4:7], v[150:153], v[224:227], v[4:7]
	v_mfma_f32_16x16x32_bf16 v[0:3], v[158:161], v[224:227], v[0:3]
	v_mfma_f32_16x16x32_bf16 v[124:127], v[162:165], v[196:199], v[124:127]
	v_mfma_f32_16x16x32_bf16 v[120:123], v[188:191], v[196:199], v[120:123]
	v_mfma_f32_16x16x32_bf16 v[116:119], v[162:165], v[204:207], v[116:119]
	v_mfma_f32_16x16x32_bf16 v[112:115], v[188:191], v[204:207], v[112:115]
	v_mfma_f32_16x16x32_bf16 v[108:111], v[162:165], v[212:215], v[108:111]
	v_mfma_f32_16x16x32_bf16 v[104:107], v[188:191], v[212:215], v[104:107]
	v_mfma_f32_16x16x32_bf16 v[100:103], v[162:165], v[220:223], v[100:103]
	v_mfma_f32_16x16x32_bf16 v[96:99], v[188:191], v[220:223], v[96:99]
	v_mfma_f32_16x16x32_bf16 v[124:127], v[176:179], v[200:203], v[124:127]
	v_mfma_f32_16x16x32_bf16 v[120:123], v[192:195], v[200:203], v[120:123]
	v_mfma_f32_16x16x32_bf16 v[116:119], v[176:179], v[208:211], v[116:119]
	v_mfma_f32_16x16x32_bf16 v[112:115], v[192:195], v[208:211], v[112:115]
	v_mfma_f32_16x16x32_bf16 v[108:111], v[176:179], v[216:219], v[108:111]
	v_mfma_f32_16x16x32_bf16 v[104:107], v[192:195], v[216:219], v[104:107]
	v_mfma_f32_16x16x32_bf16 v[100:103], v[176:179], v[224:227], v[100:103]
	v_mfma_f32_16x16x32_bf16 v[96:99], v[192:195], v[224:227], v[96:99]
	s_setprio 0
	s_barrier
	s_add_i32 s6, 0, 0x18000
	s_add_i32 s7, 0, 0x1c000
	v_add_u32_e32 v158, s6, v171
	v_add_u32_e32 v166, s7, v171
	ds_read_b128 v[128:131], v158
	ds_read_b128 v[150:153], v158 offset:1024
	ds_read_b128 v[154:157], v158 offset:2048
	ds_read_b128 v[158:161], v158 offset:3072
	ds_read_b128 v[162:165], v166
	ds_read_b128 v[176:179], v166 offset:1024
	ds_read_b128 v[188:191], v166 offset:2048
	ds_read_b128 v[192:195], v166 offset:3072
	s_and_b64 s[90:91], s[62:63], s[90:91]
	s_and_b64 vcc, s[90:91], s[86:87]
	s_add_u32 s92, s92, 0x40000
	s_addc_u32 s93, s93, 0
	s_and_b64 s[90:91], vcc, exec
	s_mov_b32 m0, s53
	v_cndmask_b32_e32 v166, v132, v134, vcc
	s_cselect_b32 s91, s4, s93
	s_cselect_b32 s90, s68, s92
	ds_read_b128 v[196:199], v184 offset:32768
	ds_read_b128 v[200:203], v184 offset:33792
	ds_read_b128 v[204:207], v184 offset:34816
	ds_read_b128 v[208:211], v184 offset:35840
	ds_read_b128 v[212:215], v184 offset:36864
	ds_read_b128 v[216:219], v184 offset:37888
	ds_read_b128 v[220:223], v184 offset:38912
	ds_read_b128 v[224:227], v184 offset:39936
	v_cndmask_b32_e32 v170, v136, v138, vcc
	global_load_lds_dwordx4 v166, s[90:91]
	s_mov_b32 m0, s54
	s_nop 0
	global_load_lds_dwordx4 v170, s[90:91]
	s_waitcnt vmcnt(8)
	s_waitcnt lgkmcnt(0)
	s_barrier
	s_setprio 1
	s_waitcnt lgkmcnt(0)
	v_mfma_f32_16x16x32_bf16 v[92:95], v[128:131], v[196:199], v[92:95]
	v_mfma_f32_16x16x32_bf16 v[88:91], v[154:157], v[196:199], v[88:91]
	v_mfma_f32_16x16x32_bf16 v[84:87], v[128:131], v[204:207], v[84:87]
	v_mfma_f32_16x16x32_bf16 v[80:83], v[154:157], v[204:207], v[80:83]
	v_mfma_f32_16x16x32_bf16 v[68:71], v[128:131], v[212:215], v[68:71]
	v_mfma_f32_16x16x32_bf16 v[64:67], v[154:157], v[212:215], v[64:67]
	v_mfma_f32_16x16x32_bf16 v[52:55], v[128:131], v[220:223], v[52:55]
	v_mfma_f32_16x16x32_bf16 v[48:51], v[154:157], v[220:223], v[48:51]
	v_mfma_f32_16x16x32_bf16 v[92:95], v[150:153], v[200:203], v[92:95]
	v_mfma_f32_16x16x32_bf16 v[88:91], v[158:161], v[200:203], v[88:91]
	v_mfma_f32_16x16x32_bf16 v[84:87], v[150:153], v[208:211], v[84:87]
	v_mfma_f32_16x16x32_bf16 v[80:83], v[158:161], v[208:211], v[80:83]
	v_mfma_f32_16x16x32_bf16 v[68:71], v[150:153], v[216:219], v[68:71]
	v_mfma_f32_16x16x32_bf16 v[64:67], v[158:161], v[216:219], v[64:67]
	v_mfma_f32_16x16x32_bf16 v[52:55], v[150:153], v[224:227], v[52:55]
	v_mfma_f32_16x16x32_bf16 v[48:51], v[158:161], v[224:227], v[48:51]
	v_mfma_f32_16x16x32_bf16 v[76:79], v[162:165], v[196:199], v[76:79]
	v_mfma_f32_16x16x32_bf16 v[72:75], v[188:191], v[196:199], v[72:75]
	v_mfma_f32_16x16x32_bf16 v[60:63], v[162:165], v[204:207], v[60:63]
	v_mfma_f32_16x16x32_bf16 v[56:59], v[188:191], v[204:207], v[56:59]
	v_mfma_f32_16x16x32_bf16 v[44:47], v[162:165], v[212:215], v[44:47]
	v_mfma_f32_16x16x32_bf16 v[40:43], v[188:191], v[212:215], v[40:43]
	v_mfma_f32_16x16x32_bf16 v[36:39], v[162:165], v[220:223], v[36:39]
	v_mfma_f32_16x16x32_bf16 v[32:35], v[188:191], v[220:223], v[32:35]
	v_mfma_f32_16x16x32_bf16 v[76:79], v[176:179], v[200:203], v[76:79]
	v_mfma_f32_16x16x32_bf16 v[72:75], v[192:195], v[200:203], v[72:75]
	v_mfma_f32_16x16x32_bf16 v[60:63], v[176:179], v[208:211], v[60:63]
	v_mfma_f32_16x16x32_bf16 v[56:59], v[192:195], v[208:211], v[56:59]
	v_mfma_f32_16x16x32_bf16 v[44:47], v[176:179], v[216:219], v[44:47]
	v_mfma_f32_16x16x32_bf16 v[40:43], v[192:195], v[216:219], v[40:43]
	v_mfma_f32_16x16x32_bf16 v[36:39], v[176:179], v[224:227], v[36:39]
	v_mfma_f32_16x16x32_bf16 v[32:35], v[192:195], v[224:227], v[32:35]
	s_setprio 0
	s_barrier
	s_add_i32 s6, s6, s15
	v_lshl_add_u64 v[168:169], v[168:169], 0, s[10:11]
	s_mov_b32 m0, s6
	ds_read_b128 v[196:199], v184 offset:49152
	ds_read_b128 v[200:203], v184 offset:50176
	ds_read_b128 v[204:207], v184 offset:51200
	ds_read_b128 v[208:211], v184 offset:52224
	ds_read_b128 v[212:215], v184 offset:53248
	ds_read_b128 v[216:219], v184 offset:54272
	ds_read_b128 v[220:223], v184 offset:55296
	ds_read_b128 v[224:227], v184 offset:56320
	global_load_lds_dwordx4 v[168:169], off
	s_add_i32 m0, s6, 0x2000
	s_add_u32 s88, s88, 0x40080
	v_lshl_add_u64 v[168:169], v[172:173], 0, s[10:11]
	s_addc_u32 s89, s89, 0
	s_add_i32 s6, s7, s15
	global_load_lds_dwordx4 v[168:169], off
	v_lshl_add_u64 v[168:169], s[88:89], 0, v[134:135]
	s_mov_b32 m0, s6
	s_nop 0
	global_load_lds_dwordx4 v[168:169], off
	v_lshl_add_u64 v[168:169], s[88:89], 0, v[138:139]
	s_add_i32 m0, s6, 0x2000
	s_nop 0
	global_load_lds_dwordx4 v[168:169], off
	v_lshl_add_u64 v[168:169], v[180:181], 0, s[10:11]
	s_mov_b32 m0, s55
	s_nop 0
	global_load_lds_dwordx4 v[168:169], off
	v_lshl_add_u64 v[168:169], v[228:229], 0, s[10:11]
	s_mov_b32 m0, s56
	s_nop 0
	global_load_lds_dwordx4 v[168:169], off
	s_waitcnt vmcnt(8)
	s_waitcnt lgkmcnt(0)
	s_barrier
	s_setprio 1
	s_waitcnt lgkmcnt(0)
	v_mfma_f32_16x16x32_bf16 v[28:31], v[128:131], v[196:199], v[28:31]
	v_mfma_f32_16x16x32_bf16 v[24:27], v[154:157], v[196:199], v[24:27]
	v_mfma_f32_16x16x32_bf16 v[20:23], v[128:131], v[204:207], v[20:23]
	v_mfma_f32_16x16x32_bf16 v[16:19], v[154:157], v[204:207], v[16:19]
	v_mfma_f32_16x16x32_bf16 v[12:15], v[128:131], v[212:215], v[12:15]
	v_mfma_f32_16x16x32_bf16 v[8:11], v[154:157], v[212:215], v[8:11]
	v_mfma_f32_16x16x32_bf16 v[4:7], v[128:131], v[220:223], v[4:7]
	v_mfma_f32_16x16x32_bf16 v[0:3], v[154:157], v[220:223], v[0:3]
	v_mfma_f32_16x16x32_bf16 v[28:31], v[150:153], v[200:203], v[28:31]
	v_mfma_f32_16x16x32_bf16 v[24:27], v[158:161], v[200:203], v[24:27]
	v_mfma_f32_16x16x32_bf16 v[20:23], v[150:153], v[208:211], v[20:23]
	v_mfma_f32_16x16x32_bf16 v[16:19], v[158:161], v[208:211], v[16:19]
	v_mfma_f32_16x16x32_bf16 v[12:15], v[150:153], v[216:219], v[12:15]
	v_mfma_f32_16x16x32_bf16 v[8:11], v[158:161], v[216:219], v[8:11]
	v_mfma_f32_16x16x32_bf16 v[4:7], v[150:153], v[224:227], v[4:7]
	v_mfma_f32_16x16x32_bf16 v[0:3], v[158:161], v[224:227], v[0:3]
	v_mfma_f32_16x16x32_bf16 v[124:127], v[162:165], v[196:199], v[124:127]
	v_mfma_f32_16x16x32_bf16 v[120:123], v[188:191], v[196:199], v[120:123]
	v_mfma_f32_16x16x32_bf16 v[116:119], v[162:165], v[204:207], v[116:119]
	v_mfma_f32_16x16x32_bf16 v[112:115], v[188:191], v[204:207], v[112:115]
	v_mfma_f32_16x16x32_bf16 v[108:111], v[162:165], v[212:215], v[108:111]
	v_mfma_f32_16x16x32_bf16 v[104:107], v[188:191], v[212:215], v[104:107]
	v_mfma_f32_16x16x32_bf16 v[100:103], v[162:165], v[220:223], v[100:103]
	v_mfma_f32_16x16x32_bf16 v[96:99], v[188:191], v[220:223], v[96:99]
	v_mfma_f32_16x16x32_bf16 v[124:127], v[176:179], v[200:203], v[124:127]
	v_mfma_f32_16x16x32_bf16 v[120:123], v[192:195], v[200:203], v[120:123]
	v_mfma_f32_16x16x32_bf16 v[116:119], v[176:179], v[208:211], v[116:119]
	v_mfma_f32_16x16x32_bf16 v[112:115], v[192:195], v[208:211], v[112:115]
	v_mfma_f32_16x16x32_bf16 v[108:111], v[176:179], v[216:219], v[108:111]
	v_mfma_f32_16x16x32_bf16 v[104:107], v[192:195], v[216:219], v[104:107]
	v_mfma_f32_16x16x32_bf16 v[100:103], v[176:179], v[224:227], v[100:103]
	v_mfma_f32_16x16x32_bf16 v[96:99], v[192:195], v[224:227], v[96:99]
	s_setprio 0
	s_barrier
	s_add_i32 s5, s5, 2
	s_add_u32 s84, s84, 0x100
	s_addc_u32 s85, s85, 0
	s_add_u32 s69, s69, 0x100
	s_addc_u32 s71, s71, 0
	s_cmp_gt_u32 s5, 13
	s_cbranch_scc0 .LBB0_881

.LBB0_971:
	ds_read_b128 v[120:123], v237
	ds_read_b128 v[128:131], v237 offset:1024
	ds_read_b128 v[136:139], v237 offset:2048
	ds_read_b128 v[140:143], v237 offset:3072
	ds_read_b128 v[144:147], v238
	ds_read_b128 v[148:151], v238 offset:1024
	ds_read_b128 v[152:155], v238 offset:2048
	ds_read_b128 v[156:159], v238 offset:3072
	s_add_u32 s6, s4, 0xfffc0080
	s_addc_u32 s7, s5, -1
	s_cmp_eq_u32 s88, 12
	s_cselect_b32 s83, s65, s7
	s_cselect_b32 s82, s73, s6
	s_cselect_b32 s7, s67, s87
	s_cselect_b32 s6, s76, s86
	v_lshl_add_u64 v[210:211], s[4:5], 0, v[190:191]
	s_add_i32 m0, s53, 0xc000
	ds_read_b128 v[160:163], v239
	ds_read_b128 v[164:167], v239 offset:1024
	ds_read_b128 v[168:171], v239 offset:2048
	ds_read_b128 v[172:175], v239 offset:3072
	ds_read_b128 v[176:179], v239 offset:4096
	ds_read_b128 v[198:201], v239 offset:5120
	ds_read_b128 v[202:205], v239 offset:6144
	ds_read_b128 v[206:209], v239 offset:7168
	global_load_lds_dwordx4 v[210:211], off
	v_lshl_add_u64 v[210:211], s[4:5], 0, v[192:193]
	s_add_i32 m0, s53, 0xe000
	s_nop 0
	global_load_lds_dwordx4 v[210:211], off
	s_waitcnt vmcnt(8)
	s_waitcnt lgkmcnt(0)
	s_barrier
	s_setprio 1
	s_waitcnt lgkmcnt(0)
	v_mfma_f32_16x16x32_bf16 v[132:135], v[120:123], v[160:163], v[132:135]
	v_mfma_f32_16x16x32_bf16 v[124:127], v[136:139], v[160:163], v[124:127]
	v_mfma_f32_16x16x32_bf16 v[116:119], v[120:123], v[168:171], v[116:119]
	v_mfma_f32_16x16x32_bf16 v[112:115], v[136:139], v[168:171], v[112:115]
	v_mfma_f32_16x16x32_bf16 v[108:111], v[120:123], v[176:179], v[108:111]
	v_mfma_f32_16x16x32_bf16 v[104:107], v[136:139], v[176:179], v[104:107]
	v_mfma_f32_16x16x32_bf16 v[100:103], v[120:123], v[202:205], v[100:103]
	v_mfma_f32_16x16x32_bf16 v[96:99], v[136:139], v[202:205], v[96:99]
	v_mfma_f32_16x16x32_bf16 v[132:135], v[128:131], v[164:167], v[132:135]
	v_mfma_f32_16x16x32_bf16 v[124:127], v[140:143], v[164:167], v[124:127]
	v_mfma_f32_16x16x32_bf16 v[116:119], v[128:131], v[172:175], v[116:119]
	v_mfma_f32_16x16x32_bf16 v[112:115], v[140:143], v[172:175], v[112:115]
	v_mfma_f32_16x16x32_bf16 v[108:111], v[128:131], v[198:201], v[108:111]
	v_mfma_f32_16x16x32_bf16 v[104:107], v[140:143], v[198:201], v[104:107]
	v_mfma_f32_16x16x32_bf16 v[100:103], v[128:131], v[206:209], v[100:103]
	v_mfma_f32_16x16x32_bf16 v[96:99], v[140:143], v[206:209], v[96:99]
	v_mfma_f32_16x16x32_bf16 v[92:95], v[144:147], v[160:163], v[92:95]
	v_mfma_f32_16x16x32_bf16 v[88:91], v[152:155], v[160:163], v[88:91]
	v_mfma_f32_16x16x32_bf16 v[84:87], v[144:147], v[168:171], v[84:87]
	v_mfma_f32_16x16x32_bf16 v[80:83], v[152:155], v[168:171], v[80:83]
	v_mfma_f32_16x16x32_bf16 v[76:79], v[144:147], v[176:179], v[76:79]
	v_mfma_f32_16x16x32_bf16 v[72:75], v[152:155], v[176:179], v[72:75]
	v_mfma_f32_16x16x32_bf16 v[68:71], v[144:147], v[202:205], v[68:71]
	v_mfma_f32_16x16x32_bf16 v[64:67], v[152:155], v[202:205], v[64:67]
	v_mfma_f32_16x16x32_bf16 v[92:95], v[148:151], v[164:167], v[92:95]
	v_mfma_f32_16x16x32_bf16 v[88:91], v[156:159], v[164:167], v[88:91]
	v_mfma_f32_16x16x32_bf16 v[84:87], v[148:151], v[172:175], v[84:87]
	v_mfma_f32_16x16x32_bf16 v[80:83], v[156:159], v[172:175], v[80:83]
	v_mfma_f32_16x16x32_bf16 v[76:79], v[148:151], v[198:201], v[76:79]
	v_mfma_f32_16x16x32_bf16 v[72:75], v[156:159], v[198:201], v[72:75]
	v_mfma_f32_16x16x32_bf16 v[68:71], v[148:151], v[206:209], v[68:71]
	v_mfma_f32_16x16x32_bf16 v[64:67], v[156:159], v[206:209], v[64:67]
	s_setprio 0
	s_barrier
	s_add_i32 s89, s68, s52
	v_lshl_add_u64 v[210:211], s[6:7], 0, v[182:183]
	s_mov_b32 m0, s89
	ds_read_b128 v[160:163], v239 offset:16384
	ds_read_b128 v[164:167], v239 offset:17408
	ds_read_b128 v[168:171], v239 offset:18432
	ds_read_b128 v[172:175], v239 offset:19456
	ds_read_b128 v[176:179], v239 offset:20480
	ds_read_b128 v[198:201], v239 offset:21504
	ds_read_b128 v[202:205], v239 offset:22528
	ds_read_b128 v[206:209], v239 offset:23552
	global_load_lds_dwordx4 v[210:211], off
	s_add_i32 m0, s89, 0x2000
	s_add_u32 s90, s6, 0x40000
	v_lshl_add_u64 v[212:213], s[6:7], 0, v[186:187]
	s_addc_u32 s91, s7, 0
	s_add_i32 s89, s69, s52
	global_load_lds_dwordx4 v[212:213], off
	v_lshl_add_u64 v[214:215], s[90:91], 0, v[182:183]
	s_mov_b32 m0, s89
	v_lshl_add_u64 v[216:217], s[82:83], 0, v[184:185]
	global_load_lds_dwordx4 v[214:215], off
	v_lshl_add_u64 v[214:215], s[90:91], 0, v[186:187]
	s_add_i32 m0, s89, 0x2000
	s_nop 0
	global_load_lds_dwordx4 v[214:215], off
	v_lshl_add_u64 v[214:215], s[82:83], 0, v[180:181]
	s_mov_b32 m0, s53
	s_nop 0
	global_load_lds_dwordx4 v[214:215], off
	s_mov_b32 m0, s54
	s_nop 0
	global_load_lds_dwordx4 v[216:217], off
	s_waitcnt vmcnt(8)
	s_waitcnt lgkmcnt(0)
	s_barrier
	s_setprio 1
	s_waitcnt lgkmcnt(0)
	v_mfma_f32_16x16x32_bf16 v[60:63], v[120:123], v[160:163], v[60:63]
	v_mfma_f32_16x16x32_bf16 v[56:59], v[136:139], v[160:163], v[56:59]
	v_mfma_f32_16x16x32_bf16 v[52:55], v[120:123], v[168:171], v[52:55]
	v_mfma_f32_16x16x32_bf16 v[48:51], v[136:139], v[168:171], v[48:51]
	v_mfma_f32_16x16x32_bf16 v[44:47], v[120:123], v[176:179], v[44:47]
	v_mfma_f32_16x16x32_bf16 v[40:43], v[136:139], v[176:179], v[40:43]
	v_mfma_f32_16x16x32_bf16 v[36:39], v[120:123], v[202:205], v[36:39]
	v_mfma_f32_16x16x32_bf16 v[32:35], v[136:139], v[202:205], v[32:35]
	v_mfma_f32_16x16x32_bf16 v[60:63], v[128:131], v[164:167], v[60:63]
	v_mfma_f32_16x16x32_bf16 v[56:59], v[140:143], v[164:167], v[56:59]
	v_mfma_f32_16x16x32_bf16 v[52:55], v[128:131], v[172:175], v[52:55]
	v_mfma_f32_16x16x32_bf16 v[48:51], v[140:143], v[172:175], v[48:51]
	v_mfma_f32_16x16x32_bf16 v[44:47], v[128:131], v[198:201], v[44:47]
	v_mfma_f32_16x16x32_bf16 v[40:43], v[140:143], v[198:201], v[40:43]
	v_mfma_f32_16x16x32_bf16 v[36:39], v[128:131], v[206:209], v[36:39]
	v_mfma_f32_16x16x32_bf16 v[32:35], v[140:143], v[206:209], v[32:35]
	v_mfma_f32_16x16x32_bf16 v[28:31], v[144:147], v[160:163], v[28:31]
	v_mfma_f32_16x16x32_bf16 v[24:27], v[152:155], v[160:163], v[24:27]
	v_mfma_f32_16x16x32_bf16 v[20:23], v[144:147], v[168:171], v[20:23]
	v_mfma_f32_16x16x32_bf16 v[16:19], v[152:155], v[168:171], v[16:19]
	v_mfma_f32_16x16x32_bf16 v[12:15], v[144:147], v[176:179], v[12:15]
	v_mfma_f32_16x16x32_bf16 v[8:11], v[152:155], v[176:179], v[8:11]
	v_mfma_f32_16x16x32_bf16 v[4:7], v[144:147], v[202:205], v[4:7]
	v_mfma_f32_16x16x32_bf16 v[0:3], v[152:155], v[202:205], v[0:3]
	v_mfma_f32_16x16x32_bf16 v[28:31], v[148:151], v[164:167], v[28:31]
	v_mfma_f32_16x16x32_bf16 v[24:27], v[156:159], v[164:167], v[24:27]
	v_mfma_f32_16x16x32_bf16 v[20:23], v[148:151], v[172:175], v[20:23]
	v_mfma_f32_16x16x32_bf16 v[16:19], v[156:159], v[172:175], v[16:19]
	v_mfma_f32_16x16x32_bf16 v[12:15], v[148:151], v[198:201], v[12:15]
	v_mfma_f32_16x16x32_bf16 v[8:11], v[156:159], v[198:201], v[8:11]
	v_mfma_f32_16x16x32_bf16 v[4:7], v[148:151], v[206:209], v[4:7]
	v_mfma_f32_16x16x32_bf16 v[0:3], v[156:159], v[206:209], v[0:3]
	s_setprio 0
	s_barrier
	s_add_i32 s89, 0, 0x18000
	s_add_i32 s90, 0, 0x1c000
	v_add_u32_e32 v140, s89, v235
	v_add_u32_e32 v156, s90, v235
	ds_read_b128 v[120:123], v140
	ds_read_b128 v[128:131], v140 offset:1024
	ds_read_b128 v[136:139], v140 offset:2048
	ds_read_b128 v[140:143], v140 offset:3072
	ds_read_b128 v[144:147], v156
	ds_read_b128 v[148:151], v156 offset:1024
	ds_read_b128 v[152:155], v156 offset:2048
	ds_read_b128 v[156:159], v156 offset:3072
	s_add_u32 s82, s82, 0x40000
	s_addc_u32 s83, s83, 0
	s_mov_b32 m0, s55
	v_lshl_add_u64 v[218:219], s[82:83], 0, v[180:181]
	ds_read_b128 v[160:163], v239 offset:32768
	ds_read_b128 v[164:167], v239 offset:33792
	ds_read_b128 v[168:171], v239 offset:34816
	ds_read_b128 v[172:175], v239 offset:35840
	ds_read_b128 v[176:179], v239 offset:36864
	ds_read_b128 v[198:201], v239 offset:37888
	ds_read_b128 v[202:205], v239 offset:38912
	ds_read_b128 v[206:209], v239 offset:39936
	global_load_lds_dwordx4 v[218:219], off
	v_lshl_add_u64 v[218:219], s[82:83], 0, v[184:185]
	s_mov_b32 m0, s56
	s_nop 0
	global_load_lds_dwordx4 v[218:219], off
	s_waitcnt vmcnt(8)
	s_waitcnt lgkmcnt(0)
	s_barrier
	s_setprio 1
	s_waitcnt lgkmcnt(0)
	v_mfma_f32_16x16x32_bf16 v[132:135], v[120:123], v[160:163], v[132:135]
	v_mfma_f32_16x16x32_bf16 v[124:127], v[136:139], v[160:163], v[124:127]
	v_mfma_f32_16x16x32_bf16 v[116:119], v[120:123], v[168:171], v[116:119]
	v_mfma_f32_16x16x32_bf16 v[112:115], v[136:139], v[168:171], v[112:115]
	v_mfma_f32_16x16x32_bf16 v[108:111], v[120:123], v[176:179], v[108:111]
	v_mfma_f32_16x16x32_bf16 v[104:107], v[136:139], v[176:179], v[104:107]
	v_mfma_f32_16x16x32_bf16 v[100:103], v[120:123], v[202:205], v[100:103]
	v_mfma_f32_16x16x32_bf16 v[96:99], v[136:139], v[202:205], v[96:99]
	v_mfma_f32_16x16x32_bf16 v[132:135], v[128:131], v[164:167], v[132:135]
	v_mfma_f32_16x16x32_bf16 v[124:127], v[140:143], v[164:167], v[124:127]
	v_mfma_f32_16x16x32_bf16 v[116:119], v[128:131], v[172:175], v[116:119]
	v_mfma_f32_16x16x32_bf16 v[112:115], v[140:143], v[172:175], v[112:115]
	v_mfma_f32_16x16x32_bf16 v[108:111], v[128:131], v[198:201], v[108:111]
	v_mfma_f32_16x16x32_bf16 v[104:107], v[140:143], v[198:201], v[104:107]
	v_mfma_f32_16x16x32_bf16 v[100:103], v[128:131], v[206:209], v[100:103]
	v_mfma_f32_16x16x32_bf16 v[96:99], v[140:143], v[206:209], v[96:99]
	v_mfma_f32_16x16x32_bf16 v[92:95], v[144:147], v[160:163], v[92:95]
	v_mfma_f32_16x16x32_bf16 v[88:91], v[152:155], v[160:163], v[88:91]
	v_mfma_f32_16x16x32_bf16 v[84:87], v[144:147], v[168:171], v[84:87]
	v_mfma_f32_16x16x32_bf16 v[80:83], v[152:155], v[168:171], v[80:83]
	v_mfma_f32_16x16x32_bf16 v[76:79], v[144:147], v[176:179], v[76:79]
	v_mfma_f32_16x16x32_bf16 v[72:75], v[152:155], v[176:179], v[72:75]
	v_mfma_f32_16x16x32_bf16 v[68:71], v[144:147], v[202:205], v[68:71]
	v_mfma_f32_16x16x32_bf16 v[64:67], v[152:155], v[202:205], v[64:67]
	v_mfma_f32_16x16x32_bf16 v[92:95], v[148:151], v[164:167], v[92:95]
	v_mfma_f32_16x16x32_bf16 v[88:91], v[156:159], v[164:167], v[88:91]
	v_mfma_f32_16x16x32_bf16 v[84:87], v[148:151], v[172:175], v[84:87]
	v_mfma_f32_16x16x32_bf16 v[80:83], v[156:159], v[172:175], v[80:83]
	v_mfma_f32_16x16x32_bf16 v[76:79], v[148:151], v[198:201], v[76:79]
	v_mfma_f32_16x16x32_bf16 v[72:75], v[156:159], v[198:201], v[72:75]
	v_mfma_f32_16x16x32_bf16 v[68:71], v[148:151], v[206:209], v[68:71]
	v_mfma_f32_16x16x32_bf16 v[64:67], v[156:159], v[206:209], v[64:67]
	s_setprio 0
	s_barrier
	s_add_i32 s82, s89, s52
	v_lshl_add_u64 v[210:211], v[210:211], 0, s[18:19]
	s_mov_b32 m0, s82
	ds_read_b128 v[160:163], v239 offset:49152
	ds_read_b128 v[164:167], v239 offset:50176
	ds_read_b128 v[168:171], v239 offset:51200
	ds_read_b128 v[172:175], v239 offset:52224
	ds_read_b128 v[176:179], v239 offset:53248
	ds_read_b128 v[198:201], v239 offset:54272
	ds_read_b128 v[202:205], v239 offset:55296
	ds_read_b128 v[206:209], v239 offset:56320
	global_load_lds_dwordx4 v[210:211], off
	s_add_i32 m0, s82, 0x2000
	s_add_u32 s6, s6, 0x40080
	v_lshl_add_u64 v[210:211], v[212:213], 0, s[18:19]
	s_addc_u32 s7, s7, 0
	s_add_i32 s82, s90, s52
	global_load_lds_dwordx4 v[210:211], off
	v_lshl_add_u64 v[210:211], s[6:7], 0, v[182:183]
	s_mov_b32 m0, s82
	s_nop 0
	global_load_lds_dwordx4 v[210:211], off
	v_lshl_add_u64 v[210:211], s[6:7], 0, v[186:187]
	s_add_i32 m0, s82, 0x2000
	s_nop 0
	global_load_lds_dwordx4 v[210:211], off
	v_lshl_add_u64 v[210:211], v[214:215], 0, s[18:19]
	s_mov_b32 m0, s58
	s_nop 0
	global_load_lds_dwordx4 v[210:211], off
	v_lshl_add_u64 v[210:211], v[216:217], 0, s[18:19]
	s_mov_b32 m0, s59
	s_nop 0
	global_load_lds_dwordx4 v[210:211], off
	s_waitcnt vmcnt(8)
	s_waitcnt lgkmcnt(0)
	s_barrier
	s_setprio 1
	s_waitcnt lgkmcnt(0)
	v_mfma_f32_16x16x32_bf16 v[60:63], v[120:123], v[160:163], v[60:63]
	v_mfma_f32_16x16x32_bf16 v[56:59], v[136:139], v[160:163], v[56:59]
	v_mfma_f32_16x16x32_bf16 v[52:55], v[120:123], v[168:171], v[52:55]
	v_mfma_f32_16x16x32_bf16 v[48:51], v[136:139], v[168:171], v[48:51]
	v_mfma_f32_16x16x32_bf16 v[44:47], v[120:123], v[176:179], v[44:47]
	v_mfma_f32_16x16x32_bf16 v[40:43], v[136:139], v[176:179], v[40:43]
	v_mfma_f32_16x16x32_bf16 v[36:39], v[120:123], v[202:205], v[36:39]
	v_mfma_f32_16x16x32_bf16 v[32:35], v[136:139], v[202:205], v[32:35]
	v_mfma_f32_16x16x32_bf16 v[60:63], v[128:131], v[164:167], v[60:63]
	v_mfma_f32_16x16x32_bf16 v[56:59], v[140:143], v[164:167], v[56:59]
	v_mfma_f32_16x16x32_bf16 v[52:55], v[128:131], v[172:175], v[52:55]
	v_mfma_f32_16x16x32_bf16 v[48:51], v[140:143], v[172:175], v[48:51]
	v_mfma_f32_16x16x32_bf16 v[44:47], v[128:131], v[198:201], v[44:47]
	v_mfma_f32_16x16x32_bf16 v[40:43], v[140:143], v[198:201], v[40:43]
	v_mfma_f32_16x16x32_bf16 v[36:39], v[128:131], v[206:209], v[36:39]
	v_mfma_f32_16x16x32_bf16 v[32:35], v[140:143], v[206:209], v[32:35]
	v_mfma_f32_16x16x32_bf16 v[28:31], v[144:147], v[160:163], v[28:31]
	v_mfma_f32_16x16x32_bf16 v[24:27], v[152:155], v[160:163], v[24:27]
	v_mfma_f32_16x16x32_bf16 v[20:23], v[144:147], v[168:171], v[20:23]
	v_mfma_f32_16x16x32_bf16 v[16:19], v[152:155], v[168:171], v[16:19]
	v_mfma_f32_16x16x32_bf16 v[12:15], v[144:147], v[176:179], v[12:15]
	v_mfma_f32_16x16x32_bf16 v[8:11], v[152:155], v[176:179], v[8:11]
	v_mfma_f32_16x16x32_bf16 v[4:7], v[144:147], v[202:205], v[4:7]
	v_mfma_f32_16x16x32_bf16 v[0:3], v[152:155], v[202:205], v[0:3]
	v_mfma_f32_16x16x32_bf16 v[28:31], v[148:151], v[164:167], v[28:31]
	v_mfma_f32_16x16x32_bf16 v[24:27], v[156:159], v[164:167], v[24:27]
	v_mfma_f32_16x16x32_bf16 v[20:23], v[148:151], v[172:175], v[20:23]
	v_mfma_f32_16x16x32_bf16 v[16:19], v[156:159], v[172:175], v[16:19]
	v_mfma_f32_16x16x32_bf16 v[12:15], v[148:151], v[198:201], v[12:15]
	v_mfma_f32_16x16x32_bf16 v[8:11], v[156:159], v[198:201], v[8:11]
	v_mfma_f32_16x16x32_bf16 v[4:7], v[148:151], v[206:209], v[4:7]
	v_mfma_f32_16x16x32_bf16 v[0:3], v[156:159], v[206:209], v[0:3]
	s_setprio 0
	s_barrier
	s_add_i32 s88, s88, 2
	s_add_u32 s4, s4, 0x100
	s_addc_u32 s5, s5, 0
	s_add_u32 s86, s86, 0x100
	s_addc_u32 s87, s87, 0
	s_cmp_gt_u32 s88, 13
	s_cbranch_scc0 .LBB0_971
	s_and_b64 vcc, exec, s[36:37]
	s_cbranch_vccz .LBB0_974
	s_barrier

.LBB0_1080:
	ds_read_b128 v[128:131], v187
	ds_read_b128 v[132:135], v187 offset:1024
	ds_read_b128 v[136:139], v187 offset:2048
	ds_read_b128 v[140:143], v187 offset:3072
	ds_read_b128 v[144:147], v188
	ds_read_b128 v[148:151], v188 offset:1024
	ds_read_b128 v[168:171], v188 offset:2048
	ds_read_b128 v[172:175], v188 offset:3072
	s_add_u32 s38, s36, 0x100
	s_addc_u32 s39, s37, 0
	s_cmp_eq_u32 s77, 40
	s_cselect_b32 s61, s5, s39
	s_cselect_b32 s60, s4, s38
	s_cselect_b32 s45, s7, s76
	s_cselect_b32 s44, s6, s73
	v_lshl_add_u64 v[216:217], s[36:37], 0, v[160:161]
	s_add_i32 m0, s54, 0xc000
	ds_read_b128 v[176:179], v189
	ds_read_b128 v[180:183], v189 offset:1024
	ds_read_b128 v[192:195], v189 offset:2048
	ds_read_b128 v[196:199], v189 offset:3072
	ds_read_b128 v[200:203], v189 offset:4096
	ds_read_b128 v[204:207], v189 offset:5120
	ds_read_b128 v[208:211], v189 offset:6144
	ds_read_b128 v[212:215], v189 offset:7168
	global_load_lds_dwordx4 v[216:217], off
	v_lshl_add_u64 v[216:217], s[36:37], 0, v[162:163]
	s_add_i32 m0, s54, 0xe000
	s_nop 0
	global_load_lds_dwordx4 v[216:217], off
	s_waitcnt vmcnt(8)
	s_waitcnt lgkmcnt(0)
	s_barrier
	s_setprio 1
	s_waitcnt lgkmcnt(0)
	v_mfma_f32_16x16x32_bf16 v[124:127], v[128:131], v[176:179], v[124:127]
	v_mfma_f32_16x16x32_bf16 v[120:123], v[136:139], v[176:179], v[120:123]
	v_mfma_f32_16x16x32_bf16 v[108:111], v[128:131], v[192:195], v[108:111]
	v_mfma_f32_16x16x32_bf16 v[104:107], v[136:139], v[192:195], v[104:107]
	v_mfma_f32_16x16x32_bf16 v[92:95], v[128:131], v[200:203], v[92:95]
	v_mfma_f32_16x16x32_bf16 v[88:91], v[136:139], v[200:203], v[88:91]
	v_mfma_f32_16x16x32_bf16 v[76:79], v[128:131], v[208:211], v[76:79]
	v_mfma_f32_16x16x32_bf16 v[72:75], v[136:139], v[208:211], v[72:75]
	v_mfma_f32_16x16x32_bf16 v[124:127], v[132:135], v[180:183], v[124:127]
	v_mfma_f32_16x16x32_bf16 v[120:123], v[140:143], v[180:183], v[120:123]
	v_mfma_f32_16x16x32_bf16 v[108:111], v[132:135], v[196:199], v[108:111]
	v_mfma_f32_16x16x32_bf16 v[104:107], v[140:143], v[196:199], v[104:107]
	v_mfma_f32_16x16x32_bf16 v[92:95], v[132:135], v[204:207], v[92:95]
	v_mfma_f32_16x16x32_bf16 v[88:91], v[140:143], v[204:207], v[88:91]
	v_mfma_f32_16x16x32_bf16 v[76:79], v[132:135], v[212:215], v[76:79]
	v_mfma_f32_16x16x32_bf16 v[72:75], v[140:143], v[212:215], v[72:75]
	v_mfma_f32_16x16x32_bf16 v[116:119], v[144:147], v[176:179], v[116:119]
	v_mfma_f32_16x16x32_bf16 v[112:115], v[168:171], v[176:179], v[112:115]
	v_mfma_f32_16x16x32_bf16 v[100:103], v[144:147], v[192:195], v[100:103]
	v_mfma_f32_16x16x32_bf16 v[96:99], v[168:171], v[192:195], v[96:99]
	v_mfma_f32_16x16x32_bf16 v[84:87], v[144:147], v[200:203], v[84:87]
	v_mfma_f32_16x16x32_bf16 v[80:83], v[168:171], v[200:203], v[80:83]
	v_mfma_f32_16x16x32_bf16 v[68:71], v[144:147], v[208:211], v[68:71]
	v_mfma_f32_16x16x32_bf16 v[64:67], v[168:171], v[208:211], v[64:67]
	v_mfma_f32_16x16x32_bf16 v[116:119], v[148:151], v[180:183], v[116:119]
	v_mfma_f32_16x16x32_bf16 v[112:115], v[172:175], v[180:183], v[112:115]
	v_mfma_f32_16x16x32_bf16 v[100:103], v[148:151], v[196:199], v[100:103]
	v_mfma_f32_16x16x32_bf16 v[96:99], v[172:175], v[196:199], v[96:99]
	v_mfma_f32_16x16x32_bf16 v[84:87], v[148:151], v[204:207], v[84:87]
	v_mfma_f32_16x16x32_bf16 v[80:83], v[172:175], v[204:207], v[80:83]
	v_mfma_f32_16x16x32_bf16 v[68:71], v[148:151], v[212:215], v[68:71]
	v_mfma_f32_16x16x32_bf16 v[64:67], v[172:175], v[212:215], v[64:67]
	s_setprio 0
	s_barrier
	s_add_i32 s36, s65, s53
	v_lshl_add_u64 v[216:217], s[44:45], 0, v[154:155]
	s_mov_b32 m0, s36
	ds_read_b128 v[176:179], v189 offset:16384
	ds_read_b128 v[180:183], v189 offset:17408
	ds_read_b128 v[192:195], v189 offset:18432
	ds_read_b128 v[196:199], v189 offset:19456
	ds_read_b128 v[200:203], v189 offset:20480
	ds_read_b128 v[204:207], v189 offset:21504
	ds_read_b128 v[208:211], v189 offset:22528
	ds_read_b128 v[212:215], v189 offset:23552
	global_load_lds_dwordx4 v[216:217], off
	s_add_i32 m0, s36, 0x2000
	s_add_u32 s36, s44, 0xb0000
	v_lshl_add_u64 v[218:219], s[44:45], 0, v[158:159]
	s_addc_u32 s37, s45, 0
	s_add_i32 s78, s66, s53
	global_load_lds_dwordx4 v[218:219], off
	v_lshl_add_u64 v[220:221], s[36:37], 0, v[154:155]
	s_mov_b32 m0, s78
	v_lshl_add_u64 v[222:223], s[60:61], 0, v[156:157]
	global_load_lds_dwordx4 v[220:221], off
	v_lshl_add_u64 v[220:221], s[36:37], 0, v[158:159]
	s_add_i32 m0, s78, 0x2000
	s_nop 0
	global_load_lds_dwordx4 v[220:221], off
	v_lshl_add_u64 v[220:221], s[60:61], 0, v[152:153]
	s_mov_b32 m0, s54
	s_nop 0
	global_load_lds_dwordx4 v[220:221], off
	s_mov_b32 m0, s55
	s_nop 0
	global_load_lds_dwordx4 v[222:223], off
	s_waitcnt vmcnt(8)
	s_waitcnt lgkmcnt(0)
	s_barrier
	s_setprio 1
	s_waitcnt lgkmcnt(0)
	v_mfma_f32_16x16x32_bf16 v[60:63], v[128:131], v[176:179], v[60:63]
	v_mfma_f32_16x16x32_bf16 v[56:59], v[136:139], v[176:179], v[56:59]
	v_mfma_f32_16x16x32_bf16 v[44:47], v[128:131], v[192:195], v[44:47]
	v_mfma_f32_16x16x32_bf16 v[40:43], v[136:139], v[192:195], v[40:43]
	v_mfma_f32_16x16x32_bf16 v[28:31], v[128:131], v[200:203], v[28:31]
	v_mfma_f32_16x16x32_bf16 v[24:27], v[136:139], v[200:203], v[24:27]
	v_mfma_f32_16x16x32_bf16 v[12:15], v[128:131], v[208:211], v[12:15]
	v_mfma_f32_16x16x32_bf16 v[8:11], v[136:139], v[208:211], v[8:11]
	v_mfma_f32_16x16x32_bf16 v[60:63], v[132:135], v[180:183], v[60:63]
	v_mfma_f32_16x16x32_bf16 v[56:59], v[140:143], v[180:183], v[56:59]
	v_mfma_f32_16x16x32_bf16 v[44:47], v[132:135], v[196:199], v[44:47]
	v_mfma_f32_16x16x32_bf16 v[40:43], v[140:143], v[196:199], v[40:43]
	v_mfma_f32_16x16x32_bf16 v[28:31], v[132:135], v[204:207], v[28:31]
	v_mfma_f32_16x16x32_bf16 v[24:27], v[140:143], v[204:207], v[24:27]
	v_mfma_f32_16x16x32_bf16 v[12:15], v[132:135], v[212:215], v[12:15]
	v_mfma_f32_16x16x32_bf16 v[8:11], v[140:143], v[212:215], v[8:11]
	v_mfma_f32_16x16x32_bf16 v[52:55], v[144:147], v[176:179], v[52:55]
	v_mfma_f32_16x16x32_bf16 v[48:51], v[168:171], v[176:179], v[48:51]
	v_mfma_f32_16x16x32_bf16 v[36:39], v[144:147], v[192:195], v[36:39]
	v_mfma_f32_16x16x32_bf16 v[32:35], v[168:171], v[192:195], v[32:35]
	v_mfma_f32_16x16x32_bf16 v[20:23], v[144:147], v[200:203], v[20:23]
	v_mfma_f32_16x16x32_bf16 v[16:19], v[168:171], v[200:203], v[16:19]
	v_mfma_f32_16x16x32_bf16 v[4:7], v[144:147], v[208:211], v[4:7]
	v_mfma_f32_16x16x32_bf16 v[0:3], v[168:171], v[208:211], v[0:3]
	v_mfma_f32_16x16x32_bf16 v[52:55], v[148:151], v[180:183], v[52:55]
	v_mfma_f32_16x16x32_bf16 v[48:51], v[172:175], v[180:183], v[48:51]
	v_mfma_f32_16x16x32_bf16 v[36:39], v[148:151], v[196:199], v[36:39]
	v_mfma_f32_16x16x32_bf16 v[32:35], v[172:175], v[196:199], v[32:35]
	v_mfma_f32_16x16x32_bf16 v[20:23], v[148:151], v[204:207], v[20:23]
	v_mfma_f32_16x16x32_bf16 v[16:19], v[172:175], v[204:207], v[16:19]
	v_mfma_f32_16x16x32_bf16 v[4:7], v[148:151], v[212:215], v[4:7]
	v_mfma_f32_16x16x32_bf16 v[0:3], v[172:175], v[212:215], v[0:3]
	s_setprio 0
	s_barrier
	s_add_i32 s78, 0, 0x18000
	s_add_i32 s79, 0, 0x1c000
	v_add_u32_e32 v140, s78, v185
	v_add_u32_e32 v172, s79, v185
	ds_read_b128 v[128:131], v140
	ds_read_b128 v[132:135], v140 offset:1024
	ds_read_b128 v[136:139], v140 offset:2048
	ds_read_b128 v[140:143], v140 offset:3072
	ds_read_b128 v[144:147], v172
	ds_read_b128 v[148:151], v172 offset:1024
	ds_read_b128 v[168:171], v172 offset:2048
	ds_read_b128 v[172:175], v172 offset:3072
	s_add_u32 s36, s60, 0xb0000
	s_addc_u32 s37, s61, 0
	s_mov_b32 m0, s56
	v_lshl_add_u64 v[224:225], s[36:37], 0, v[152:153]
	ds_read_b128 v[176:179], v189 offset:32768
	ds_read_b128 v[180:183], v189 offset:33792
	ds_read_b128 v[192:195], v189 offset:34816
	ds_read_b128 v[196:199], v189 offset:35840
	ds_read_b128 v[200:203], v189 offset:36864
	ds_read_b128 v[204:207], v189 offset:37888
	ds_read_b128 v[208:211], v189 offset:38912
	ds_read_b128 v[212:215], v189 offset:39936
	global_load_lds_dwordx4 v[224:225], off
	v_lshl_add_u64 v[224:225], s[36:37], 0, v[156:157]
	s_mov_b32 m0, s57
	s_nop 0
	global_load_lds_dwordx4 v[224:225], off
	s_waitcnt vmcnt(8)
	s_waitcnt lgkmcnt(0)
	s_barrier
	s_setprio 1
	s_waitcnt lgkmcnt(0)
	v_mfma_f32_16x16x32_bf16 v[124:127], v[128:131], v[176:179], v[124:127]
	v_mfma_f32_16x16x32_bf16 v[120:123], v[136:139], v[176:179], v[120:123]
	v_mfma_f32_16x16x32_bf16 v[108:111], v[128:131], v[192:195], v[108:111]
	v_mfma_f32_16x16x32_bf16 v[104:107], v[136:139], v[192:195], v[104:107]
	v_mfma_f32_16x16x32_bf16 v[92:95], v[128:131], v[200:203], v[92:95]
	v_mfma_f32_16x16x32_bf16 v[88:91], v[136:139], v[200:203], v[88:91]
	v_mfma_f32_16x16x32_bf16 v[76:79], v[128:131], v[208:211], v[76:79]
	v_mfma_f32_16x16x32_bf16 v[72:75], v[136:139], v[208:211], v[72:75]
	v_mfma_f32_16x16x32_bf16 v[124:127], v[132:135], v[180:183], v[124:127]
	v_mfma_f32_16x16x32_bf16 v[120:123], v[140:143], v[180:183], v[120:123]
	v_mfma_f32_16x16x32_bf16 v[108:111], v[132:135], v[196:199], v[108:111]
	v_mfma_f32_16x16x32_bf16 v[104:107], v[140:143], v[196:199], v[104:107]
	v_mfma_f32_16x16x32_bf16 v[92:95], v[132:135], v[204:207], v[92:95]
	v_mfma_f32_16x16x32_bf16 v[88:91], v[140:143], v[204:207], v[88:91]
	v_mfma_f32_16x16x32_bf16 v[76:79], v[132:135], v[212:215], v[76:79]
	v_mfma_f32_16x16x32_bf16 v[72:75], v[140:143], v[212:215], v[72:75]
	v_mfma_f32_16x16x32_bf16 v[116:119], v[144:147], v[176:179], v[116:119]
	v_mfma_f32_16x16x32_bf16 v[112:115], v[168:171], v[176:179], v[112:115]
	v_mfma_f32_16x16x32_bf16 v[100:103], v[144:147], v[192:195], v[100:103]
	v_mfma_f32_16x16x32_bf16 v[96:99], v[168:171], v[192:195], v[96:99]
	v_mfma_f32_16x16x32_bf16 v[84:87], v[144:147], v[200:203], v[84:87]
	v_mfma_f32_16x16x32_bf16 v[80:83], v[168:171], v[200:203], v[80:83]
	v_mfma_f32_16x16x32_bf16 v[68:71], v[144:147], v[208:211], v[68:71]
	v_mfma_f32_16x16x32_bf16 v[64:67], v[168:171], v[208:211], v[64:67]
	v_mfma_f32_16x16x32_bf16 v[116:119], v[148:151], v[180:183], v[116:119]
	v_mfma_f32_16x16x32_bf16 v[112:115], v[172:175], v[180:183], v[112:115]
	v_mfma_f32_16x16x32_bf16 v[100:103], v[148:151], v[196:199], v[100:103]
	v_mfma_f32_16x16x32_bf16 v[96:99], v[172:175], v[196:199], v[96:99]
	v_mfma_f32_16x16x32_bf16 v[84:87], v[148:151], v[204:207], v[84:87]
	v_mfma_f32_16x16x32_bf16 v[80:83], v[172:175], v[204:207], v[80:83]
	v_mfma_f32_16x16x32_bf16 v[68:71], v[148:151], v[212:215], v[68:71]
	v_mfma_f32_16x16x32_bf16 v[64:67], v[172:175], v[212:215], v[64:67]
	s_setprio 0
	s_barrier
	s_add_i32 s36, s78, s53
	v_lshl_add_u64 v[216:217], v[216:217], 0, s[14:15]
	s_mov_b32 m0, s36
	ds_read_b128 v[176:179], v189 offset:49152
	ds_read_b128 v[180:183], v189 offset:50176
	ds_read_b128 v[192:195], v189 offset:51200
	ds_read_b128 v[196:199], v189 offset:52224
	ds_read_b128 v[200:203], v189 offset:53248
	ds_read_b128 v[204:207], v189 offset:54272
	ds_read_b128 v[208:211], v189 offset:55296
	ds_read_b128 v[212:215], v189 offset:56320
	global_load_lds_dwordx4 v[216:217], off
	s_add_i32 m0, s36, 0x2000
	s_add_u32 s36, s44, 0xb0080
	v_lshl_add_u64 v[216:217], v[218:219], 0, s[14:15]
	s_addc_u32 s37, s45, 0
	s_add_i32 s44, s79, s53
	global_load_lds_dwordx4 v[216:217], off
	v_lshl_add_u64 v[216:217], s[36:37], 0, v[154:155]
	s_mov_b32 m0, s44
	s_nop 0
	global_load_lds_dwordx4 v[216:217], off
	v_lshl_add_u64 v[216:217], s[36:37], 0, v[158:159]
	s_add_i32 m0, s44, 0x2000
	s_nop 0
	global_load_lds_dwordx4 v[216:217], off
	v_lshl_add_u64 v[216:217], v[220:221], 0, s[14:15]
	s_mov_b32 m0, s59
	s_nop 0
	global_load_lds_dwordx4 v[216:217], off
	v_lshl_add_u64 v[216:217], v[222:223], 0, s[14:15]
	s_mov_b32 m0, s62
	s_nop 0
	global_load_lds_dwordx4 v[216:217], off
	s_waitcnt vmcnt(8)
	s_waitcnt lgkmcnt(0)
	s_barrier
	s_setprio 1
	s_waitcnt lgkmcnt(0)
	v_mfma_f32_16x16x32_bf16 v[60:63], v[128:131], v[176:179], v[60:63]
	v_mfma_f32_16x16x32_bf16 v[56:59], v[136:139], v[176:179], v[56:59]
	v_mfma_f32_16x16x32_bf16 v[44:47], v[128:131], v[192:195], v[44:47]
	v_mfma_f32_16x16x32_bf16 v[40:43], v[136:139], v[192:195], v[40:43]
	v_mfma_f32_16x16x32_bf16 v[28:31], v[128:131], v[200:203], v[28:31]
	v_mfma_f32_16x16x32_bf16 v[24:27], v[136:139], v[200:203], v[24:27]
	v_mfma_f32_16x16x32_bf16 v[12:15], v[128:131], v[208:211], v[12:15]
	v_mfma_f32_16x16x32_bf16 v[8:11], v[136:139], v[208:211], v[8:11]
	v_mfma_f32_16x16x32_bf16 v[60:63], v[132:135], v[180:183], v[60:63]
	v_mfma_f32_16x16x32_bf16 v[56:59], v[140:143], v[180:183], v[56:59]
	v_mfma_f32_16x16x32_bf16 v[44:47], v[132:135], v[196:199], v[44:47]
	v_mfma_f32_16x16x32_bf16 v[40:43], v[140:143], v[196:199], v[40:43]
	v_mfma_f32_16x16x32_bf16 v[28:31], v[132:135], v[204:207], v[28:31]
	v_mfma_f32_16x16x32_bf16 v[24:27], v[140:143], v[204:207], v[24:27]
	v_mfma_f32_16x16x32_bf16 v[12:15], v[132:135], v[212:215], v[12:15]
	v_mfma_f32_16x16x32_bf16 v[8:11], v[140:143], v[212:215], v[8:11]
	v_mfma_f32_16x16x32_bf16 v[52:55], v[144:147], v[176:179], v[52:55]
	v_mfma_f32_16x16x32_bf16 v[48:51], v[168:171], v[176:179], v[48:51]
	v_mfma_f32_16x16x32_bf16 v[36:39], v[144:147], v[192:195], v[36:39]
	v_mfma_f32_16x16x32_bf16 v[32:35], v[168:171], v[192:195], v[32:35]
	v_mfma_f32_16x16x32_bf16 v[20:23], v[144:147], v[200:203], v[20:23]
	v_mfma_f32_16x16x32_bf16 v[16:19], v[168:171], v[200:203], v[16:19]
	v_mfma_f32_16x16x32_bf16 v[4:7], v[144:147], v[208:211], v[4:7]
	v_mfma_f32_16x16x32_bf16 v[0:3], v[168:171], v[208:211], v[0:3]
	v_mfma_f32_16x16x32_bf16 v[52:55], v[148:151], v[180:183], v[52:55]
	v_mfma_f32_16x16x32_bf16 v[48:51], v[172:175], v[180:183], v[48:51]
	v_mfma_f32_16x16x32_bf16 v[36:39], v[148:151], v[196:199], v[36:39]
	v_mfma_f32_16x16x32_bf16 v[32:35], v[172:175], v[196:199], v[32:35]
	v_mfma_f32_16x16x32_bf16 v[20:23], v[148:151], v[204:207], v[20:23]
	v_mfma_f32_16x16x32_bf16 v[16:19], v[172:175], v[204:207], v[16:19]
	v_mfma_f32_16x16x32_bf16 v[4:7], v[148:151], v[212:215], v[4:7]
	v_mfma_f32_16x16x32_bf16 v[0:3], v[172:175], v[212:215], v[0:3]
	s_setprio 0
	s_barrier
	s_add_i32 s77, s77, 2
	s_add_u32 s73, s73, 0x100
	s_addc_u32 s76, s76, 0
	s_cmp_gt_u32 s77, 41
	s_mov_b64 s[36:37], s[38:39]
	s_cbranch_scc0 .LBB0_1080
	v_lshl_add_u32 v168, s72, 8, v184
	v_lshl_or_b32 v128, s18, 8, v186
	v_ashrrev_i32_e32 v169, 31, v168
	v_ashrrev_i32_e32 v129, 31, v128
	v_lshlrev_b64 v[130:131], 11, v[168:169]
	v_lshl_add_u64 v[130:131], s[34:35], 0, v[130:131]
	v_lshlrev_b64 v[170:171], 1, v[128:129]
	v_lshl_add_u64 v[200:201], v[130:131], 0, v[170:171]
	global_load_dwordx4 v[192:195], v[200:201], off
	global_load_dwordx4 v[196:199], v[200:201], off offset:256
	v_or_b32_e32 v180, 16, v168
	v_or_b32_e32 v176, 32, v168
	v_or_b32_e32 v172, 48, v168
	v_ashrrev_i32_e32 v181, 31, v180
	v_ashrrev_i32_e32 v177, 31, v176
	v_ashrrev_i32_e32 v173, 31, v172
	v_lshlrev_b64 v[128:129], 11, v[180:181]
	v_lshlrev_b64 v[130:131], 11, v[176:177]
	v_lshlrev_b64 v[132:133], 11, v[172:173]
	v_lshl_add_u64 v[128:129], s[34:35], 0, v[128:129]
	v_lshl_add_u64 v[130:131], s[34:35], 0, v[130:131]
	v_lshl_add_u64 v[132:133], s[34:35], 0, v[132:133]
	v_lshl_add_u64 v[182:183], v[128:129], 0, v[170:171]
	v_lshl_add_u64 v[178:179], v[130:131], 0, v[170:171]
	v_lshl_add_u64 v[174:175], v[132:133], 0, v[170:171]
	global_load_dwordx4 v[148:151], v[182:183], off
	global_load_dwordx4 v[144:147], v[182:183], off offset:256
	global_load_dwordx4 v[140:143], v[178:179], off
	global_load_dwordx4 v[136:139], v[178:179], off offset:256
	global_load_dwordx4 v[132:135], v[174:175], off
	global_load_dwordx4 v[128:131], v[174:175], off offset:256
	v_and_b32_e32 v202, 64, v190
	v_xor_b32_e32 v191, 16, v190
	v_add_u32_e32 v202, 64, v202
	v_xor_b32_e32 v203, 32, v190
	v_cmp_lt_i32_e32 vcc, v191, v202
	s_lshl_b32 s36, s18, 2
	s_ashr_i32 s37, s36, 31
	v_cndmask_b32_e32 v191, v190, v191, vcc
	v_cmp_lt_i32_e32 vcc, v203, v202
	v_lshlrev_b32_e32 v191, 2, v191
	s_waitcnt vmcnt(0)
	v_lshlrev_b32_e32 v202, 16, v192
	v_cndmask_b32_e32 v210, v190, v203, vcc
	v_and_b32_e32 v203, 0xffff0000, v192
	v_lshlrev_b32_e32 v192, 16, v193
	v_and_b32_e32 v193, 0xffff0000, v193
	v_lshlrev_b32_e32 v204, 16, v194
	v_and_b32_e32 v205, 0xffff0000, v194
	v_lshlrev_b32_e32 v194, 16, v195
	v_and_b32_e32 v195, 0xffff0000, v195
	v_lshlrev_b32_e32 v206, 16, v196
	v_and_b32_e32 v207, 0xffff0000, v196
	v_lshlrev_b32_e32 v196, 16, v197
	v_and_b32_e32 v197, 0xffff0000, v197
	v_lshlrev_b32_e32 v208, 16, v198
	v_and_b32_e32 v209, 0xffff0000, v198
	v_lshlrev_b32_e32 v198, 16, v199
	v_and_b32_e32 v199, 0xffff0000, v199
	v_pk_add_f32 v[126:127], v[126:127], v[192:193]
	v_pk_add_f32 v[124:125], v[124:125], v[202:203]
	v_pk_add_f32 v[122:123], v[122:123], v[194:195]
	v_pk_add_f32 v[120:121], v[120:121], v[204:205]
	v_pk_add_f32 v[118:119], v[118:119], v[196:197]
	v_pk_add_f32 v[116:117], v[116:117], v[206:207]
	v_pk_add_f32 v[192:193], v[114:115], v[198:199]
	v_pk_add_f32 v[194:195], v[112:113], v[208:209]
	v_cvt_pk_bf16_f32 v112, v124, v125
	v_cvt_pk_bf16_f32 v113, v126, v127
	v_mul_f32_e32 v114, v125, v125
	v_mul_f32_e32 v115, v127, v127
	v_mul_f32_e32 v125, v121, v121
	v_mul_f32_e32 v127, v123, v123
	v_mul_f32_e32 v196, v117, v117
	v_mul_f32_e32 v197, v119, v119
	v_mul_f32_e32 v198, v195, v195
	v_mul_f32_e32 v199, v193, v193
	v_fmac_f32_e32 v114, v124, v124
	v_fmac_f32_e32 v115, v126, v126
	v_fmac_f32_e32 v125, v120, v120
	v_fmac_f32_e32 v127, v122, v122
	v_fmac_f32_e32 v196, v116, v116
	v_fmac_f32_e32 v197, v118, v118
	v_fmac_f32_e32 v198, v194, v194
	v_fmac_f32_e32 v199, v192, v192
	v_add_f32_e32 v114, v114, v115
	v_add_f32_e32 v115, v125, v127
	v_add_f32_e32 v124, v196, v197
	v_add_f32_e32 v125, v198, v199
	v_add_f32_e32 v114, v114, v115
	v_add_f32_e32 v115, v124, v125
	v_add_f32_e32 v124, v114, v115
	ds_bpermute_b32 v125, v191, v124
	v_cvt_pk_bf16_f32 v114, v120, v121
	v_cvt_pk_bf16_f32 v115, v122, v123
	global_store_dwordx4 v[200:201], v[112:115], off
	v_cvt_pk_bf16_f32 v116, v116, v117
	v_cvt_pk_bf16_f32 v117, v118, v119
	s_waitcnt lgkmcnt(0)
	v_add_f32_e32 v113, v124, v125
	v_lshlrev_b32_e32 v112, 2, v210
	ds_bpermute_b32 v114, v112, v113
	v_cvt_pk_bf16_f32 v118, v194, v195
	v_cvt_pk_bf16_f32 v119, v192, v193
	global_store_dwordx4 v[200:201], v[116:119], off offset:256
	s_and_saveexec_b64 s[38:39], s[0:1]
	s_cbranch_execz .LBB0_1083
	s_waitcnt lgkmcnt(0)
	v_add_f32_e32 v113, v113, v114
	v_lshlrev_b64 v[114:115], 6, v[168:169]
	v_lshl_add_u64 v[114:115], s[74:75], 0, v[114:115]
	v_lshl_add_u64 v[114:115], s[36:37], 2, v[114:115]
	s_lshl_b32 s18, s58, 2
	v_lshl_add_u64 v[114:115], v[114:115], 0, s[18:19]
	global_store_dword v[114:115], v113, off

.LBB0_1181:
	ds_read_b128 v[128:131], v175
	ds_read_b128 v[152:155], v175 offset:1024
	ds_read_b128 v[156:159], v175 offset:2048
	ds_read_b128 v[160:163], v175 offset:3072
	ds_read_b128 v[164:167], v176
	ds_read_b128 v[168:171], v176 offset:1024
	ds_read_b128 v[180:183], v176 offset:2048
	ds_read_b128 v[184:187], v176 offset:3072
	s_add_u32 s57, s2, 0xfffc0080
	s_addc_u32 s58, s3, -1
	s_cmp_eq_u32 s56, 12
	s_cselect_b32 s65, s37, s58
	s_cselect_b32 s64, s52, s57
	s_cselect_b32 s63, s39, s55
	s_cselect_b32 s62, s53, s54
	v_lshl_add_u64 v[220:221], s[2:3], 0, v[144:145]
	s_add_i32 m0, s79, 0xc000
	ds_read_b128 v[188:191], v177
	ds_read_b128 v[192:195], v177 offset:1024
	ds_read_b128 v[196:199], v177 offset:2048
	ds_read_b128 v[200:203], v177 offset:3072
	ds_read_b128 v[204:207], v177 offset:4096
	ds_read_b128 v[208:211], v177 offset:5120
	ds_read_b128 v[212:215], v177 offset:6144
	ds_read_b128 v[216:219], v177 offset:7168
	global_load_lds_dwordx4 v[220:221], off
	v_lshl_add_u64 v[220:221], s[2:3], 0, v[146:147]
	s_add_i32 m0, s79, 0xe000
	s_nop 0
	global_load_lds_dwordx4 v[220:221], off
	s_waitcnt vmcnt(8)
	s_waitcnt lgkmcnt(0)
	s_barrier
	s_setprio 1
	s_waitcnt lgkmcnt(0)
	v_mfma_f32_16x16x32_bf16 v[124:127], v[128:131], v[188:191], v[124:127]
	v_mfma_f32_16x16x32_bf16 v[120:123], v[156:159], v[188:191], v[120:123]
	v_mfma_f32_16x16x32_bf16 v[116:119], v[128:131], v[196:199], v[116:119]
	v_mfma_f32_16x16x32_bf16 v[112:115], v[156:159], v[196:199], v[112:115]
	v_mfma_f32_16x16x32_bf16 v[100:103], v[128:131], v[204:207], v[100:103]
	v_mfma_f32_16x16x32_bf16 v[96:99], v[156:159], v[204:207], v[96:99]
	v_mfma_f32_16x16x32_bf16 v[80:83], v[128:131], v[212:215], v[80:83]
	v_mfma_f32_16x16x32_bf16 v[76:79], v[156:159], v[212:215], v[76:79]
	v_mfma_f32_16x16x32_bf16 v[124:127], v[152:155], v[192:195], v[124:127]
	v_mfma_f32_16x16x32_bf16 v[120:123], v[160:163], v[192:195], v[120:123]
	v_mfma_f32_16x16x32_bf16 v[116:119], v[152:155], v[200:203], v[116:119]
	v_mfma_f32_16x16x32_bf16 v[112:115], v[160:163], v[200:203], v[112:115]
	v_mfma_f32_16x16x32_bf16 v[100:103], v[152:155], v[208:211], v[100:103]
	v_mfma_f32_16x16x32_bf16 v[96:99], v[160:163], v[208:211], v[96:99]
	v_mfma_f32_16x16x32_bf16 v[80:83], v[152:155], v[216:219], v[80:83]
	v_mfma_f32_16x16x32_bf16 v[76:79], v[160:163], v[216:219], v[76:79]
	v_mfma_f32_16x16x32_bf16 v[108:111], v[164:167], v[188:191], v[108:111]
	v_mfma_f32_16x16x32_bf16 v[104:107], v[180:183], v[188:191], v[104:107]
	v_mfma_f32_16x16x32_bf16 v[92:95], v[164:167], v[196:199], v[92:95]
	v_mfma_f32_16x16x32_bf16 v[88:91], v[180:183], v[196:199], v[88:91]
	v_mfma_f32_16x16x32_bf16 v[84:87], v[164:167], v[204:207], v[84:87]
	v_mfma_f32_16x16x32_bf16 v[72:75], v[180:183], v[204:207], v[72:75]
	v_mfma_f32_16x16x32_bf16 v[68:71], v[164:167], v[212:215], v[68:71]
	v_mfma_f32_16x16x32_bf16 v[32:35], v[180:183], v[212:215], v[32:35]
	v_mfma_f32_16x16x32_bf16 v[108:111], v[168:171], v[192:195], v[108:111]
	v_mfma_f32_16x16x32_bf16 v[104:107], v[184:187], v[192:195], v[104:107]
	v_mfma_f32_16x16x32_bf16 v[92:95], v[168:171], v[200:203], v[92:95]
	v_mfma_f32_16x16x32_bf16 v[88:91], v[184:187], v[200:203], v[88:91]
	v_mfma_f32_16x16x32_bf16 v[84:87], v[168:171], v[208:211], v[84:87]
	v_mfma_f32_16x16x32_bf16 v[72:75], v[184:187], v[208:211], v[72:75]
	v_mfma_f32_16x16x32_bf16 v[68:71], v[168:171], v[216:219], v[68:71]
	v_mfma_f32_16x16x32_bf16 v[32:35], v[184:187], v[216:219], v[32:35]
	s_setprio 0
	s_barrier
	s_add_i32 s57, s89, s66
	v_lshl_add_u64 v[220:221], s[62:63], 0, v[134:135]
	s_mov_b32 m0, s57
	ds_read_b128 v[188:191], v177 offset:16384
	ds_read_b128 v[192:195], v177 offset:17408
	ds_read_b128 v[196:199], v177 offset:18432
	ds_read_b128 v[200:203], v177 offset:19456
	ds_read_b128 v[204:207], v177 offset:20480
	ds_read_b128 v[208:211], v177 offset:21504
	ds_read_b128 v[212:215], v177 offset:22528
	ds_read_b128 v[216:219], v177 offset:23552
	global_load_lds_dwordx4 v[220:221], off
	s_add_i32 m0, s57, 0x2000
	s_add_u32 s58, s62, 0x40000
	v_lshl_add_u64 v[222:223], s[62:63], 0, v[138:139]
	s_addc_u32 s59, s63, 0
	s_add_i32 s57, s90, s66
	global_load_lds_dwordx4 v[222:223], off
	v_lshl_add_u64 v[224:225], s[58:59], 0, v[134:135]
	s_mov_b32 m0, s57
	v_lshl_add_u64 v[226:227], s[64:65], 0, v[136:137]
	global_load_lds_dwordx4 v[224:225], off
	v_lshl_add_u64 v[224:225], s[58:59], 0, v[138:139]
	s_add_i32 m0, s57, 0x2000
	s_nop 0
	global_load_lds_dwordx4 v[224:225], off
	v_lshl_add_u64 v[224:225], s[64:65], 0, v[132:133]
	s_mov_b32 m0, s79
	s_nop 0
	global_load_lds_dwordx4 v[224:225], off
	s_mov_b32 m0, s80
	s_nop 0
	global_load_lds_dwordx4 v[226:227], off
	s_waitcnt vmcnt(8)
	s_waitcnt lgkmcnt(0)
	s_barrier
	s_setprio 1
	s_waitcnt lgkmcnt(0)
	v_mfma_f32_16x16x32_bf16 v[64:67], v[128:131], v[188:191], v[64:67]
	v_mfma_f32_16x16x32_bf16 v[60:63], v[156:159], v[188:191], v[60:63]
	v_mfma_f32_16x16x32_bf16 v[56:59], v[128:131], v[196:199], v[56:59]
	v_mfma_f32_16x16x32_bf16 v[52:55], v[156:159], v[196:199], v[52:55]
	v_mfma_f32_16x16x32_bf16 v[48:51], v[128:131], v[204:207], v[48:51]
	v_mfma_f32_16x16x32_bf16 v[44:47], v[156:159], v[204:207], v[44:47]
	v_mfma_f32_16x16x32_bf16 v[40:43], v[128:131], v[212:215], v[40:43]
	v_mfma_f32_16x16x32_bf16 v[36:39], v[156:159], v[212:215], v[36:39]
	v_mfma_f32_16x16x32_bf16 v[64:67], v[152:155], v[192:195], v[64:67]
	v_mfma_f32_16x16x32_bf16 v[60:63], v[160:163], v[192:195], v[60:63]
	v_mfma_f32_16x16x32_bf16 v[56:59], v[152:155], v[200:203], v[56:59]
	v_mfma_f32_16x16x32_bf16 v[52:55], v[160:163], v[200:203], v[52:55]
	v_mfma_f32_16x16x32_bf16 v[48:51], v[152:155], v[208:211], v[48:51]
	v_mfma_f32_16x16x32_bf16 v[44:47], v[160:163], v[208:211], v[44:47]
	v_mfma_f32_16x16x32_bf16 v[40:43], v[152:155], v[216:219], v[40:43]
	v_mfma_f32_16x16x32_bf16 v[36:39], v[160:163], v[216:219], v[36:39]
	v_mfma_f32_16x16x32_bf16 v[28:31], v[164:167], v[188:191], v[28:31]
	v_mfma_f32_16x16x32_bf16 v[24:27], v[180:183], v[188:191], v[24:27]
	v_mfma_f32_16x16x32_bf16 v[20:23], v[164:167], v[196:199], v[20:23]
	v_mfma_f32_16x16x32_bf16 v[16:19], v[180:183], v[196:199], v[16:19]
	v_mfma_f32_16x16x32_bf16 v[12:15], v[164:167], v[204:207], v[12:15]
	v_mfma_f32_16x16x32_bf16 v[8:11], v[180:183], v[204:207], v[8:11]
	v_mfma_f32_16x16x32_bf16 v[4:7], v[164:167], v[212:215], v[4:7]
	v_mfma_f32_16x16x32_bf16 v[0:3], v[180:183], v[212:215], v[0:3]
	v_mfma_f32_16x16x32_bf16 v[28:31], v[168:171], v[192:195], v[28:31]
	v_mfma_f32_16x16x32_bf16 v[24:27], v[184:187], v[192:195], v[24:27]
	v_mfma_f32_16x16x32_bf16 v[20:23], v[168:171], v[200:203], v[20:23]
	v_mfma_f32_16x16x32_bf16 v[16:19], v[184:187], v[200:203], v[16:19]
	v_mfma_f32_16x16x32_bf16 v[12:15], v[168:171], v[208:211], v[12:15]
	v_mfma_f32_16x16x32_bf16 v[8:11], v[184:187], v[208:211], v[8:11]
	v_mfma_f32_16x16x32_bf16 v[4:7], v[168:171], v[216:219], v[4:7]
	v_mfma_f32_16x16x32_bf16 v[0:3], v[184:187], v[216:219], v[0:3]
	s_setprio 0
	s_barrier
	s_add_i32 s57, 0, 0x18000
	v_add_u32_e32 v140, s57, v173
	s_add_i32 s68, 0, 0x1c000
	ds_read_b128 v[128:131], v140
	ds_read_b128 v[152:155], v140 offset:1024
	ds_read_b128 v[156:159], v140 offset:2048
	ds_read_b128 v[160:163], v140 offset:3072
	v_add_u32_e32 v140, s68, v173
	ds_read_b128 v[164:167], v140
	ds_read_b128 v[168:171], v140 offset:1024
	ds_read_b128 v[180:183], v140 offset:2048
	ds_read_b128 v[184:187], v140 offset:3072
	s_add_u32 s58, s64, 0x40000
	s_addc_u32 s59, s65, 0
	s_mov_b32 m0, s81
	v_lshl_add_u64 v[228:229], s[58:59], 0, v[132:133]
	ds_read_b128 v[188:191], v177 offset:32768
	ds_read_b128 v[192:195], v177 offset:33792
	ds_read_b128 v[196:199], v177 offset:34816
	ds_read_b128 v[200:203], v177 offset:35840
	ds_read_b128 v[204:207], v177 offset:36864
	ds_read_b128 v[208:211], v177 offset:37888
	ds_read_b128 v[212:215], v177 offset:38912
	ds_read_b128 v[216:219], v177 offset:39936
	global_load_lds_dwordx4 v[228:229], off
	v_lshl_add_u64 v[228:229], s[58:59], 0, v[136:137]
	s_mov_b32 m0, s82
	s_nop 0
	global_load_lds_dwordx4 v[228:229], off
	s_waitcnt vmcnt(8)
	s_waitcnt lgkmcnt(0)
	s_barrier
	s_setprio 1
	s_waitcnt lgkmcnt(0)
	v_mfma_f32_16x16x32_bf16 v[124:127], v[128:131], v[188:191], v[124:127]
	v_mfma_f32_16x16x32_bf16 v[120:123], v[156:159], v[188:191], v[120:123]
	v_mfma_f32_16x16x32_bf16 v[116:119], v[128:131], v[196:199], v[116:119]
	v_mfma_f32_16x16x32_bf16 v[112:115], v[156:159], v[196:199], v[112:115]
	v_mfma_f32_16x16x32_bf16 v[100:103], v[128:131], v[204:207], v[100:103]
	v_mfma_f32_16x16x32_bf16 v[96:99], v[156:159], v[204:207], v[96:99]
	v_mfma_f32_16x16x32_bf16 v[80:83], v[128:131], v[212:215], v[80:83]
	v_mfma_f32_16x16x32_bf16 v[76:79], v[156:159], v[212:215], v[76:79]
	v_mfma_f32_16x16x32_bf16 v[124:127], v[152:155], v[192:195], v[124:127]
	v_mfma_f32_16x16x32_bf16 v[120:123], v[160:163], v[192:195], v[120:123]
	v_mfma_f32_16x16x32_bf16 v[116:119], v[152:155], v[200:203], v[116:119]
	v_mfma_f32_16x16x32_bf16 v[112:115], v[160:163], v[200:203], v[112:115]
	v_mfma_f32_16x16x32_bf16 v[100:103], v[152:155], v[208:211], v[100:103]
	v_mfma_f32_16x16x32_bf16 v[96:99], v[160:163], v[208:211], v[96:99]
	v_mfma_f32_16x16x32_bf16 v[80:83], v[152:155], v[216:219], v[80:83]
	v_mfma_f32_16x16x32_bf16 v[76:79], v[160:163], v[216:219], v[76:79]
	v_mfma_f32_16x16x32_bf16 v[108:111], v[164:167], v[188:191], v[108:111]
	v_mfma_f32_16x16x32_bf16 v[104:107], v[180:183], v[188:191], v[104:107]
	v_mfma_f32_16x16x32_bf16 v[92:95], v[164:167], v[196:199], v[92:95]
	v_mfma_f32_16x16x32_bf16 v[88:91], v[180:183], v[196:199], v[88:91]
	v_mfma_f32_16x16x32_bf16 v[84:87], v[164:167], v[204:207], v[84:87]
	v_mfma_f32_16x16x32_bf16 v[72:75], v[180:183], v[204:207], v[72:75]
	v_mfma_f32_16x16x32_bf16 v[68:71], v[164:167], v[212:215], v[68:71]
	v_mfma_f32_16x16x32_bf16 v[32:35], v[180:183], v[212:215], v[32:35]
	v_mfma_f32_16x16x32_bf16 v[108:111], v[168:171], v[192:195], v[108:111]
	v_mfma_f32_16x16x32_bf16 v[104:107], v[184:187], v[192:195], v[104:107]
	v_mfma_f32_16x16x32_bf16 v[92:95], v[168:171], v[200:203], v[92:95]
	v_mfma_f32_16x16x32_bf16 v[88:91], v[184:187], v[200:203], v[88:91]
	v_mfma_f32_16x16x32_bf16 v[84:87], v[168:171], v[208:211], v[84:87]
	v_mfma_f32_16x16x32_bf16 v[72:75], v[184:187], v[208:211], v[72:75]
	v_mfma_f32_16x16x32_bf16 v[68:71], v[168:171], v[216:219], v[68:71]
	v_mfma_f32_16x16x32_bf16 v[32:35], v[184:187], v[216:219], v[32:35]
	s_setprio 0
	s_barrier
	s_add_i32 s57, s57, s66
	v_lshl_add_u64 v[220:221], v[220:221], 0, s[12:13]
	s_mov_b32 m0, s57
	ds_read_b128 v[188:191], v177 offset:49152
	ds_read_b128 v[192:195], v177 offset:50176
	ds_read_b128 v[196:199], v177 offset:51200
	ds_read_b128 v[200:203], v177 offset:52224
	ds_read_b128 v[204:207], v177 offset:53248
	ds_read_b128 v[208:211], v177 offset:54272
	ds_read_b128 v[212:215], v177 offset:55296
	ds_read_b128 v[216:219], v177 offset:56320
	global_load_lds_dwordx4 v[220:221], off
	s_add_i32 m0, s57, 0x2000
	s_add_u32 s58, s62, 0x40080
	v_lshl_add_u64 v[220:221], v[222:223], 0, s[12:13]
	s_addc_u32 s59, s63, 0
	s_add_i32 s57, s68, s66
	global_load_lds_dwordx4 v[220:221], off
	v_lshl_add_u64 v[220:221], s[58:59], 0, v[134:135]
	s_mov_b32 m0, s57
	s_nop 0
	global_load_lds_dwordx4 v[220:221], off
	v_lshl_add_u64 v[220:221], s[58:59], 0, v[138:139]
	s_add_i32 m0, s57, 0x2000
	s_nop 0
	global_load_lds_dwordx4 v[220:221], off
	v_lshl_add_u64 v[220:221], v[224:225], 0, s[12:13]
	s_mov_b32 m0, s86
	s_nop 0
	global_load_lds_dwordx4 v[220:221], off
	v_lshl_add_u64 v[220:221], v[226:227], 0, s[12:13]
	s_mov_b32 m0, s87
	s_nop 0
	global_load_lds_dwordx4 v[220:221], off
	s_waitcnt vmcnt(8)
	s_waitcnt lgkmcnt(0)
	s_barrier
	s_setprio 1
	s_waitcnt lgkmcnt(0)
	v_mfma_f32_16x16x32_bf16 v[64:67], v[128:131], v[188:191], v[64:67]
	v_mfma_f32_16x16x32_bf16 v[60:63], v[156:159], v[188:191], v[60:63]
	v_mfma_f32_16x16x32_bf16 v[56:59], v[128:131], v[196:199], v[56:59]
	v_mfma_f32_16x16x32_bf16 v[52:55], v[156:159], v[196:199], v[52:55]
	v_mfma_f32_16x16x32_bf16 v[48:51], v[128:131], v[204:207], v[48:51]
	v_mfma_f32_16x16x32_bf16 v[44:47], v[156:159], v[204:207], v[44:47]
	v_mfma_f32_16x16x32_bf16 v[40:43], v[128:131], v[212:215], v[40:43]
	v_mfma_f32_16x16x32_bf16 v[36:39], v[156:159], v[212:215], v[36:39]
	v_mfma_f32_16x16x32_bf16 v[64:67], v[152:155], v[192:195], v[64:67]
	v_mfma_f32_16x16x32_bf16 v[60:63], v[160:163], v[192:195], v[60:63]
	v_mfma_f32_16x16x32_bf16 v[56:59], v[152:155], v[200:203], v[56:59]
	v_mfma_f32_16x16x32_bf16 v[52:55], v[160:163], v[200:203], v[52:55]
	v_mfma_f32_16x16x32_bf16 v[48:51], v[152:155], v[208:211], v[48:51]
	v_mfma_f32_16x16x32_bf16 v[44:47], v[160:163], v[208:211], v[44:47]
	v_mfma_f32_16x16x32_bf16 v[40:43], v[152:155], v[216:219], v[40:43]
	v_mfma_f32_16x16x32_bf16 v[36:39], v[160:163], v[216:219], v[36:39]
	v_mfma_f32_16x16x32_bf16 v[28:31], v[164:167], v[188:191], v[28:31]
	v_mfma_f32_16x16x32_bf16 v[24:27], v[180:183], v[188:191], v[24:27]
	v_mfma_f32_16x16x32_bf16 v[20:23], v[164:167], v[196:199], v[20:23]
	v_mfma_f32_16x16x32_bf16 v[16:19], v[180:183], v[196:199], v[16:19]
	v_mfma_f32_16x16x32_bf16 v[12:15], v[164:167], v[204:207], v[12:15]
	v_mfma_f32_16x16x32_bf16 v[8:11], v[180:183], v[204:207], v[8:11]
	v_mfma_f32_16x16x32_bf16 v[4:7], v[164:167], v[212:215], v[4:7]
	v_mfma_f32_16x16x32_bf16 v[0:3], v[180:183], v[212:215], v[0:3]
	v_mfma_f32_16x16x32_bf16 v[28:31], v[168:171], v[192:195], v[28:31]
	v_mfma_f32_16x16x32_bf16 v[24:27], v[184:187], v[192:195], v[24:27]
	v_mfma_f32_16x16x32_bf16 v[20:23], v[168:171], v[200:203], v[20:23]
	v_mfma_f32_16x16x32_bf16 v[16:19], v[184:187], v[200:203], v[16:19]
	v_mfma_f32_16x16x32_bf16 v[12:15], v[168:171], v[208:211], v[12:15]
	v_mfma_f32_16x16x32_bf16 v[8:11], v[184:187], v[208:211], v[8:11]
	v_mfma_f32_16x16x32_bf16 v[4:7], v[168:171], v[216:219], v[4:7]
	v_mfma_f32_16x16x32_bf16 v[0:3], v[184:187], v[216:219], v[0:3]
	s_setprio 0
	s_barrier
	s_add_i32 s56, s56, 2
	s_add_u32 s2, s2, 0x100
	s_addc_u32 s3, s3, 0
	s_add_u32 s54, s54, 0x100
	s_addc_u32 s55, s55, 0
	s_cmp_gt_u32 s56, 13
	s_cbranch_scc0 .LBB0_1181
	s_and_b64 vcc, exec, s[14:15]
	s_cbranch_vccz .LBB0_1184
	s_barrier

.LBB0_1530:
	ds_read_b128 v[128:131], v187
	ds_read_b128 v[132:135], v187 offset:1024
	ds_read_b128 v[136:139], v187 offset:2048
	ds_read_b128 v[140:143], v187 offset:3072
	ds_read_b128 v[144:147], v188
	ds_read_b128 v[148:151], v188 offset:1024
	ds_read_b128 v[168:171], v188 offset:2048
	ds_read_b128 v[172:175], v188 offset:3072
	s_add_u32 s36, s24, 0xfffc0080
	s_addc_u32 s37, s25, -1
	s_cmp_eq_u32 s65, 12
	s_cselect_b32 s39, s11, s37
	s_cselect_b32 s38, s61, s36
	s_cselect_b32 s37, s13, s64
	s_cselect_b32 s36, s62, s63
	v_lshl_add_u64 v[216:217], s[24:25], 0, v[160:161]
	s_add_i32 m0, s46, 0xc000
	ds_read_b128 v[176:179], v189
	ds_read_b128 v[180:183], v189 offset:1024
	ds_read_b128 v[192:195], v189 offset:2048
	ds_read_b128 v[196:199], v189 offset:3072
	ds_read_b128 v[200:203], v189 offset:4096
	ds_read_b128 v[204:207], v189 offset:5120
	ds_read_b128 v[208:211], v189 offset:6144
	ds_read_b128 v[212:215], v189 offset:7168
	global_load_lds_dwordx4 v[216:217], off
	v_lshl_add_u64 v[216:217], s[24:25], 0, v[162:163]
	s_add_i32 m0, s46, 0xe000
	s_nop 0
	global_load_lds_dwordx4 v[216:217], off
	s_waitcnt vmcnt(8)
	s_waitcnt lgkmcnt(0)
	s_barrier
	s_setprio 1
	s_waitcnt lgkmcnt(0)
	v_mfma_f32_16x16x32_bf16 v[124:127], v[128:131], v[176:179], v[124:127]
	v_mfma_f32_16x16x32_bf16 v[120:123], v[136:139], v[176:179], v[120:123]
	v_mfma_f32_16x16x32_bf16 v[108:111], v[128:131], v[192:195], v[108:111]
	v_mfma_f32_16x16x32_bf16 v[104:107], v[136:139], v[192:195], v[104:107]
	v_mfma_f32_16x16x32_bf16 v[92:95], v[128:131], v[200:203], v[92:95]
	v_mfma_f32_16x16x32_bf16 v[88:91], v[136:139], v[200:203], v[88:91]
	v_mfma_f32_16x16x32_bf16 v[76:79], v[128:131], v[208:211], v[76:79]
	v_mfma_f32_16x16x32_bf16 v[72:75], v[136:139], v[208:211], v[72:75]
	v_mfma_f32_16x16x32_bf16 v[124:127], v[132:135], v[180:183], v[124:127]
	v_mfma_f32_16x16x32_bf16 v[120:123], v[140:143], v[180:183], v[120:123]
	v_mfma_f32_16x16x32_bf16 v[108:111], v[132:135], v[196:199], v[108:111]
	v_mfma_f32_16x16x32_bf16 v[104:107], v[140:143], v[196:199], v[104:107]
	v_mfma_f32_16x16x32_bf16 v[92:95], v[132:135], v[204:207], v[92:95]
	v_mfma_f32_16x16x32_bf16 v[88:91], v[140:143], v[204:207], v[88:91]
	v_mfma_f32_16x16x32_bf16 v[76:79], v[132:135], v[212:215], v[76:79]
	v_mfma_f32_16x16x32_bf16 v[72:75], v[140:143], v[212:215], v[72:75]
	v_mfma_f32_16x16x32_bf16 v[116:119], v[144:147], v[176:179], v[116:119]
	v_mfma_f32_16x16x32_bf16 v[112:115], v[168:171], v[176:179], v[112:115]
	v_mfma_f32_16x16x32_bf16 v[100:103], v[144:147], v[192:195], v[100:103]
	v_mfma_f32_16x16x32_bf16 v[96:99], v[168:171], v[192:195], v[96:99]
	v_mfma_f32_16x16x32_bf16 v[84:87], v[144:147], v[200:203], v[84:87]
	v_mfma_f32_16x16x32_bf16 v[80:83], v[168:171], v[200:203], v[80:83]
	v_mfma_f32_16x16x32_bf16 v[68:71], v[144:147], v[208:211], v[68:71]
	v_mfma_f32_16x16x32_bf16 v[64:67], v[168:171], v[208:211], v[64:67]
	v_mfma_f32_16x16x32_bf16 v[116:119], v[148:151], v[180:183], v[116:119]
	v_mfma_f32_16x16x32_bf16 v[112:115], v[172:175], v[180:183], v[112:115]
	v_mfma_f32_16x16x32_bf16 v[100:103], v[148:151], v[196:199], v[100:103]
	v_mfma_f32_16x16x32_bf16 v[96:99], v[172:175], v[196:199], v[96:99]
	v_mfma_f32_16x16x32_bf16 v[84:87], v[148:151], v[204:207], v[84:87]
	v_mfma_f32_16x16x32_bf16 v[80:83], v[172:175], v[204:207], v[80:83]
	v_mfma_f32_16x16x32_bf16 v[68:71], v[148:151], v[212:215], v[68:71]
	v_mfma_f32_16x16x32_bf16 v[64:67], v[172:175], v[212:215], v[64:67]
	s_setprio 0
	s_barrier
	s_add_i32 s66, s55, s45
	v_lshl_add_u64 v[216:217], s[36:37], 0, v[154:155]
	s_mov_b32 m0, s66
	ds_read_b128 v[176:179], v189 offset:16384
	ds_read_b128 v[180:183], v189 offset:17408
	ds_read_b128 v[192:195], v189 offset:18432
	ds_read_b128 v[196:199], v189 offset:19456
	ds_read_b128 v[200:203], v189 offset:20480
	ds_read_b128 v[204:207], v189 offset:21504
	ds_read_b128 v[208:211], v189 offset:22528
	ds_read_b128 v[212:215], v189 offset:23552
	global_load_lds_dwordx4 v[216:217], off
	s_add_i32 m0, s66, 0x2000
	s_add_u32 s66, s36, 0x40000
	v_lshl_add_u64 v[218:219], s[36:37], 0, v[158:159]
	s_addc_u32 s67, s37, 0
	s_add_i32 s68, s56, s45
	global_load_lds_dwordx4 v[218:219], off
	v_lshl_add_u64 v[220:221], s[66:67], 0, v[154:155]
	s_mov_b32 m0, s68
	v_lshl_add_u64 v[222:223], s[38:39], 0, v[156:157]
	global_load_lds_dwordx4 v[220:221], off
	v_lshl_add_u64 v[220:221], s[66:67], 0, v[158:159]
	s_add_i32 m0, s68, 0x2000
	s_nop 0
	global_load_lds_dwordx4 v[220:221], off
	v_lshl_add_u64 v[220:221], s[38:39], 0, v[152:153]
	s_mov_b32 m0, s46
	s_nop 0
	global_load_lds_dwordx4 v[220:221], off
	s_mov_b32 m0, s47
	s_nop 0
	global_load_lds_dwordx4 v[222:223], off
	s_waitcnt vmcnt(8)
	s_waitcnt lgkmcnt(0)
	s_barrier
	s_setprio 1
	s_waitcnt lgkmcnt(0)
	v_mfma_f32_16x16x32_bf16 v[60:63], v[128:131], v[176:179], v[60:63]
	v_mfma_f32_16x16x32_bf16 v[56:59], v[136:139], v[176:179], v[56:59]
	v_mfma_f32_16x16x32_bf16 v[44:47], v[128:131], v[192:195], v[44:47]
	v_mfma_f32_16x16x32_bf16 v[40:43], v[136:139], v[192:195], v[40:43]
	v_mfma_f32_16x16x32_bf16 v[28:31], v[128:131], v[200:203], v[28:31]
	v_mfma_f32_16x16x32_bf16 v[24:27], v[136:139], v[200:203], v[24:27]
	v_mfma_f32_16x16x32_bf16 v[12:15], v[128:131], v[208:211], v[12:15]
	v_mfma_f32_16x16x32_bf16 v[8:11], v[136:139], v[208:211], v[8:11]
	v_mfma_f32_16x16x32_bf16 v[60:63], v[132:135], v[180:183], v[60:63]
	v_mfma_f32_16x16x32_bf16 v[56:59], v[140:143], v[180:183], v[56:59]
	v_mfma_f32_16x16x32_bf16 v[44:47], v[132:135], v[196:199], v[44:47]
	v_mfma_f32_16x16x32_bf16 v[40:43], v[140:143], v[196:199], v[40:43]
	v_mfma_f32_16x16x32_bf16 v[28:31], v[132:135], v[204:207], v[28:31]
	v_mfma_f32_16x16x32_bf16 v[24:27], v[140:143], v[204:207], v[24:27]
	v_mfma_f32_16x16x32_bf16 v[12:15], v[132:135], v[212:215], v[12:15]
	v_mfma_f32_16x16x32_bf16 v[8:11], v[140:143], v[212:215], v[8:11]
	v_mfma_f32_16x16x32_bf16 v[52:55], v[144:147], v[176:179], v[52:55]
	v_mfma_f32_16x16x32_bf16 v[48:51], v[168:171], v[176:179], v[48:51]
	v_mfma_f32_16x16x32_bf16 v[36:39], v[144:147], v[192:195], v[36:39]
	v_mfma_f32_16x16x32_bf16 v[32:35], v[168:171], v[192:195], v[32:35]
	v_mfma_f32_16x16x32_bf16 v[20:23], v[144:147], v[200:203], v[20:23]
	v_mfma_f32_16x16x32_bf16 v[16:19], v[168:171], v[200:203], v[16:19]
	v_mfma_f32_16x16x32_bf16 v[4:7], v[144:147], v[208:211], v[4:7]
	v_mfma_f32_16x16x32_bf16 v[0:3], v[168:171], v[208:211], v[0:3]
	v_mfma_f32_16x16x32_bf16 v[52:55], v[148:151], v[180:183], v[52:55]
	v_mfma_f32_16x16x32_bf16 v[48:51], v[172:175], v[180:183], v[48:51]
	v_mfma_f32_16x16x32_bf16 v[36:39], v[148:151], v[196:199], v[36:39]
	v_mfma_f32_16x16x32_bf16 v[32:35], v[172:175], v[196:199], v[32:35]
	v_mfma_f32_16x16x32_bf16 v[20:23], v[148:151], v[204:207], v[20:23]
	v_mfma_f32_16x16x32_bf16 v[16:19], v[172:175], v[204:207], v[16:19]
	v_mfma_f32_16x16x32_bf16 v[4:7], v[148:151], v[212:215], v[4:7]
	v_mfma_f32_16x16x32_bf16 v[0:3], v[172:175], v[212:215], v[0:3]
	s_setprio 0
	s_barrier
	s_add_i32 s66, 0, 0x18000
	s_add_i32 s67, 0, 0x1c000
	v_add_u32_e32 v140, s66, v185
	v_add_u32_e32 v172, s67, v185
	ds_read_b128 v[128:131], v140
	ds_read_b128 v[132:135], v140 offset:1024
	ds_read_b128 v[136:139], v140 offset:2048
	ds_read_b128 v[140:143], v140 offset:3072
	ds_read_b128 v[144:147], v172
	ds_read_b128 v[148:151], v172 offset:1024
	ds_read_b128 v[168:171], v172 offset:2048
	ds_read_b128 v[172:175], v172 offset:3072
	s_add_u32 s38, s38, 0x40000
	s_addc_u32 s39, s39, 0
	s_mov_b32 m0, s48
	v_lshl_add_u64 v[224:225], s[38:39], 0, v[152:153]
	ds_read_b128 v[176:179], v189 offset:32768
	ds_read_b128 v[180:183], v189 offset:33792
	ds_read_b128 v[192:195], v189 offset:34816
	ds_read_b128 v[196:199], v189 offset:35840
	ds_read_b128 v[200:203], v189 offset:36864
	ds_read_b128 v[204:207], v189 offset:37888
	ds_read_b128 v[208:211], v189 offset:38912
	ds_read_b128 v[212:215], v189 offset:39936
	global_load_lds_dwordx4 v[224:225], off
	v_lshl_add_u64 v[224:225], s[38:39], 0, v[156:157]
	s_mov_b32 m0, s49
	s_nop 0
	global_load_lds_dwordx4 v[224:225], off
	s_waitcnt vmcnt(8)
	s_waitcnt lgkmcnt(0)
	s_barrier
	s_setprio 1
	s_waitcnt lgkmcnt(0)
	v_mfma_f32_16x16x32_bf16 v[124:127], v[128:131], v[176:179], v[124:127]
	v_mfma_f32_16x16x32_bf16 v[120:123], v[136:139], v[176:179], v[120:123]
	v_mfma_f32_16x16x32_bf16 v[108:111], v[128:131], v[192:195], v[108:111]
	v_mfma_f32_16x16x32_bf16 v[104:107], v[136:139], v[192:195], v[104:107]
	v_mfma_f32_16x16x32_bf16 v[92:95], v[128:131], v[200:203], v[92:95]
	v_mfma_f32_16x16x32_bf16 v[88:91], v[136:139], v[200:203], v[88:91]
	v_mfma_f32_16x16x32_bf16 v[76:79], v[128:131], v[208:211], v[76:79]
	v_mfma_f32_16x16x32_bf16 v[72:75], v[136:139], v[208:211], v[72:75]
	v_mfma_f32_16x16x32_bf16 v[124:127], v[132:135], v[180:183], v[124:127]
	v_mfma_f32_16x16x32_bf16 v[120:123], v[140:143], v[180:183], v[120:123]
	v_mfma_f32_16x16x32_bf16 v[108:111], v[132:135], v[196:199], v[108:111]
	v_mfma_f32_16x16x32_bf16 v[104:107], v[140:143], v[196:199], v[104:107]
	v_mfma_f32_16x16x32_bf16 v[92:95], v[132:135], v[204:207], v[92:95]
	v_mfma_f32_16x16x32_bf16 v[88:91], v[140:143], v[204:207], v[88:91]
	v_mfma_f32_16x16x32_bf16 v[76:79], v[132:135], v[212:215], v[76:79]
	v_mfma_f32_16x16x32_bf16 v[72:75], v[140:143], v[212:215], v[72:75]
	v_mfma_f32_16x16x32_bf16 v[116:119], v[144:147], v[176:179], v[116:119]
	v_mfma_f32_16x16x32_bf16 v[112:115], v[168:171], v[176:179], v[112:115]
	v_mfma_f32_16x16x32_bf16 v[100:103], v[144:147], v[192:195], v[100:103]
	v_mfma_f32_16x16x32_bf16 v[96:99], v[168:171], v[192:195], v[96:99]
	v_mfma_f32_16x16x32_bf16 v[84:87], v[144:147], v[200:203], v[84:87]
	v_mfma_f32_16x16x32_bf16 v[80:83], v[168:171], v[200:203], v[80:83]
	v_mfma_f32_16x16x32_bf16 v[68:71], v[144:147], v[208:211], v[68:71]
	v_mfma_f32_16x16x32_bf16 v[64:67], v[168:171], v[208:211], v[64:67]
	v_mfma_f32_16x16x32_bf16 v[116:119], v[148:151], v[180:183], v[116:119]
	v_mfma_f32_16x16x32_bf16 v[112:115], v[172:175], v[180:183], v[112:115]
	v_mfma_f32_16x16x32_bf16 v[100:103], v[148:151], v[196:199], v[100:103]
	v_mfma_f32_16x16x32_bf16 v[96:99], v[172:175], v[196:199], v[96:99]
	v_mfma_f32_16x16x32_bf16 v[84:87], v[148:151], v[204:207], v[84:87]
	v_mfma_f32_16x16x32_bf16 v[80:83], v[172:175], v[204:207], v[80:83]
	v_mfma_f32_16x16x32_bf16 v[68:71], v[148:151], v[212:215], v[68:71]
	v_mfma_f32_16x16x32_bf16 v[64:67], v[172:175], v[212:215], v[64:67]
	s_setprio 0
	s_barrier
	s_add_i32 s38, s66, s45
	v_lshl_add_u64 v[216:217], v[216:217], 0, s[6:7]
	s_mov_b32 m0, s38
	ds_read_b128 v[176:179], v189 offset:49152
	ds_read_b128 v[180:183], v189 offset:50176
	ds_read_b128 v[192:195], v189 offset:51200
	ds_read_b128 v[196:199], v189 offset:52224
	ds_read_b128 v[200:203], v189 offset:53248
	ds_read_b128 v[204:207], v189 offset:54272
	ds_read_b128 v[208:211], v189 offset:55296
	ds_read_b128 v[212:215], v189 offset:56320
	global_load_lds_dwordx4 v[216:217], off
	s_add_i32 m0, s38, 0x2000
	s_add_u32 s36, s36, 0x40080
	v_lshl_add_u64 v[216:217], v[218:219], 0, s[6:7]
	s_addc_u32 s37, s37, 0
	s_add_i32 s38, s67, s45
	global_load_lds_dwordx4 v[216:217], off
	v_lshl_add_u64 v[216:217], s[36:37], 0, v[154:155]
	s_mov_b32 m0, s38
	s_nop 0
	global_load_lds_dwordx4 v[216:217], off
	v_lshl_add_u64 v[216:217], s[36:37], 0, v[158:159]
	s_add_i32 m0, s38, 0x2000
	s_nop 0
	global_load_lds_dwordx4 v[216:217], off
	v_lshl_add_u64 v[216:217], v[220:221], 0, s[6:7]
	s_mov_b32 m0, s51
	s_nop 0
	global_load_lds_dwordx4 v[216:217], off
	v_lshl_add_u64 v[216:217], v[222:223], 0, s[6:7]
	s_mov_b32 m0, s52
	s_nop 0
	global_load_lds_dwordx4 v[216:217], off
	s_waitcnt vmcnt(8)
	s_waitcnt lgkmcnt(0)
	s_barrier
	s_setprio 1
	s_waitcnt lgkmcnt(0)
	v_mfma_f32_16x16x32_bf16 v[60:63], v[128:131], v[176:179], v[60:63]
	v_mfma_f32_16x16x32_bf16 v[56:59], v[136:139], v[176:179], v[56:59]
	v_mfma_f32_16x16x32_bf16 v[44:47], v[128:131], v[192:195], v[44:47]
	v_mfma_f32_16x16x32_bf16 v[40:43], v[136:139], v[192:195], v[40:43]
	v_mfma_f32_16x16x32_bf16 v[28:31], v[128:131], v[200:203], v[28:31]
	v_mfma_f32_16x16x32_bf16 v[24:27], v[136:139], v[200:203], v[24:27]
	v_mfma_f32_16x16x32_bf16 v[12:15], v[128:131], v[208:211], v[12:15]
	v_mfma_f32_16x16x32_bf16 v[8:11], v[136:139], v[208:211], v[8:11]
	v_mfma_f32_16x16x32_bf16 v[60:63], v[132:135], v[180:183], v[60:63]
	v_mfma_f32_16x16x32_bf16 v[56:59], v[140:143], v[180:183], v[56:59]
	v_mfma_f32_16x16x32_bf16 v[44:47], v[132:135], v[196:199], v[44:47]
	v_mfma_f32_16x16x32_bf16 v[40:43], v[140:143], v[196:199], v[40:43]
	v_mfma_f32_16x16x32_bf16 v[28:31], v[132:135], v[204:207], v[28:31]
	v_mfma_f32_16x16x32_bf16 v[24:27], v[140:143], v[204:207], v[24:27]
	v_mfma_f32_16x16x32_bf16 v[12:15], v[132:135], v[212:215], v[12:15]
	v_mfma_f32_16x16x32_bf16 v[8:11], v[140:143], v[212:215], v[8:11]
	v_mfma_f32_16x16x32_bf16 v[52:55], v[144:147], v[176:179], v[52:55]
	v_mfma_f32_16x16x32_bf16 v[48:51], v[168:171], v[176:179], v[48:51]
	v_mfma_f32_16x16x32_bf16 v[36:39], v[144:147], v[192:195], v[36:39]
	v_mfma_f32_16x16x32_bf16 v[32:35], v[168:171], v[192:195], v[32:35]
	v_mfma_f32_16x16x32_bf16 v[20:23], v[144:147], v[200:203], v[20:23]
	v_mfma_f32_16x16x32_bf16 v[16:19], v[168:171], v[200:203], v[16:19]
	v_mfma_f32_16x16x32_bf16 v[4:7], v[144:147], v[208:211], v[4:7]
	v_mfma_f32_16x16x32_bf16 v[0:3], v[168:171], v[208:211], v[0:3]
	v_mfma_f32_16x16x32_bf16 v[52:55], v[148:151], v[180:183], v[52:55]
	v_mfma_f32_16x16x32_bf16 v[48:51], v[172:175], v[180:183], v[48:51]
	v_mfma_f32_16x16x32_bf16 v[36:39], v[148:151], v[196:199], v[36:39]
	v_mfma_f32_16x16x32_bf16 v[32:35], v[172:175], v[196:199], v[32:35]
	v_mfma_f32_16x16x32_bf16 v[20:23], v[148:151], v[204:207], v[20:23]
	v_mfma_f32_16x16x32_bf16 v[16:19], v[172:175], v[204:207], v[16:19]
	v_mfma_f32_16x16x32_bf16 v[4:7], v[148:151], v[212:215], v[4:7]
	v_mfma_f32_16x16x32_bf16 v[0:3], v[172:175], v[212:215], v[0:3]
	s_setprio 0
	s_barrier
	s_add_i32 s65, s65, 2
	s_add_u32 s24, s24, 0x100
	s_addc_u32 s25, s25, 0
	s_add_u32 s63, s63, 0x100
	s_addc_u32 s64, s64, 0
	s_cmp_gt_u32 s65, 13
	s_cbranch_scc0 .LBB0_1530
	v_lshl_add_u32 v168, s60, 8, v184
	v_lshl_or_b32 v128, s8, 8, v186
	v_ashrrev_i32_e32 v169, 31, v168
	v_ashrrev_i32_e32 v129, 31, v128
	v_lshlrev_b64 v[130:131], 11, v[168:169]
	v_lshl_add_u64 v[130:131], s[34:35], 0, v[130:131]
	v_lshlrev_b64 v[170:171], 1, v[128:129]
	v_lshl_add_u64 v[200:201], v[130:131], 0, v[170:171]
	global_load_dwordx4 v[192:195], v[200:201], off
	global_load_dwordx4 v[196:199], v[200:201], off offset:256
	v_or_b32_e32 v180, 16, v168
	v_or_b32_e32 v176, 32, v168
	v_or_b32_e32 v172, 48, v168
	v_ashrrev_i32_e32 v181, 31, v180
	v_ashrrev_i32_e32 v177, 31, v176
	v_ashrrev_i32_e32 v173, 31, v172
	v_lshlrev_b64 v[128:129], 11, v[180:181]
	v_lshlrev_b64 v[130:131], 11, v[176:177]
	v_lshlrev_b64 v[132:133], 11, v[172:173]
	v_lshl_add_u64 v[128:129], s[34:35], 0, v[128:129]
	v_lshl_add_u64 v[130:131], s[34:35], 0, v[130:131]
	v_lshl_add_u64 v[132:133], s[34:35], 0, v[132:133]
	v_lshl_add_u64 v[182:183], v[128:129], 0, v[170:171]
	v_lshl_add_u64 v[178:179], v[130:131], 0, v[170:171]
	v_lshl_add_u64 v[174:175], v[132:133], 0, v[170:171]
	global_load_dwordx4 v[148:151], v[182:183], off
	global_load_dwordx4 v[144:147], v[182:183], off offset:256
	global_load_dwordx4 v[140:143], v[178:179], off
	global_load_dwordx4 v[136:139], v[178:179], off offset:256
	global_load_dwordx4 v[132:135], v[174:175], off
	global_load_dwordx4 v[128:131], v[174:175], off offset:256
	v_and_b32_e32 v202, 64, v190
	v_xor_b32_e32 v191, 16, v190
	v_add_u32_e32 v202, 64, v202
	v_xor_b32_e32 v203, 32, v190
	v_cmp_lt_i32_e32 vcc, v191, v202
	s_lshl_b32 s24, s8, 2
	s_ashr_i32 s25, s24, 31
	v_cndmask_b32_e32 v191, v190, v191, vcc
	v_cmp_lt_i32_e32 vcc, v203, v202
	v_lshlrev_b32_e32 v191, 2, v191
	s_waitcnt vmcnt(0)
	v_lshlrev_b32_e32 v202, 16, v192
	v_cndmask_b32_e32 v210, v190, v203, vcc
	v_and_b32_e32 v203, 0xffff0000, v192
	v_lshlrev_b32_e32 v192, 16, v193
	v_and_b32_e32 v193, 0xffff0000, v193
	v_lshlrev_b32_e32 v204, 16, v194
	v_and_b32_e32 v205, 0xffff0000, v194
	v_lshlrev_b32_e32 v194, 16, v195
	v_and_b32_e32 v195, 0xffff0000, v195
	v_lshlrev_b32_e32 v206, 16, v196
	v_and_b32_e32 v207, 0xffff0000, v196
	v_lshlrev_b32_e32 v196, 16, v197
	v_and_b32_e32 v197, 0xffff0000, v197
	v_lshlrev_b32_e32 v208, 16, v198
	v_and_b32_e32 v209, 0xffff0000, v198
	v_lshlrev_b32_e32 v198, 16, v199
	v_and_b32_e32 v199, 0xffff0000, v199
	v_pk_add_f32 v[126:127], v[126:127], v[192:193]
	v_pk_add_f32 v[124:125], v[124:125], v[202:203]
	v_pk_add_f32 v[122:123], v[122:123], v[194:195]
	v_pk_add_f32 v[120:121], v[120:121], v[204:205]
	v_pk_add_f32 v[118:119], v[118:119], v[196:197]
	v_pk_add_f32 v[116:117], v[116:117], v[206:207]
	v_pk_add_f32 v[192:193], v[114:115], v[198:199]
	v_pk_add_f32 v[194:195], v[112:113], v[208:209]
	v_cvt_pk_bf16_f32 v112, v124, v125
	v_cvt_pk_bf16_f32 v113, v126, v127
	v_mul_f32_e32 v114, v125, v125
	v_mul_f32_e32 v115, v127, v127
	v_mul_f32_e32 v125, v121, v121
	v_mul_f32_e32 v127, v123, v123
	v_mul_f32_e32 v196, v117, v117
	v_mul_f32_e32 v197, v119, v119
	v_mul_f32_e32 v198, v195, v195
	v_mul_f32_e32 v199, v193, v193
	v_fmac_f32_e32 v114, v124, v124
	v_fmac_f32_e32 v115, v126, v126
	v_fmac_f32_e32 v125, v120, v120
	v_fmac_f32_e32 v127, v122, v122
	v_fmac_f32_e32 v196, v116, v116
	v_fmac_f32_e32 v197, v118, v118
	v_fmac_f32_e32 v198, v194, v194
	v_fmac_f32_e32 v199, v192, v192
	v_add_f32_e32 v114, v114, v115
	v_add_f32_e32 v115, v125, v127
	v_add_f32_e32 v124, v196, v197
	v_add_f32_e32 v125, v198, v199
	v_add_f32_e32 v114, v114, v115
	v_add_f32_e32 v115, v124, v125
	v_add_f32_e32 v124, v114, v115
	ds_bpermute_b32 v125, v191, v124
	v_cvt_pk_bf16_f32 v114, v120, v121
	v_cvt_pk_bf16_f32 v115, v122, v123
	global_store_dwordx4 v[200:201], v[112:115], off
	v_cvt_pk_bf16_f32 v116, v116, v117
	v_cvt_pk_bf16_f32 v117, v118, v119
	s_waitcnt lgkmcnt(0)
	v_add_f32_e32 v113, v124, v125
	v_lshlrev_b32_e32 v112, 2, v210
	ds_bpermute_b32 v114, v112, v113
	v_cvt_pk_bf16_f32 v118, v194, v195
	v_cvt_pk_bf16_f32 v119, v192, v193
	global_store_dwordx4 v[200:201], v[116:119], off offset:256
	s_and_saveexec_b64 s[36:37], s[0:1]
	s_cbranch_execz .LBB0_1533
	s_waitcnt lgkmcnt(0)
	v_add_f32_e32 v113, v113, v114
	v_lshlrev_b64 v[114:115], 6, v[168:169]
	v_lshl_add_u64 v[114:115], s[74:75], 0, v[114:115]
	v_lshl_add_u64 v[114:115], s[24:25], 2, v[114:115]
	s_lshl_b32 s8, s50, 2
	v_lshl_add_u64 v[114:115], v[114:115], 0, s[8:9]
	global_store_dword v[114:115], v113, off

.LBB0_1658:
	ds_read_b128 v[96:99], v169
	ds_read_b128 v[100:103], v169 offset:1024
	ds_read_b128 v[104:107], v169 offset:2048
	ds_read_b128 v[108:111], v169 offset:3072
	ds_read_b128 v[112:115], v170
	ds_read_b128 v[116:119], v170 offset:1024
	ds_read_b128 v[120:123], v170 offset:2048
	ds_read_b128 v[124:127], v170 offset:3072
	s_add_u32 s54, s50, 0xfff80080
	s_addc_u32 s55, s51, -1
	s_cmp_eq_u32 s58, 12
	s_cselect_b32 s89, s3, s57
	s_cselect_b32 s88, s5, s56
	s_cselect_b32 s55, s39, s55
	s_cselect_b32 s54, s43, s54
	v_lshl_add_u64 v[164:165], s[50:51], 0, v[138:139]
	s_add_i32 m0, s53, 0xc000
	ds_read_b128 v[146:149], v171
	ds_read_b128 v[150:153], v171 offset:1024
	ds_read_b128 v[154:157], v171 offset:2048
	ds_read_b128 v[158:161], v171 offset:3072
	ds_read_b128 v[174:177], v171 offset:4096
	ds_read_b128 v[178:181], v171 offset:5120
	ds_read_b128 v[182:185], v171 offset:6144
	ds_read_b128 v[186:189], v171 offset:7168
	global_load_lds_dwordx4 v[164:165], off
	v_lshl_add_u64 v[164:165], s[50:51], 0, v[140:141]
	s_add_i32 m0, s53, 0xe000
	s_nop 0
	global_load_lds_dwordx4 v[164:165], off
	s_waitcnt vmcnt(8)
	s_waitcnt lgkmcnt(0)
	s_barrier
	s_setprio 1
	s_waitcnt lgkmcnt(0)
	v_mfma_f32_16x16x32_bf16 v[92:95], v[96:99], v[146:149], v[92:95]
	v_mfma_f32_16x16x32_bf16 v[88:91], v[104:107], v[146:149], v[88:91]
	v_mfma_f32_16x16x32_bf16 v[84:87], v[96:99], v[154:157], v[84:87]
	v_mfma_f32_16x16x32_bf16 v[80:83], v[104:107], v[154:157], v[80:83]
	v_mfma_f32_16x16x32_bf16 v[68:71], v[96:99], v[174:177], v[68:71]
	v_mfma_f32_16x16x32_bf16 v[64:67], v[104:107], v[174:177], v[64:67]
	v_mfma_f32_16x16x32_bf16 v[52:55], v[96:99], v[182:185], v[52:55]
	v_mfma_f32_16x16x32_bf16 v[48:51], v[104:107], v[182:185], v[48:51]
	v_mfma_f32_16x16x32_bf16 v[92:95], v[100:103], v[150:153], v[92:95]
	v_mfma_f32_16x16x32_bf16 v[88:91], v[108:111], v[150:153], v[88:91]
	v_mfma_f32_16x16x32_bf16 v[84:87], v[100:103], v[158:161], v[84:87]
	v_mfma_f32_16x16x32_bf16 v[80:83], v[108:111], v[158:161], v[80:83]
	v_mfma_f32_16x16x32_bf16 v[68:71], v[100:103], v[178:181], v[68:71]
	v_mfma_f32_16x16x32_bf16 v[64:67], v[108:111], v[178:181], v[64:67]
	v_mfma_f32_16x16x32_bf16 v[52:55], v[100:103], v[186:189], v[52:55]
	v_mfma_f32_16x16x32_bf16 v[48:51], v[108:111], v[186:189], v[48:51]
	v_mfma_f32_16x16x32_bf16 v[76:79], v[112:115], v[146:149], v[76:79]
	v_mfma_f32_16x16x32_bf16 v[72:75], v[120:123], v[146:149], v[72:75]
	v_mfma_f32_16x16x32_bf16 v[60:63], v[112:115], v[154:157], v[60:63]
	v_mfma_f32_16x16x32_bf16 v[56:59], v[120:123], v[154:157], v[56:59]
	v_mfma_f32_16x16x32_bf16 v[44:47], v[112:115], v[174:177], v[44:47]
	v_mfma_f32_16x16x32_bf16 v[40:43], v[120:123], v[174:177], v[40:43]
	v_mfma_f32_16x16x32_bf16 v[36:39], v[112:115], v[182:185], v[36:39]
	v_mfma_f32_16x16x32_bf16 v[32:35], v[120:123], v[182:185], v[32:35]
	v_mfma_f32_16x16x32_bf16 v[76:79], v[116:119], v[150:153], v[76:79]
	v_mfma_f32_16x16x32_bf16 v[72:75], v[124:127], v[150:153], v[72:75]
	v_mfma_f32_16x16x32_bf16 v[60:63], v[116:119], v[158:161], v[60:63]
	v_mfma_f32_16x16x32_bf16 v[56:59], v[124:127], v[158:161], v[56:59]
	v_mfma_f32_16x16x32_bf16 v[44:47], v[116:119], v[178:181], v[44:47]
	v_mfma_f32_16x16x32_bf16 v[40:43], v[124:127], v[178:181], v[40:43]
	v_mfma_f32_16x16x32_bf16 v[36:39], v[116:119], v[186:189], v[36:39]
	v_mfma_f32_16x16x32_bf16 v[32:35], v[124:127], v[186:189], v[32:35]
	s_setprio 0
	s_barrier
	s_add_i32 s59, s73, s25
	v_lshl_add_u64 v[164:165], s[54:55], 0, v[130:131]
	s_mov_b32 m0, s59
	ds_read_b128 v[96:99], v172 offset:16384
	ds_read_b128 v[100:103], v172 offset:17408
	ds_read_b128 v[104:107], v172 offset:18432
	ds_read_b128 v[108:111], v172 offset:19456
	global_load_lds_dwordx4 v[164:165], off
	s_add_i32 m0, s59, 0x2000
	s_add_u32 s90, s54, 0x40000
	v_lshl_add_u64 v[190:191], s[54:55], 0, v[134:135]
	s_addc_u32 s91, s55, 0
	s_add_i32 s59, s76, s25
	global_load_lds_dwordx4 v[190:191], off
	v_lshl_add_u64 v[112:113], s[90:91], 0, v[130:131]
	s_mov_b32 m0, s59
	v_lshl_add_u64 v[192:193], s[88:89], 0, v[128:129]
	global_load_lds_dwordx4 v[112:113], off
	v_lshl_add_u64 v[112:113], s[90:91], 0, v[134:135]
	s_add_i32 m0, s59, 0x2000
	v_lshl_add_u64 v[194:195], s[88:89], 0, v[132:133]
	global_load_lds_dwordx4 v[112:113], off
	s_mov_b32 m0, s53
	s_nop 0
	global_load_lds_dwordx4 v[192:193], off
	s_mov_b32 m0, s60
	s_nop 0
	global_load_lds_dwordx4 v[194:195], off
	s_waitcnt vmcnt(8)
	s_waitcnt lgkmcnt(0)
	s_barrier
	s_setprio 1
	s_waitcnt lgkmcnt(0)
	v_mfma_f32_16x16x32_bf16 v[28:31], v[96:99], v[146:149], v[28:31]
	v_mfma_f32_16x16x32_bf16 v[24:27], v[104:107], v[146:149], v[24:27]
	v_mfma_f32_16x16x32_bf16 v[20:23], v[96:99], v[154:157], v[20:23]
	v_mfma_f32_16x16x32_bf16 v[16:19], v[104:107], v[154:157], v[16:19]
	v_mfma_f32_16x16x32_bf16 v[12:15], v[96:99], v[174:177], v[12:15]
	v_mfma_f32_16x16x32_bf16 v[8:11], v[104:107], v[174:177], v[8:11]
	v_mfma_f32_16x16x32_bf16 v[4:7], v[96:99], v[182:185], v[4:7]
	v_mfma_f32_16x16x32_bf16 v[0:3], v[104:107], v[182:185], v[0:3]
	v_mfma_f32_16x16x32_bf16 v[28:31], v[100:103], v[150:153], v[28:31]
	v_mfma_f32_16x16x32_bf16 v[24:27], v[108:111], v[150:153], v[24:27]
	v_mfma_f32_16x16x32_bf16 v[20:23], v[100:103], v[158:161], v[20:23]
	v_mfma_f32_16x16x32_bf16 v[16:19], v[108:111], v[158:161], v[16:19]
	v_mfma_f32_16x16x32_bf16 v[12:15], v[100:103], v[178:181], v[12:15]
	v_mfma_f32_16x16x32_bf16 v[8:11], v[108:111], v[178:181], v[8:11]
	v_mfma_f32_16x16x32_bf16 v[4:7], v[100:103], v[186:189], v[4:7]
	v_mfma_f32_16x16x32_bf16 v[0:3], v[108:111], v[186:189], v[0:3]
	s_setprio 0
	s_barrier
	s_add_i32 s59, 0, 0x18000
	s_add_i32 s87, 0, 0x1c000
	v_add_u32_e32 v108, s59, v167
	v_add_u32_e32 v124, s87, v167
	ds_read_b128 v[96:99], v108
	ds_read_b128 v[100:103], v108 offset:1024
	ds_read_b128 v[104:107], v108 offset:2048
	ds_read_b128 v[108:111], v108 offset:3072
	ds_read_b128 v[112:115], v124
	ds_read_b128 v[116:119], v124 offset:1024
	ds_read_b128 v[120:123], v124 offset:2048
	ds_read_b128 v[124:127], v124 offset:3072
	s_add_u32 s88, s54, 0x80000
	s_addc_u32 s89, s55, 0
	s_mov_b32 m0, s61
	v_lshl_add_u64 v[196:197], s[88:89], 0, v[130:131]
	ds_read_b128 v[146:149], v171 offset:32768
	ds_read_b128 v[150:153], v171 offset:33792
	ds_read_b128 v[154:157], v171 offset:34816
	ds_read_b128 v[158:161], v171 offset:35840
	ds_read_b128 v[174:177], v171 offset:36864
	ds_read_b128 v[178:181], v171 offset:37888
	ds_read_b128 v[182:185], v171 offset:38912
	ds_read_b128 v[186:189], v171 offset:39936
	global_load_lds_dwordx4 v[196:197], off
	v_lshl_add_u64 v[196:197], s[88:89], 0, v[134:135]
	s_mov_b32 m0, s62
	s_nop 0
	global_load_lds_dwordx4 v[196:197], off
	s_waitcnt vmcnt(8)
	s_waitcnt lgkmcnt(0)
	s_barrier
	s_setprio 1
	s_waitcnt lgkmcnt(0)
	v_mfma_f32_16x16x32_bf16 v[92:95], v[96:99], v[146:149], v[92:95]
	v_mfma_f32_16x16x32_bf16 v[88:91], v[104:107], v[146:149], v[88:91]
	v_mfma_f32_16x16x32_bf16 v[84:87], v[96:99], v[154:157], v[84:87]
	v_mfma_f32_16x16x32_bf16 v[80:83], v[104:107], v[154:157], v[80:83]
	v_mfma_f32_16x16x32_bf16 v[68:71], v[96:99], v[174:177], v[68:71]
	v_mfma_f32_16x16x32_bf16 v[64:67], v[104:107], v[174:177], v[64:67]
	v_mfma_f32_16x16x32_bf16 v[52:55], v[96:99], v[182:185], v[52:55]
	v_mfma_f32_16x16x32_bf16 v[48:51], v[104:107], v[182:185], v[48:51]
	v_mfma_f32_16x16x32_bf16 v[92:95], v[100:103], v[150:153], v[92:95]
	v_mfma_f32_16x16x32_bf16 v[88:91], v[108:111], v[150:153], v[88:91]
	v_mfma_f32_16x16x32_bf16 v[84:87], v[100:103], v[158:161], v[84:87]
	v_mfma_f32_16x16x32_bf16 v[80:83], v[108:111], v[158:161], v[80:83]
	v_mfma_f32_16x16x32_bf16 v[68:71], v[100:103], v[178:181], v[68:71]
	v_mfma_f32_16x16x32_bf16 v[64:67], v[108:111], v[178:181], v[64:67]
	v_mfma_f32_16x16x32_bf16 v[52:55], v[100:103], v[186:189], v[52:55]
	v_mfma_f32_16x16x32_bf16 v[48:51], v[108:111], v[186:189], v[48:51]
	v_mfma_f32_16x16x32_bf16 v[76:79], v[112:115], v[146:149], v[76:79]
	v_mfma_f32_16x16x32_bf16 v[72:75], v[120:123], v[146:149], v[72:75]
	v_mfma_f32_16x16x32_bf16 v[60:63], v[112:115], v[154:157], v[60:63]
	v_mfma_f32_16x16x32_bf16 v[56:59], v[120:123], v[154:157], v[56:59]
	v_mfma_f32_16x16x32_bf16 v[44:47], v[112:115], v[174:177], v[44:47]
	v_mfma_f32_16x16x32_bf16 v[40:43], v[120:123], v[174:177], v[40:43]
	v_mfma_f32_16x16x32_bf16 v[36:39], v[112:115], v[182:185], v[36:39]
	v_mfma_f32_16x16x32_bf16 v[32:35], v[120:123], v[182:185], v[32:35]
	v_mfma_f32_16x16x32_bf16 v[76:79], v[116:119], v[150:153], v[76:79]
	v_mfma_f32_16x16x32_bf16 v[72:75], v[124:127], v[150:153], v[72:75]
	v_mfma_f32_16x16x32_bf16 v[60:63], v[116:119], v[158:161], v[60:63]
	v_mfma_f32_16x16x32_bf16 v[56:59], v[124:127], v[158:161], v[56:59]
	v_mfma_f32_16x16x32_bf16 v[44:47], v[116:119], v[178:181], v[44:47]
	v_mfma_f32_16x16x32_bf16 v[40:43], v[124:127], v[178:181], v[40:43]
	v_mfma_f32_16x16x32_bf16 v[36:39], v[116:119], v[186:189], v[36:39]
	v_mfma_f32_16x16x32_bf16 v[32:35], v[124:127], v[186:189], v[32:35]
	s_setprio 0
	s_barrier
	s_add_i32 s59, s59, s25
	v_lshl_add_u64 v[112:113], v[164:165], 0, s[14:15]
	s_mov_b32 m0, s59
	ds_read_b128 v[96:99], v172 offset:49152
	ds_read_b128 v[100:103], v172 offset:50176
	ds_read_b128 v[104:107], v172 offset:51200
	ds_read_b128 v[108:111], v172 offset:52224
	global_load_lds_dwordx4 v[112:113], off
	s_add_i32 m0, s59, 0x2000
	s_add_u32 s54, s54, 0x40080
	v_lshl_add_u64 v[112:113], v[190:191], 0, s[14:15]
	s_addc_u32 s55, s55, 0
	s_add_i32 s59, s87, s25
	global_load_lds_dwordx4 v[112:113], off
	v_lshl_add_u64 v[112:113], s[54:55], 0, v[130:131]
	s_mov_b32 m0, s59
	s_nop 0
	global_load_lds_dwordx4 v[112:113], off
	v_lshl_add_u64 v[112:113], s[54:55], 0, v[134:135]
	s_add_i32 m0, s59, 0x2000
	s_nop 0
	global_load_lds_dwordx4 v[112:113], off
	v_lshl_add_u64 v[112:113], v[192:193], 0, s[14:15]
	s_mov_b32 m0, s63
	s_nop 0
	global_load_lds_dwordx4 v[112:113], off
	v_lshl_add_u64 v[112:113], v[194:195], 0, s[14:15]
	s_mov_b32 m0, s64
	s_nop 0
	global_load_lds_dwordx4 v[112:113], off
	s_waitcnt vmcnt(8)
	s_waitcnt lgkmcnt(0)
	s_barrier
	s_setprio 1
	s_waitcnt lgkmcnt(0)
	v_mfma_f32_16x16x32_bf16 v[28:31], v[96:99], v[146:149], v[28:31]
	v_mfma_f32_16x16x32_bf16 v[24:27], v[104:107], v[146:149], v[24:27]
	v_mfma_f32_16x16x32_bf16 v[20:23], v[96:99], v[154:157], v[20:23]
	v_mfma_f32_16x16x32_bf16 v[16:19], v[104:107], v[154:157], v[16:19]
	v_mfma_f32_16x16x32_bf16 v[12:15], v[96:99], v[174:177], v[12:15]
	v_mfma_f32_16x16x32_bf16 v[8:11], v[104:107], v[174:177], v[8:11]
	v_mfma_f32_16x16x32_bf16 v[4:7], v[96:99], v[182:185], v[4:7]
	v_mfma_f32_16x16x32_bf16 v[0:3], v[104:107], v[182:185], v[0:3]
	v_mfma_f32_16x16x32_bf16 v[28:31], v[100:103], v[150:153], v[28:31]
	v_mfma_f32_16x16x32_bf16 v[24:27], v[108:111], v[150:153], v[24:27]
	v_mfma_f32_16x16x32_bf16 v[20:23], v[100:103], v[158:161], v[20:23]
	v_mfma_f32_16x16x32_bf16 v[16:19], v[108:111], v[158:161], v[16:19]
	v_mfma_f32_16x16x32_bf16 v[12:15], v[100:103], v[178:181], v[12:15]
	v_mfma_f32_16x16x32_bf16 v[8:11], v[108:111], v[178:181], v[8:11]
	v_mfma_f32_16x16x32_bf16 v[4:7], v[100:103], v[186:189], v[4:7]
	v_mfma_f32_16x16x32_bf16 v[0:3], v[108:111], v[186:189], v[0:3]
	s_setprio 0
	s_barrier
	s_add_i32 s58, s58, 2
	s_add_u32 s56, s56, 0x100
	s_addc_u32 s57, s57, 0
	s_add_u32 s50, s50, 0x100
	s_addc_u32 s51, s51, 0
	s_cmp_gt_u32 s58, 13
	s_cbranch_scc0 .LBB0_1658
	s_mov_b64 s[50:51], 0
	s_branch .LBB0_1661

.LBB0_1663:
	ds_read_b128 v[146:149], v169
	ds_read_b128 v[150:153], v169 offset:1024
	ds_read_b128 v[154:157], v169 offset:2048
	ds_read_b128 v[158:161], v169 offset:3072
	ds_read_b128 v[174:177], v170
	ds_read_b128 v[178:181], v170 offset:1024
	ds_read_b128 v[182:185], v170 offset:2048
	ds_read_b128 v[186:189], v170 offset:3072
	s_add_u32 s58, s48, 0xfffc0080
	s_addc_u32 s59, s49, -1
	s_cmp_eq_u32 s89, 12
	s_cselect_b64 s[56:57], -1, 0
	s_and_b64 s[54:55], s[56:57], exec
	s_cselect_b32 s55, s39, s86
	s_cselect_b32 s54, s43, s85
	s_cselect_b32 s59, s3, s59
	s_cselect_b32 s58, s5, s58
	v_lshl_add_u64 v[164:165], s[48:49], 0, v[142:143]
	s_add_i32 m0, s53, 0xc000
	ds_read_b128 v[190:193], v171
	ds_read_b128 v[194:197], v171 offset:1024
	ds_read_b128 v[198:201], v171 offset:2048
	ds_read_b128 v[202:205], v171 offset:3072
	ds_read_b128 v[206:209], v171 offset:4096
	ds_read_b128 v[210:213], v171 offset:5120
	ds_read_b128 v[214:217], v171 offset:6144
	ds_read_b128 v[218:221], v171 offset:7168
	global_load_lds_dwordx4 v[164:165], off
	v_lshl_add_u64 v[164:165], s[48:49], 0, v[132:133]
	s_add_i32 m0, s53, 0xe000
	s_nop 0
	global_load_lds_dwordx4 v[164:165], off
	s_waitcnt vmcnt(8)
	s_waitcnt lgkmcnt(0)
	s_barrier
	s_setprio 1
	s_waitcnt lgkmcnt(0)
	v_mfma_f32_16x16x32_bf16 v[92:95], v[146:149], v[190:193], v[92:95]
	v_mfma_f32_16x16x32_bf16 v[88:91], v[154:157], v[190:193], v[88:91]
	v_mfma_f32_16x16x32_bf16 v[84:87], v[146:149], v[198:201], v[84:87]
	v_mfma_f32_16x16x32_bf16 v[80:83], v[154:157], v[198:201], v[80:83]
	v_mfma_f32_16x16x32_bf16 v[68:71], v[146:149], v[206:209], v[68:71]
	v_mfma_f32_16x16x32_bf16 v[64:67], v[154:157], v[206:209], v[64:67]
	v_mfma_f32_16x16x32_bf16 v[52:55], v[146:149], v[214:217], v[52:55]
	v_mfma_f32_16x16x32_bf16 v[48:51], v[154:157], v[214:217], v[48:51]
	v_mfma_f32_16x16x32_bf16 v[92:95], v[150:153], v[194:197], v[92:95]
	v_mfma_f32_16x16x32_bf16 v[88:91], v[158:161], v[194:197], v[88:91]
	v_mfma_f32_16x16x32_bf16 v[84:87], v[150:153], v[202:205], v[84:87]
	v_mfma_f32_16x16x32_bf16 v[80:83], v[158:161], v[202:205], v[80:83]
	v_mfma_f32_16x16x32_bf16 v[68:71], v[150:153], v[210:213], v[68:71]
	v_mfma_f32_16x16x32_bf16 v[64:67], v[158:161], v[210:213], v[64:67]
	v_mfma_f32_16x16x32_bf16 v[52:55], v[150:153], v[218:221], v[52:55]
	v_mfma_f32_16x16x32_bf16 v[48:51], v[158:161], v[218:221], v[48:51]
	v_mfma_f32_16x16x32_bf16 v[76:79], v[174:177], v[190:193], v[76:79]
	v_mfma_f32_16x16x32_bf16 v[72:75], v[182:185], v[190:193], v[72:75]
	v_mfma_f32_16x16x32_bf16 v[60:63], v[174:177], v[198:201], v[60:63]
	v_mfma_f32_16x16x32_bf16 v[56:59], v[182:185], v[198:201], v[56:59]
	v_mfma_f32_16x16x32_bf16 v[44:47], v[174:177], v[206:209], v[44:47]
	v_mfma_f32_16x16x32_bf16 v[40:43], v[182:185], v[206:209], v[40:43]
	v_mfma_f32_16x16x32_bf16 v[36:39], v[174:177], v[214:217], v[36:39]
	v_mfma_f32_16x16x32_bf16 v[32:35], v[182:185], v[214:217], v[32:35]
	v_mfma_f32_16x16x32_bf16 v[76:79], v[178:181], v[194:197], v[76:79]
	v_mfma_f32_16x16x32_bf16 v[72:75], v[186:189], v[194:197], v[72:75]
	v_mfma_f32_16x16x32_bf16 v[60:63], v[178:181], v[202:205], v[60:63]
	v_mfma_f32_16x16x32_bf16 v[56:59], v[186:189], v[202:205], v[56:59]
	v_mfma_f32_16x16x32_bf16 v[44:47], v[178:181], v[210:213], v[44:47]
	v_mfma_f32_16x16x32_bf16 v[40:43], v[186:189], v[210:213], v[40:43]
	v_mfma_f32_16x16x32_bf16 v[36:39], v[178:181], v[218:221], v[36:39]
	v_mfma_f32_16x16x32_bf16 v[32:35], v[186:189], v[218:221], v[32:35]
	s_setprio 0
	s_barrier
	s_add_i32 s90, s73, s25
	v_lshl_add_u64 v[164:165], s[54:55], 0, v[130:131]
	s_mov_b32 m0, s90
	ds_read_b128 v[190:193], v171 offset:16384
	ds_read_b128 v[194:197], v171 offset:17408
	ds_read_b128 v[198:201], v171 offset:18432
	ds_read_b128 v[202:205], v171 offset:19456
	ds_read_b128 v[206:209], v171 offset:20480
	ds_read_b128 v[210:213], v171 offset:21504
	ds_read_b128 v[214:217], v171 offset:22528
	ds_read_b128 v[218:221], v171 offset:23552
	global_load_lds_dwordx4 v[164:165], off
	s_add_i32 m0, s90, 0x2000
	s_add_u32 s90, s54, 0x40000
	v_lshl_add_u64 v[222:223], s[54:55], 0, v[134:135]
	s_addc_u32 s91, s55, 0
	s_add_i32 s92, s76, s25
	global_load_lds_dwordx4 v[222:223], off
	v_lshl_add_u64 v[224:225], s[90:91], 0, v[130:131]
	s_mov_b32 m0, s92
	v_lshl_add_u64 v[226:227], s[58:59], 0, v[132:133]
	global_load_lds_dwordx4 v[224:225], off
	v_lshl_add_u64 v[224:225], s[90:91], 0, v[134:135]
	s_add_i32 m0, s92, 0x2000
	s_nop 0
	global_load_lds_dwordx4 v[224:225], off
	v_lshl_add_u64 v[224:225], s[58:59], 0, v[128:129]
	s_mov_b32 m0, s53
	s_nop 0
	global_load_lds_dwordx4 v[224:225], off
	s_mov_b32 m0, s60
	s_nop 0
	global_load_lds_dwordx4 v[226:227], off
	s_waitcnt vmcnt(8)
	s_waitcnt lgkmcnt(0)
	s_barrier
	s_setprio 1
	s_waitcnt lgkmcnt(0)
	v_mfma_f32_16x16x32_bf16 v[28:31], v[146:149], v[190:193], v[28:31]
	v_mfma_f32_16x16x32_bf16 v[24:27], v[154:157], v[190:193], v[24:27]
	v_mfma_f32_16x16x32_bf16 v[20:23], v[146:149], v[198:201], v[20:23]
	v_mfma_f32_16x16x32_bf16 v[16:19], v[154:157], v[198:201], v[16:19]
	v_mfma_f32_16x16x32_bf16 v[12:15], v[146:149], v[206:209], v[12:15]
	v_mfma_f32_16x16x32_bf16 v[8:11], v[154:157], v[206:209], v[8:11]
	v_mfma_f32_16x16x32_bf16 v[4:7], v[146:149], v[214:217], v[4:7]
	v_mfma_f32_16x16x32_bf16 v[0:3], v[154:157], v[214:217], v[0:3]
	v_mfma_f32_16x16x32_bf16 v[28:31], v[150:153], v[194:197], v[28:31]
	v_mfma_f32_16x16x32_bf16 v[24:27], v[158:161], v[194:197], v[24:27]
	v_mfma_f32_16x16x32_bf16 v[20:23], v[150:153], v[202:205], v[20:23]
	v_mfma_f32_16x16x32_bf16 v[16:19], v[158:161], v[202:205], v[16:19]
	v_mfma_f32_16x16x32_bf16 v[12:15], v[150:153], v[210:213], v[12:15]
	v_mfma_f32_16x16x32_bf16 v[8:11], v[158:161], v[210:213], v[8:11]
	v_mfma_f32_16x16x32_bf16 v[4:7], v[150:153], v[218:221], v[4:7]
	v_mfma_f32_16x16x32_bf16 v[0:3], v[158:161], v[218:221], v[0:3]
	v_mfma_f32_16x16x32_bf16 v[124:127], v[174:177], v[190:193], v[124:127]
	v_mfma_f32_16x16x32_bf16 v[120:123], v[182:185], v[190:193], v[120:123]
	v_mfma_f32_16x16x32_bf16 v[116:119], v[174:177], v[198:201], v[116:119]
	v_mfma_f32_16x16x32_bf16 v[112:115], v[182:185], v[198:201], v[112:115]
	v_mfma_f32_16x16x32_bf16 v[108:111], v[174:177], v[206:209], v[108:111]
	v_mfma_f32_16x16x32_bf16 v[104:107], v[182:185], v[206:209], v[104:107]
	v_mfma_f32_16x16x32_bf16 v[100:103], v[174:177], v[214:217], v[100:103]
	v_mfma_f32_16x16x32_bf16 v[96:99], v[182:185], v[214:217], v[96:99]
	v_mfma_f32_16x16x32_bf16 v[124:127], v[178:181], v[194:197], v[124:127]
	v_mfma_f32_16x16x32_bf16 v[120:123], v[186:189], v[194:197], v[120:123]
	v_mfma_f32_16x16x32_bf16 v[116:119], v[178:181], v[202:205], v[116:119]
	v_mfma_f32_16x16x32_bf16 v[112:115], v[186:189], v[202:205], v[112:115]
	v_mfma_f32_16x16x32_bf16 v[108:111], v[178:181], v[210:213], v[108:111]
	v_mfma_f32_16x16x32_bf16 v[104:107], v[186:189], v[210:213], v[104:107]
	v_mfma_f32_16x16x32_bf16 v[100:103], v[178:181], v[218:221], v[100:103]
	v_mfma_f32_16x16x32_bf16 v[96:99], v[186:189], v[218:221], v[96:99]
	s_setprio 0
	s_barrier
	s_add_i32 s90, 0, 0x18000
	s_add_i32 s91, 0, 0x1c000
	v_add_u32_e32 v158, s90, v167
	v_add_u32_e32 v162, s91, v167
	ds_read_b128 v[146:149], v158
	ds_read_b128 v[150:153], v158 offset:1024
	ds_read_b128 v[154:157], v158 offset:2048
	ds_read_b128 v[158:161], v158 offset:3072
	ds_read_b128 v[174:177], v162
	ds_read_b128 v[178:181], v162 offset:1024
	ds_read_b128 v[182:185], v162 offset:2048
	ds_read_b128 v[186:189], v162 offset:3072
	s_and_b64 s[56:57], s[40:41], s[56:57]
	s_and_b64 vcc, s[56:57], s[50:51]
	s_add_u32 s58, s58, 0x40000
	s_addc_u32 s59, s59, 0
	s_and_b64 s[56:57], vcc, exec
	s_mov_b32 m0, s61
	v_cndmask_b32_e32 v162, v128, v130, vcc
	s_cselect_b32 s57, s88, s59
	s_cselect_b32 s56, s87, s58
	ds_read_b128 v[190:193], v171 offset:32768
	ds_read_b128 v[194:197], v171 offset:33792
	ds_read_b128 v[198:201], v171 offset:34816
	ds_read_b128 v[202:205], v171 offset:35840
	ds_read_b128 v[206:209], v171 offset:36864
	ds_read_b128 v[210:213], v171 offset:37888
	ds_read_b128 v[214:217], v171 offset:38912
	ds_read_b128 v[218:221], v171 offset:39936
	v_cndmask_b32_e32 v166, v132, v134, vcc
	global_load_lds_dwordx4 v162, s[56:57]
	s_mov_b32 m0, s62
	s_nop 0
	global_load_lds_dwordx4 v166, s[56:57]
	s_waitcnt vmcnt(8)
	s_waitcnt lgkmcnt(0)
	s_barrier
	s_setprio 1
	s_waitcnt lgkmcnt(0)
	v_mfma_f32_16x16x32_bf16 v[92:95], v[146:149], v[190:193], v[92:95]
	v_mfma_f32_16x16x32_bf16 v[88:91], v[154:157], v[190:193], v[88:91]
	v_mfma_f32_16x16x32_bf16 v[84:87], v[146:149], v[198:201], v[84:87]
	v_mfma_f32_16x16x32_bf16 v[80:83], v[154:157], v[198:201], v[80:83]
	v_mfma_f32_16x16x32_bf16 v[68:71], v[146:149], v[206:209], v[68:71]
	v_mfma_f32_16x16x32_bf16 v[64:67], v[154:157], v[206:209], v[64:67]
	v_mfma_f32_16x16x32_bf16 v[52:55], v[146:149], v[214:217], v[52:55]
	v_mfma_f32_16x16x32_bf16 v[48:51], v[154:157], v[214:217], v[48:51]
	v_mfma_f32_16x16x32_bf16 v[92:95], v[150:153], v[194:197], v[92:95]
	v_mfma_f32_16x16x32_bf16 v[88:91], v[158:161], v[194:197], v[88:91]
	v_mfma_f32_16x16x32_bf16 v[84:87], v[150:153], v[202:205], v[84:87]
	v_mfma_f32_16x16x32_bf16 v[80:83], v[158:161], v[202:205], v[80:83]
	v_mfma_f32_16x16x32_bf16 v[68:71], v[150:153], v[210:213], v[68:71]
	v_mfma_f32_16x16x32_bf16 v[64:67], v[158:161], v[210:213], v[64:67]
	v_mfma_f32_16x16x32_bf16 v[52:55], v[150:153], v[218:221], v[52:55]
	v_mfma_f32_16x16x32_bf16 v[48:51], v[158:161], v[218:221], v[48:51]
	v_mfma_f32_16x16x32_bf16 v[76:79], v[174:177], v[190:193], v[76:79]
	v_mfma_f32_16x16x32_bf16 v[72:75], v[182:185], v[190:193], v[72:75]
	v_mfma_f32_16x16x32_bf16 v[60:63], v[174:177], v[198:201], v[60:63]
	v_mfma_f32_16x16x32_bf16 v[56:59], v[182:185], v[198:201], v[56:59]
	v_mfma_f32_16x16x32_bf16 v[44:47], v[174:177], v[206:209], v[44:47]
	v_mfma_f32_16x16x32_bf16 v[40:43], v[182:185], v[206:209], v[40:43]
	v_mfma_f32_16x16x32_bf16 v[36:39], v[174:177], v[214:217], v[36:39]
	v_mfma_f32_16x16x32_bf16 v[32:35], v[182:185], v[214:217], v[32:35]
	v_mfma_f32_16x16x32_bf16 v[76:79], v[178:181], v[194:197], v[76:79]
	v_mfma_f32_16x16x32_bf16 v[72:75], v[186:189], v[194:197], v[72:75]
	v_mfma_f32_16x16x32_bf16 v[60:63], v[178:181], v[202:205], v[60:63]
	v_mfma_f32_16x16x32_bf16 v[56:59], v[186:189], v[202:205], v[56:59]
	v_mfma_f32_16x16x32_bf16 v[44:47], v[178:181], v[210:213], v[44:47]
	v_mfma_f32_16x16x32_bf16 v[40:43], v[186:189], v[210:213], v[40:43]
	v_mfma_f32_16x16x32_bf16 v[36:39], v[178:181], v[218:221], v[36:39]
	v_mfma_f32_16x16x32_bf16 v[32:35], v[186:189], v[218:221], v[32:35]
	s_setprio 0
	s_barrier
	s_add_i32 s56, s90, s25
	v_lshl_add_u64 v[164:165], v[164:165], 0, s[14:15]
	s_mov_b32 m0, s56
	ds_read_b128 v[190:193], v171 offset:49152
	ds_read_b128 v[194:197], v171 offset:50176
	ds_read_b128 v[198:201], v171 offset:51200
	ds_read_b128 v[202:205], v171 offset:52224
	ds_read_b128 v[206:209], v171 offset:53248
	ds_read_b128 v[210:213], v171 offset:54272
	ds_read_b128 v[214:217], v171 offset:55296
	ds_read_b128 v[218:221], v171 offset:56320
	global_load_lds_dwordx4 v[164:165], off
	s_add_i32 m0, s56, 0x2000
	s_add_u32 s54, s54, 0x40080
	v_lshl_add_u64 v[164:165], v[222:223], 0, s[14:15]
	s_addc_u32 s55, s55, 0
	s_add_i32 s56, s91, s25
	global_load_lds_dwordx4 v[164:165], off
	v_lshl_add_u64 v[164:165], s[54:55], 0, v[130:131]
	s_mov_b32 m0, s56
	s_nop 0
	global_load_lds_dwordx4 v[164:165], off
	v_lshl_add_u64 v[164:165], s[54:55], 0, v[134:135]
	s_add_i32 m0, s56, 0x2000
	s_nop 0
	global_load_lds_dwordx4 v[164:165], off
	v_lshl_add_u64 v[164:165], v[224:225], 0, s[14:15]
	s_mov_b32 m0, s63
	s_nop 0
	global_load_lds_dwordx4 v[164:165], off
	v_lshl_add_u64 v[164:165], v[226:227], 0, s[14:15]
	s_mov_b32 m0, s64
	s_nop 0
	global_load_lds_dwordx4 v[164:165], off
	s_waitcnt vmcnt(8)
	s_waitcnt lgkmcnt(0)
	s_barrier
	s_setprio 1
	s_waitcnt lgkmcnt(0)
	v_mfma_f32_16x16x32_bf16 v[28:31], v[146:149], v[190:193], v[28:31]
	v_mfma_f32_16x16x32_bf16 v[24:27], v[154:157], v[190:193], v[24:27]
	v_mfma_f32_16x16x32_bf16 v[20:23], v[146:149], v[198:201], v[20:23]
	v_mfma_f32_16x16x32_bf16 v[16:19], v[154:157], v[198:201], v[16:19]
	v_mfma_f32_16x16x32_bf16 v[12:15], v[146:149], v[206:209], v[12:15]
	v_mfma_f32_16x16x32_bf16 v[8:11], v[154:157], v[206:209], v[8:11]
	v_mfma_f32_16x16x32_bf16 v[4:7], v[146:149], v[214:217], v[4:7]
	v_mfma_f32_16x16x32_bf16 v[0:3], v[154:157], v[214:217], v[0:3]
	v_mfma_f32_16x16x32_bf16 v[28:31], v[150:153], v[194:197], v[28:31]
	v_mfma_f32_16x16x32_bf16 v[24:27], v[158:161], v[194:197], v[24:27]
	v_mfma_f32_16x16x32_bf16 v[20:23], v[150:153], v[202:205], v[20:23]
	v_mfma_f32_16x16x32_bf16 v[16:19], v[158:161], v[202:205], v[16:19]
	v_mfma_f32_16x16x32_bf16 v[12:15], v[150:153], v[210:213], v[12:15]
	v_mfma_f32_16x16x32_bf16 v[8:11], v[158:161], v[210:213], v[8:11]
	v_mfma_f32_16x16x32_bf16 v[4:7], v[150:153], v[218:221], v[4:7]
	v_mfma_f32_16x16x32_bf16 v[0:3], v[158:161], v[218:221], v[0:3]
	v_mfma_f32_16x16x32_bf16 v[124:127], v[174:177], v[190:193], v[124:127]
	v_mfma_f32_16x16x32_bf16 v[120:123], v[182:185], v[190:193], v[120:123]
	v_mfma_f32_16x16x32_bf16 v[116:119], v[174:177], v[198:201], v[116:119]
	v_mfma_f32_16x16x32_bf16 v[112:115], v[182:185], v[198:201], v[112:115]
	v_mfma_f32_16x16x32_bf16 v[108:111], v[174:177], v[206:209], v[108:111]
	v_mfma_f32_16x16x32_bf16 v[104:107], v[182:185], v[206:209], v[104:107]
	v_mfma_f32_16x16x32_bf16 v[100:103], v[174:177], v[214:217], v[100:103]
	v_mfma_f32_16x16x32_bf16 v[96:99], v[182:185], v[214:217], v[96:99]
	v_mfma_f32_16x16x32_bf16 v[124:127], v[178:181], v[194:197], v[124:127]
	v_mfma_f32_16x16x32_bf16 v[120:123], v[186:189], v[194:197], v[120:123]
	v_mfma_f32_16x16x32_bf16 v[116:119], v[178:181], v[202:205], v[116:119]
	v_mfma_f32_16x16x32_bf16 v[112:115], v[186:189], v[202:205], v[112:115]
	v_mfma_f32_16x16x32_bf16 v[108:111], v[178:181], v[210:213], v[108:111]
	v_mfma_f32_16x16x32_bf16 v[104:107], v[186:189], v[210:213], v[104:107]
	v_mfma_f32_16x16x32_bf16 v[100:103], v[178:181], v[218:221], v[100:103]
	v_mfma_f32_16x16x32_bf16 v[96:99], v[186:189], v[218:221], v[96:99]
	s_setprio 0
	s_barrier
	s_add_i32 s89, s89, 2
	s_add_u32 s48, s48, 0x100
	s_addc_u32 s49, s49, 0
	s_add_u32 s85, s85, 0x100
	s_addc_u32 s86, s86, 0
	s_cmp_gt_u32 s89, 13
	s_cbranch_scc0 .LBB0_1663

.LBB0_1749:
	ds_read_b128 v[2:5], v243
	ds_read_b128 v[6:9], v243 offset:1024
	ds_read_b128 v[10:13], v243 offset:2048
	ds_read_b128 v[18:21], v243 offset:3072
	ds_read_b128 v[26:29], v244
	ds_read_b128 v[30:33], v244 offset:1024
	ds_read_b128 v[38:41], v244 offset:2048
	ds_read_b128 v[46:49], v244 offset:3072
	s_add_u32 s62, s60, 0xfff80080
	s_addc_u32 s63, s61, -1
	s_cmp_eq_u32 s66, 12
	s_cselect_b32 s69, s3, s65
	s_cselect_b32 s68, s5, s64
	s_cselect_b32 s63, s49, s63
	s_cselect_b32 s62, s52, s62
	v_lshl_add_u64 v[162:163], s[60:61], 0, v[192:193]
	s_add_i32 m0, s71, 0xc000
	ds_read_b128 v[130:133], v245
	ds_read_b128 v[134:137], v245 offset:1024
	ds_read_b128 v[138:141], v245 offset:2048
	ds_read_b128 v[142:145], v245 offset:3072
	ds_read_b128 v[146:149], v245 offset:4096
	ds_read_b128 v[150:153], v245 offset:5120
	ds_read_b128 v[154:157], v245 offset:6144
	ds_read_b128 v[158:161], v245 offset:7168
	global_load_lds_dwordx4 v[162:163], off
	v_lshl_add_u64 v[162:163], s[60:61], 0, v[194:195]
	s_add_i32 m0, s71, 0xe000
	s_nop 0
	global_load_lds_dwordx4 v[162:163], off
	s_waitcnt vmcnt(8)
	s_waitcnt lgkmcnt(0)
	s_barrier
	s_setprio 1
	s_waitcnt lgkmcnt(0)
	v_mfma_f32_16x16x32_bf16 v[126:129], v[2:5], v[130:133], v[126:129]
	v_mfma_f32_16x16x32_bf16 v[122:125], v[10:13], v[130:133], v[122:125]
	v_mfma_f32_16x16x32_bf16 v[118:121], v[2:5], v[138:141], v[118:121]
	v_mfma_f32_16x16x32_bf16 v[114:117], v[10:13], v[138:141], v[114:117]
	v_mfma_f32_16x16x32_bf16 v[110:113], v[2:5], v[146:149], v[110:113]
	v_mfma_f32_16x16x32_bf16 v[106:109], v[10:13], v[146:149], v[106:109]
	v_mfma_f32_16x16x32_bf16 v[2:5], v[2:5], v[154:157], v[102:105]
	v_mfma_f32_16x16x32_bf16 v[126:129], v[6:9], v[134:137], v[126:129]
	v_mfma_f32_16x16x32_bf16 v[122:125], v[18:21], v[134:137], v[122:125]
	v_mfma_f32_16x16x32_bf16 v[118:121], v[6:9], v[142:145], v[118:121]
	v_mfma_f32_16x16x32_bf16 v[114:117], v[18:21], v[142:145], v[114:117]
	v_mfma_f32_16x16x32_bf16 v[110:113], v[6:9], v[150:153], v[110:113]
	v_mfma_f32_16x16x32_bf16 v[106:109], v[18:21], v[150:153], v[106:109]
	v_mfma_f32_16x16x32_bf16 v[2:5], v[6:9], v[158:161], v[2:5]
	v_mfma_f32_16x16x32_bf16 v[6:9], v[10:13], v[154:157], v[98:101]
	v_mfma_f32_16x16x32_bf16 v[6:9], v[18:21], v[158:161], v[6:9]
	v_mfma_f32_16x16x32_bf16 v[10:13], v[26:29], v[130:133], v[94:97]
	v_mfma_f32_16x16x32_bf16 v[86:89], v[26:29], v[138:141], v[86:89]
	v_mfma_f32_16x16x32_bf16 v[82:85], v[38:41], v[138:141], v[82:85]
	v_mfma_f32_16x16x32_bf16 v[78:81], v[26:29], v[146:149], v[78:81]
	v_mfma_f32_16x16x32_bf16 v[74:77], v[38:41], v[146:149], v[74:77]
	v_mfma_f32_16x16x32_bf16 v[26:29], v[26:29], v[154:157], v[70:73]
	v_mfma_f32_16x16x32_bf16 v[10:13], v[30:33], v[134:137], v[10:13]
	v_mfma_f32_16x16x32_bf16 v[18:21], v[38:41], v[130:133], v[90:93]
	v_mfma_f32_16x16x32_bf16 v[86:89], v[30:33], v[142:145], v[86:89]
	v_mfma_f32_16x16x32_bf16 v[82:85], v[46:49], v[142:145], v[82:85]
	v_mfma_f32_16x16x32_bf16 v[78:81], v[30:33], v[150:153], v[78:81]
	v_mfma_f32_16x16x32_bf16 v[74:77], v[46:49], v[150:153], v[74:77]
	v_mfma_f32_16x16x32_bf16 v[26:29], v[30:33], v[158:161], v[26:29]
	v_mfma_f32_16x16x32_bf16 v[30:33], v[38:41], v[154:157], v[66:69]
	v_mfma_f32_16x16x32_bf16 v[18:21], v[46:49], v[134:137], v[18:21]
	v_mfma_f32_16x16x32_bf16 v[30:33], v[46:49], v[158:161], v[30:33]
	s_setprio 0
	s_barrier
	s_add_i32 s67, s74, s70
	v_lshl_add_u64 v[178:179], s[62:63], 0, v[184:185]
	s_mov_b32 m0, s67
	ds_read_b128 v[38:41], v246 offset:16384
	ds_read_b128 v[46:49], v246 offset:17408
	ds_read_b128 v[66:69], v246 offset:18432
	ds_read_b128 v[70:73], v246 offset:19456
	global_load_lds_dwordx4 v[178:179], off
	s_add_i32 m0, s67, 0x2000
	s_add_u32 s72, s62, 0x40000
	v_lshl_add_u64 v[180:181], s[62:63], 0, v[188:189]
	s_addc_u32 s73, s63, 0
	s_add_i32 s67, s75, s70
	global_load_lds_dwordx4 v[180:181], off
	v_lshl_add_u64 v[90:91], s[72:73], 0, v[184:185]
	s_mov_b32 m0, s67
	v_lshl_add_u64 v[198:199], s[68:69], 0, v[182:183]
	global_load_lds_dwordx4 v[90:91], off
	v_lshl_add_u64 v[90:91], s[72:73], 0, v[188:189]
	s_add_i32 m0, s67, 0x2000
	v_lshl_add_u64 v[200:201], s[68:69], 0, v[186:187]
	global_load_lds_dwordx4 v[90:91], off
	s_mov_b32 m0, s71
	s_nop 0
	global_load_lds_dwordx4 v[198:199], off
	s_mov_b32 m0, s76
	s_nop 0
	global_load_lds_dwordx4 v[200:201], off
	s_waitcnt vmcnt(8)
	s_waitcnt lgkmcnt(0)
	s_barrier
	s_setprio 1
	s_waitcnt lgkmcnt(0)
	v_mfma_f32_16x16x32_bf16 v[62:65], v[38:41], v[130:133], v[62:65]
	v_mfma_f32_16x16x32_bf16 v[58:61], v[66:69], v[130:133], v[58:61]
	v_mfma_f32_16x16x32_bf16 v[54:57], v[38:41], v[138:141], v[54:57]
	v_mfma_f32_16x16x32_bf16 v[50:53], v[66:69], v[138:141], v[50:53]
	v_mfma_f32_16x16x32_bf16 v[42:45], v[38:41], v[146:149], v[42:45]
	v_mfma_f32_16x16x32_bf16 v[34:37], v[66:69], v[146:149], v[34:37]
	v_mfma_f32_16x16x32_bf16 v[22:25], v[38:41], v[154:157], v[22:25]
	v_mfma_f32_16x16x32_bf16 v[14:17], v[66:69], v[154:157], v[14:17]
	v_mfma_f32_16x16x32_bf16 v[62:65], v[46:49], v[134:137], v[62:65]
	v_mfma_f32_16x16x32_bf16 v[58:61], v[70:73], v[134:137], v[58:61]
	v_mfma_f32_16x16x32_bf16 v[54:57], v[46:49], v[142:145], v[54:57]
	v_mfma_f32_16x16x32_bf16 v[50:53], v[70:73], v[142:145], v[50:53]
	v_mfma_f32_16x16x32_bf16 v[42:45], v[46:49], v[150:153], v[42:45]
	v_mfma_f32_16x16x32_bf16 v[34:37], v[70:73], v[150:153], v[34:37]
	v_mfma_f32_16x16x32_bf16 v[22:25], v[46:49], v[158:161], v[22:25]
	v_mfma_f32_16x16x32_bf16 v[14:17], v[70:73], v[158:161], v[14:17]
	s_setprio 0
	s_barrier
	s_add_i32 s67, 0, 0x18000
	v_add_u32_e32 v1, s67, v241
	s_add_i32 s72, 0, 0x1c000
	ds_read_b128 v[38:41], v1
	ds_read_b128 v[46:49], v1 offset:1024
	ds_read_b128 v[66:69], v1 offset:2048
	ds_read_b128 v[70:73], v1 offset:3072
	v_add_u32_e32 v1, s72, v241
	ds_read_b128 v[130:133], v1
	ds_read_b128 v[134:137], v1 offset:1024
	ds_read_b128 v[138:141], v1 offset:2048
	ds_read_b128 v[142:145], v1 offset:3072
	s_add_u32 s68, s62, 0x80000
	s_addc_u32 s69, s63, 0
	s_mov_b32 m0, s77
	v_lshl_add_u64 v[90:91], s[68:69], 0, v[184:185]
	ds_read_b128 v[146:149], v245 offset:32768
	ds_read_b128 v[150:153], v245 offset:33792
	ds_read_b128 v[154:157], v245 offset:34816
	ds_read_b128 v[158:161], v245 offset:35840
	ds_read_b128 v[162:165], v245 offset:36864
	ds_read_b128 v[166:169], v245 offset:37888
	ds_read_b128 v[170:173], v245 offset:38912
	ds_read_b128 v[174:177], v245 offset:39936
	global_load_lds_dwordx4 v[90:91], off
	v_lshl_add_u64 v[90:91], s[68:69], 0, v[188:189]
	s_mov_b32 m0, s78
	s_nop 0
	global_load_lds_dwordx4 v[90:91], off
	s_waitcnt vmcnt(8)
	s_waitcnt lgkmcnt(0)
	s_barrier
	s_setprio 1
	s_waitcnt lgkmcnt(0)
	v_mfma_f32_16x16x32_bf16 v[90:93], v[38:41], v[146:149], v[126:129]
	v_mfma_f32_16x16x32_bf16 v[126:129], v[46:49], v[150:153], v[90:93]
	v_mfma_f32_16x16x32_bf16 v[90:93], v[66:69], v[146:149], v[122:125]
	v_mfma_f32_16x16x32_bf16 v[122:125], v[70:73], v[150:153], v[90:93]
	v_mfma_f32_16x16x32_bf16 v[90:93], v[38:41], v[154:157], v[118:121]
	v_mfma_f32_16x16x32_bf16 v[118:121], v[46:49], v[158:161], v[90:93]
	v_mfma_f32_16x16x32_bf16 v[90:93], v[66:69], v[154:157], v[114:117]
	v_mfma_f32_16x16x32_bf16 v[114:117], v[70:73], v[158:161], v[90:93]
	v_mfma_f32_16x16x32_bf16 v[90:93], v[38:41], v[162:165], v[110:113]
	v_mfma_f32_16x16x32_bf16 v[2:5], v[38:41], v[170:173], v[2:5]
	v_mfma_f32_16x16x32_bf16 v[110:113], v[46:49], v[166:169], v[90:93]
	v_mfma_f32_16x16x32_bf16 v[90:93], v[66:69], v[162:165], v[106:109]
	v_mfma_f32_16x16x32_bf16 v[102:105], v[46:49], v[174:177], v[2:5]
	v_mfma_f32_16x16x32_bf16 v[2:5], v[66:69], v[170:173], v[6:9]
	v_mfma_f32_16x16x32_bf16 v[106:109], v[70:73], v[166:169], v[90:93]
	v_mfma_f32_16x16x32_bf16 v[98:101], v[70:73], v[174:177], v[2:5]
	v_mfma_f32_16x16x32_bf16 v[2:5], v[130:133], v[146:149], v[10:13]
	v_mfma_f32_16x16x32_bf16 v[94:97], v[134:137], v[150:153], v[2:5]
	v_mfma_f32_16x16x32_bf16 v[2:5], v[138:141], v[146:149], v[18:21]
	v_mfma_f32_16x16x32_bf16 v[90:93], v[142:145], v[150:153], v[2:5]
	v_mfma_f32_16x16x32_bf16 v[2:5], v[130:133], v[154:157], v[86:89]
	v_mfma_f32_16x16x32_bf16 v[86:89], v[134:137], v[158:161], v[2:5]
	v_mfma_f32_16x16x32_bf16 v[2:5], v[138:141], v[154:157], v[82:85]
	v_mfma_f32_16x16x32_bf16 v[82:85], v[142:145], v[158:161], v[2:5]
	v_mfma_f32_16x16x32_bf16 v[2:5], v[130:133], v[162:165], v[78:81]
	v_mfma_f32_16x16x32_bf16 v[78:81], v[134:137], v[166:169], v[2:5]
	v_mfma_f32_16x16x32_bf16 v[2:5], v[138:141], v[162:165], v[74:77]
	v_mfma_f32_16x16x32_bf16 v[74:77], v[142:145], v[166:169], v[2:5]
	v_mfma_f32_16x16x32_bf16 v[2:5], v[130:133], v[170:173], v[26:29]
	v_mfma_f32_16x16x32_bf16 v[70:73], v[134:137], v[174:177], v[2:5]
	v_mfma_f32_16x16x32_bf16 v[2:5], v[138:141], v[170:173], v[30:33]
	v_mfma_f32_16x16x32_bf16 v[66:69], v[142:145], v[174:177], v[2:5]
	s_setprio 0
	s_barrier
	s_add_i32 s67, s67, s70
	v_lshl_add_u64 v[26:27], v[178:179], 0, s[38:39]
	s_mov_b32 m0, s67
	s_nop 1
	ds_read_b128 v[2:5], v246 offset:49152
	ds_read_b128 v[6:9], v246 offset:50176
	ds_read_b128 v[10:13], v246 offset:51200
	ds_read_b128 v[18:21], v246 offset:52224
	global_load_lds_dwordx4 v[26:27], off
	s_add_i32 m0, s67, 0x2000
	s_add_u32 s62, s62, 0x40080
	v_lshl_add_u64 v[26:27], v[180:181], 0, s[38:39]
	s_addc_u32 s63, s63, 0
	s_add_i32 s67, s72, s70
	global_load_lds_dwordx4 v[26:27], off
	v_lshl_add_u64 v[26:27], s[62:63], 0, v[184:185]
	s_mov_b32 m0, s67
	s_nop 0
	global_load_lds_dwordx4 v[26:27], off
	v_lshl_add_u64 v[26:27], s[62:63], 0, v[188:189]
	s_add_i32 m0, s67, 0x2000
	s_nop 0
	global_load_lds_dwordx4 v[26:27], off
	v_lshl_add_u64 v[26:27], v[198:199], 0, s[38:39]
	s_mov_b32 m0, s79
	s_nop 0
	global_load_lds_dwordx4 v[26:27], off
	v_lshl_add_u64 v[26:27], v[200:201], 0, s[38:39]
	s_mov_b32 m0, s80
	s_nop 0
	global_load_lds_dwordx4 v[26:27], off
	s_waitcnt vmcnt(8)
	s_waitcnt lgkmcnt(0)
	s_barrier
	s_setprio 1
	s_waitcnt lgkmcnt(0)
	v_mfma_f32_16x16x32_bf16 v[26:29], v[2:5], v[146:149], v[62:65]
	v_mfma_f32_16x16x32_bf16 v[62:65], v[6:9], v[150:153], v[26:29]
	v_mfma_f32_16x16x32_bf16 v[26:29], v[10:13], v[146:149], v[58:61]
	v_mfma_f32_16x16x32_bf16 v[58:61], v[18:21], v[150:153], v[26:29]
	v_mfma_f32_16x16x32_bf16 v[26:29], v[2:5], v[154:157], v[54:57]
	v_mfma_f32_16x16x32_bf16 v[54:57], v[6:9], v[158:161], v[26:29]
	v_mfma_f32_16x16x32_bf16 v[26:29], v[10:13], v[154:157], v[50:53]
	v_mfma_f32_16x16x32_bf16 v[50:53], v[18:21], v[158:161], v[26:29]
	v_mfma_f32_16x16x32_bf16 v[26:29], v[2:5], v[162:165], v[42:45]
	v_mfma_f32_16x16x32_bf16 v[2:5], v[2:5], v[170:173], v[22:25]
	v_mfma_f32_16x16x32_bf16 v[42:45], v[6:9], v[166:169], v[26:29]
	v_mfma_f32_16x16x32_bf16 v[26:29], v[10:13], v[162:165], v[34:37]
	v_mfma_f32_16x16x32_bf16 v[22:25], v[6:9], v[174:177], v[2:5]
	v_mfma_f32_16x16x32_bf16 v[2:5], v[10:13], v[170:173], v[14:17]
	v_mfma_f32_16x16x32_bf16 v[34:37], v[18:21], v[166:169], v[26:29]
	v_mfma_f32_16x16x32_bf16 v[14:17], v[18:21], v[174:177], v[2:5]
	s_setprio 0
	s_barrier
	s_add_i32 s66, s66, 2
	s_add_u32 s64, s64, 0x100
	s_addc_u32 s65, s65, 0
	s_add_u32 s60, s60, 0x100
	s_addc_u32 s61, s61, 0
	s_cmp_gt_u32 s66, 13
	s_cbranch_scc0 .LBB0_1749
	s_branch .LBB0_1801

.LBB0_1752:
	ds_read_b128 v[130:133], v243
	ds_read_b128 v[134:137], v243 offset:1024
	ds_read_b128 v[138:141], v243 offset:2048
	ds_read_b128 v[142:145], v243 offset:3072
	ds_read_b128 v[146:149], v244
	ds_read_b128 v[150:153], v244 offset:1024
	ds_read_b128 v[154:157], v244 offset:2048
	ds_read_b128 v[158:161], v244 offset:3072
	s_add_u32 s66, s8, 0xfffc0080
	s_addc_u32 s67, s9, -1
	s_cmp_eq_u32 s72, 12
	s_cselect_b64 s[64:65], -1, 0
	s_and_b64 s[62:63], s[64:65], exec
	s_cselect_b32 s63, s49, s55
	s_cselect_b32 s62, s52, s53
	s_cselect_b32 s67, s3, s67
	s_cselect_b32 s66, s5, s66
	v_lshl_add_u64 v[210:211], s[8:9], 0, v[196:197]
	s_add_i32 m0, s71, 0xc000
	ds_read_b128 v[162:165], v245
	ds_read_b128 v[166:169], v245 offset:1024
	ds_read_b128 v[170:173], v245 offset:2048
	ds_read_b128 v[174:177], v245 offset:3072
	ds_read_b128 v[178:181], v245 offset:4096
	ds_read_b128 v[198:201], v245 offset:5120
	ds_read_b128 v[202:205], v245 offset:6144
	ds_read_b128 v[206:209], v245 offset:7168
	global_load_lds_dwordx4 v[210:211], off
	v_lshl_add_u64 v[210:211], s[8:9], 0, v[186:187]
	s_add_i32 m0, s71, 0xe000
	s_nop 0
	global_load_lds_dwordx4 v[210:211], off
	s_waitcnt vmcnt(8)
	s_waitcnt lgkmcnt(0)
	s_barrier
	s_setprio 1
	s_waitcnt lgkmcnt(0)
	v_mfma_f32_16x16x32_bf16 v[126:129], v[130:133], v[162:165], v[126:129]
	v_mfma_f32_16x16x32_bf16 v[122:125], v[138:141], v[162:165], v[122:125]
	v_mfma_f32_16x16x32_bf16 v[118:121], v[130:133], v[170:173], v[118:121]
	v_mfma_f32_16x16x32_bf16 v[114:117], v[138:141], v[170:173], v[114:117]
	v_mfma_f32_16x16x32_bf16 v[110:113], v[130:133], v[178:181], v[110:113]
	v_mfma_f32_16x16x32_bf16 v[106:109], v[138:141], v[178:181], v[106:109]
	v_mfma_f32_16x16x32_bf16 v[102:105], v[130:133], v[202:205], v[102:105]
	v_mfma_f32_16x16x32_bf16 v[98:101], v[138:141], v[202:205], v[98:101]
	v_mfma_f32_16x16x32_bf16 v[126:129], v[134:137], v[166:169], v[126:129]
	v_mfma_f32_16x16x32_bf16 v[122:125], v[142:145], v[166:169], v[122:125]
	v_mfma_f32_16x16x32_bf16 v[118:121], v[134:137], v[174:177], v[118:121]
	v_mfma_f32_16x16x32_bf16 v[114:117], v[142:145], v[174:177], v[114:117]
	v_mfma_f32_16x16x32_bf16 v[110:113], v[134:137], v[198:201], v[110:113]
	v_mfma_f32_16x16x32_bf16 v[106:109], v[142:145], v[198:201], v[106:109]
	v_mfma_f32_16x16x32_bf16 v[102:105], v[134:137], v[206:209], v[102:105]
	v_mfma_f32_16x16x32_bf16 v[98:101], v[142:145], v[206:209], v[98:101]
	v_mfma_f32_16x16x32_bf16 v[94:97], v[146:149], v[162:165], v[94:97]
	v_mfma_f32_16x16x32_bf16 v[90:93], v[154:157], v[162:165], v[90:93]
	v_mfma_f32_16x16x32_bf16 v[86:89], v[146:149], v[170:173], v[86:89]
	v_mfma_f32_16x16x32_bf16 v[82:85], v[154:157], v[170:173], v[82:85]
	v_mfma_f32_16x16x32_bf16 v[78:81], v[146:149], v[178:181], v[78:81]
	v_mfma_f32_16x16x32_bf16 v[74:77], v[154:157], v[178:181], v[74:77]
	v_mfma_f32_16x16x32_bf16 v[70:73], v[146:149], v[202:205], v[70:73]
	v_mfma_f32_16x16x32_bf16 v[66:69], v[154:157], v[202:205], v[66:69]
	v_mfma_f32_16x16x32_bf16 v[94:97], v[150:153], v[166:169], v[94:97]
	v_mfma_f32_16x16x32_bf16 v[90:93], v[158:161], v[166:169], v[90:93]
	v_mfma_f32_16x16x32_bf16 v[86:89], v[150:153], v[174:177], v[86:89]
	v_mfma_f32_16x16x32_bf16 v[82:85], v[158:161], v[174:177], v[82:85]
	v_mfma_f32_16x16x32_bf16 v[78:81], v[150:153], v[198:201], v[78:81]
	v_mfma_f32_16x16x32_bf16 v[74:77], v[158:161], v[198:201], v[74:77]
	v_mfma_f32_16x16x32_bf16 v[70:73], v[150:153], v[206:209], v[70:73]
	v_mfma_f32_16x16x32_bf16 v[66:69], v[158:161], v[206:209], v[66:69]
	s_setprio 0
	s_barrier
	s_add_i32 s73, s74, s70
	v_lshl_add_u64 v[210:211], s[62:63], 0, v[184:185]
	s_mov_b32 m0, s73
	ds_read_b128 v[162:165], v245 offset:16384
	ds_read_b128 v[166:169], v245 offset:17408
	ds_read_b128 v[170:173], v245 offset:18432
	ds_read_b128 v[174:177], v245 offset:19456
	ds_read_b128 v[178:181], v245 offset:20480
	ds_read_b128 v[198:201], v245 offset:21504
	ds_read_b128 v[202:205], v245 offset:22528
	ds_read_b128 v[206:209], v245 offset:23552
	global_load_lds_dwordx4 v[210:211], off
	s_add_i32 m0, s73, 0x2000
	s_add_u32 vcc_lo, s62, 0x40000
	v_lshl_add_u64 v[212:213], s[62:63], 0, v[188:189]
	s_addc_u32 vcc_hi, s63, 0
	s_add_i32 s73, s75, s70
	global_load_lds_dwordx4 v[212:213], off
	v_lshl_add_u64 v[214:215], vcc, 0, v[184:185]
	s_mov_b32 m0, s73
	v_lshl_add_u64 v[216:217], s[66:67], 0, v[186:187]
	global_load_lds_dwordx4 v[214:215], off
	v_lshl_add_u64 v[214:215], vcc, 0, v[188:189]
	s_add_i32 m0, s73, 0x2000
	s_nop 0
	global_load_lds_dwordx4 v[214:215], off
	v_lshl_add_u64 v[214:215], s[66:67], 0, v[182:183]
	s_mov_b32 m0, s71
	s_nop 0
	global_load_lds_dwordx4 v[214:215], off
	s_mov_b32 m0, s76
	s_nop 0
	global_load_lds_dwordx4 v[216:217], off
	s_waitcnt vmcnt(8)
	s_waitcnt lgkmcnt(0)
	s_barrier
	s_setprio 1
	s_waitcnt lgkmcnt(0)
	v_mfma_f32_16x16x32_bf16 v[62:65], v[130:133], v[162:165], v[62:65]
	v_mfma_f32_16x16x32_bf16 v[58:61], v[138:141], v[162:165], v[58:61]
	v_mfma_f32_16x16x32_bf16 v[54:57], v[130:133], v[170:173], v[54:57]
	v_mfma_f32_16x16x32_bf16 v[50:53], v[138:141], v[170:173], v[50:53]
	v_mfma_f32_16x16x32_bf16 v[42:45], v[130:133], v[178:181], v[42:45]
	v_mfma_f32_16x16x32_bf16 v[34:37], v[138:141], v[178:181], v[34:37]
	v_mfma_f32_16x16x32_bf16 v[22:25], v[130:133], v[202:205], v[22:25]
	v_mfma_f32_16x16x32_bf16 v[14:17], v[138:141], v[202:205], v[14:17]
	v_mfma_f32_16x16x32_bf16 v[62:65], v[134:137], v[166:169], v[62:65]
	v_mfma_f32_16x16x32_bf16 v[58:61], v[142:145], v[166:169], v[58:61]
	v_mfma_f32_16x16x32_bf16 v[54:57], v[134:137], v[174:177], v[54:57]
	v_mfma_f32_16x16x32_bf16 v[50:53], v[142:145], v[174:177], v[50:53]
	v_mfma_f32_16x16x32_bf16 v[42:45], v[134:137], v[198:201], v[42:45]
	v_mfma_f32_16x16x32_bf16 v[34:37], v[142:145], v[198:201], v[34:37]
	v_mfma_f32_16x16x32_bf16 v[22:25], v[134:137], v[206:209], v[22:25]
	v_mfma_f32_16x16x32_bf16 v[14:17], v[142:145], v[206:209], v[14:17]
	v_mfma_f32_16x16x32_bf16 v[46:49], v[146:149], v[162:165], v[46:49]
	v_mfma_f32_16x16x32_bf16 v[38:41], v[154:157], v[162:165], v[38:41]
	v_mfma_f32_16x16x32_bf16 v[30:33], v[146:149], v[170:173], v[30:33]
	v_mfma_f32_16x16x32_bf16 v[26:29], v[154:157], v[170:173], v[26:29]
	v_mfma_f32_16x16x32_bf16 v[18:21], v[146:149], v[178:181], v[18:21]
	v_mfma_f32_16x16x32_bf16 v[10:13], v[154:157], v[178:181], v[10:13]
	v_mfma_f32_16x16x32_bf16 v[6:9], v[146:149], v[202:205], v[6:9]
	v_mfma_f32_16x16x32_bf16 v[2:5], v[154:157], v[202:205], v[2:5]
	v_mfma_f32_16x16x32_bf16 v[46:49], v[150:153], v[166:169], v[46:49]
	v_mfma_f32_16x16x32_bf16 v[38:41], v[158:161], v[166:169], v[38:41]
	v_mfma_f32_16x16x32_bf16 v[30:33], v[150:153], v[174:177], v[30:33]
	v_mfma_f32_16x16x32_bf16 v[26:29], v[158:161], v[174:177], v[26:29]
	v_mfma_f32_16x16x32_bf16 v[18:21], v[150:153], v[198:201], v[18:21]
	v_mfma_f32_16x16x32_bf16 v[10:13], v[158:161], v[198:201], v[10:13]
	v_mfma_f32_16x16x32_bf16 v[6:9], v[150:153], v[206:209], v[6:9]
	v_mfma_f32_16x16x32_bf16 v[2:5], v[158:161], v[206:209], v[2:5]
	s_setprio 0
	s_barrier
	s_add_i32 s73, 0, 0x18000
	v_add_u32_e32 v1, s73, v241
	s_add_i32 s96, 0, 0x1c000
	ds_read_b128 v[130:133], v1
	ds_read_b128 v[134:137], v1 offset:1024
	ds_read_b128 v[138:141], v1 offset:2048
	ds_read_b128 v[142:145], v1 offset:3072
	v_add_u32_e32 v1, s96, v241
	ds_read_b128 v[146:149], v1
	ds_read_b128 v[150:153], v1 offset:1024
	ds_read_b128 v[154:157], v1 offset:2048
	ds_read_b128 v[158:161], v1 offset:3072
	s_and_b64 s[64:65], s[50:51], s[64:65]
	s_and_b64 vcc, s[64:65], s[60:61]
	s_add_u32 s66, s66, 0x40000
	s_addc_u32 s67, s67, 0
	s_and_b64 s[64:65], vcc, exec
	s_mov_b32 m0, s77
	v_cndmask_b32_e32 v1, v182, v184, vcc
	s_cselect_b32 s65, s69, s67
	s_cselect_b32 s64, s68, s66
	ds_read_b128 v[162:165], v245 offset:32768
	ds_read_b128 v[166:169], v245 offset:33792
	ds_read_b128 v[170:173], v245 offset:34816
	ds_read_b128 v[174:177], v245 offset:35840
	ds_read_b128 v[178:181], v245 offset:36864
	ds_read_b128 v[198:201], v245 offset:37888
	ds_read_b128 v[202:205], v245 offset:38912
	ds_read_b128 v[206:209], v245 offset:39936
	v_cndmask_b32_e32 v218, v186, v188, vcc
	global_load_lds_dwordx4 v1, s[64:65]
	s_mov_b32 m0, s78
	s_nop 0
	global_load_lds_dwordx4 v218, s[64:65]
	s_waitcnt vmcnt(8)
	s_waitcnt lgkmcnt(0)
	s_barrier
	s_setprio 1
	s_waitcnt lgkmcnt(0)
	v_mfma_f32_16x16x32_bf16 v[126:129], v[130:133], v[162:165], v[126:129]
	v_mfma_f32_16x16x32_bf16 v[122:125], v[138:141], v[162:165], v[122:125]
	v_mfma_f32_16x16x32_bf16 v[118:121], v[130:133], v[170:173], v[118:121]
	v_mfma_f32_16x16x32_bf16 v[114:117], v[138:141], v[170:173], v[114:117]
	v_mfma_f32_16x16x32_bf16 v[110:113], v[130:133], v[178:181], v[110:113]
	v_mfma_f32_16x16x32_bf16 v[106:109], v[138:141], v[178:181], v[106:109]
	v_mfma_f32_16x16x32_bf16 v[102:105], v[130:133], v[202:205], v[102:105]
	v_mfma_f32_16x16x32_bf16 v[98:101], v[138:141], v[202:205], v[98:101]
	v_mfma_f32_16x16x32_bf16 v[126:129], v[134:137], v[166:169], v[126:129]
	v_mfma_f32_16x16x32_bf16 v[122:125], v[142:145], v[166:169], v[122:125]
	v_mfma_f32_16x16x32_bf16 v[118:121], v[134:137], v[174:177], v[118:121]
	v_mfma_f32_16x16x32_bf16 v[114:117], v[142:145], v[174:177], v[114:117]
	v_mfma_f32_16x16x32_bf16 v[110:113], v[134:137], v[198:201], v[110:113]
	v_mfma_f32_16x16x32_bf16 v[106:109], v[142:145], v[198:201], v[106:109]
	v_mfma_f32_16x16x32_bf16 v[102:105], v[134:137], v[206:209], v[102:105]
	v_mfma_f32_16x16x32_bf16 v[98:101], v[142:145], v[206:209], v[98:101]
	v_mfma_f32_16x16x32_bf16 v[94:97], v[146:149], v[162:165], v[94:97]
	v_mfma_f32_16x16x32_bf16 v[90:93], v[154:157], v[162:165], v[90:93]
	v_mfma_f32_16x16x32_bf16 v[86:89], v[146:149], v[170:173], v[86:89]
	v_mfma_f32_16x16x32_bf16 v[82:85], v[154:157], v[170:173], v[82:85]
	v_mfma_f32_16x16x32_bf16 v[78:81], v[146:149], v[178:181], v[78:81]
	v_mfma_f32_16x16x32_bf16 v[74:77], v[154:157], v[178:181], v[74:77]
	v_mfma_f32_16x16x32_bf16 v[70:73], v[146:149], v[202:205], v[70:73]
	v_mfma_f32_16x16x32_bf16 v[66:69], v[154:157], v[202:205], v[66:69]
	v_mfma_f32_16x16x32_bf16 v[94:97], v[150:153], v[166:169], v[94:97]
	v_mfma_f32_16x16x32_bf16 v[90:93], v[158:161], v[166:169], v[90:93]
	v_mfma_f32_16x16x32_bf16 v[86:89], v[150:153], v[174:177], v[86:89]
	v_mfma_f32_16x16x32_bf16 v[82:85], v[158:161], v[174:177], v[82:85]
	v_mfma_f32_16x16x32_bf16 v[78:81], v[150:153], v[198:201], v[78:81]
	v_mfma_f32_16x16x32_bf16 v[74:77], v[158:161], v[198:201], v[74:77]
	v_mfma_f32_16x16x32_bf16 v[70:73], v[150:153], v[206:209], v[70:73]
	v_mfma_f32_16x16x32_bf16 v[66:69], v[158:161], v[206:209], v[66:69]
	s_setprio 0
	s_barrier
	s_add_i32 s64, s73, s70
	v_lshl_add_u64 v[210:211], v[210:211], 0, s[38:39]
	s_mov_b32 m0, s64
	ds_read_b128 v[162:165], v245 offset:49152
	ds_read_b128 v[166:169], v245 offset:50176
	ds_read_b128 v[170:173], v245 offset:51200
	ds_read_b128 v[174:177], v245 offset:52224
	ds_read_b128 v[178:181], v245 offset:53248
	ds_read_b128 v[198:201], v245 offset:54272
	ds_read_b128 v[202:205], v245 offset:55296
	ds_read_b128 v[206:209], v245 offset:56320
	global_load_lds_dwordx4 v[210:211], off
	s_add_i32 m0, s64, 0x2000
	s_add_u32 s62, s62, 0x40080
	v_lshl_add_u64 v[210:211], v[212:213], 0, s[38:39]
	s_addc_u32 s63, s63, 0
	s_add_i32 s64, s96, s70
	global_load_lds_dwordx4 v[210:211], off
	v_lshl_add_u64 v[210:211], s[62:63], 0, v[184:185]
	s_mov_b32 m0, s64
	s_nop 0
	global_load_lds_dwordx4 v[210:211], off
	v_lshl_add_u64 v[210:211], s[62:63], 0, v[188:189]
	s_add_i32 m0, s64, 0x2000
	s_nop 0
	global_load_lds_dwordx4 v[210:211], off
	v_lshl_add_u64 v[210:211], v[214:215], 0, s[38:39]
	s_mov_b32 m0, s79
	s_nop 0
	global_load_lds_dwordx4 v[210:211], off
	v_lshl_add_u64 v[210:211], v[216:217], 0, s[38:39]
	s_mov_b32 m0, s80
	s_nop 0
	global_load_lds_dwordx4 v[210:211], off
	s_waitcnt vmcnt(8)
	s_waitcnt lgkmcnt(0)
	s_barrier
	s_setprio 1
	s_waitcnt lgkmcnt(0)
	v_mfma_f32_16x16x32_bf16 v[62:65], v[130:133], v[162:165], v[62:65]
	v_mfma_f32_16x16x32_bf16 v[58:61], v[138:141], v[162:165], v[58:61]
	v_mfma_f32_16x16x32_bf16 v[54:57], v[130:133], v[170:173], v[54:57]
	v_mfma_f32_16x16x32_bf16 v[50:53], v[138:141], v[170:173], v[50:53]
	v_mfma_f32_16x16x32_bf16 v[42:45], v[130:133], v[178:181], v[42:45]
	v_mfma_f32_16x16x32_bf16 v[34:37], v[138:141], v[178:181], v[34:37]
	v_mfma_f32_16x16x32_bf16 v[22:25], v[130:133], v[202:205], v[22:25]
	v_mfma_f32_16x16x32_bf16 v[14:17], v[138:141], v[202:205], v[14:17]
	v_mfma_f32_16x16x32_bf16 v[62:65], v[134:137], v[166:169], v[62:65]
	v_mfma_f32_16x16x32_bf16 v[58:61], v[142:145], v[166:169], v[58:61]
	v_mfma_f32_16x16x32_bf16 v[54:57], v[134:137], v[174:177], v[54:57]
	v_mfma_f32_16x16x32_bf16 v[50:53], v[142:145], v[174:177], v[50:53]
	v_mfma_f32_16x16x32_bf16 v[42:45], v[134:137], v[198:201], v[42:45]
	v_mfma_f32_16x16x32_bf16 v[34:37], v[142:145], v[198:201], v[34:37]
	v_mfma_f32_16x16x32_bf16 v[22:25], v[134:137], v[206:209], v[22:25]
	v_mfma_f32_16x16x32_bf16 v[14:17], v[142:145], v[206:209], v[14:17]
	v_mfma_f32_16x16x32_bf16 v[46:49], v[146:149], v[162:165], v[46:49]
	v_mfma_f32_16x16x32_bf16 v[38:41], v[154:157], v[162:165], v[38:41]
	v_mfma_f32_16x16x32_bf16 v[30:33], v[146:149], v[170:173], v[30:33]
	v_mfma_f32_16x16x32_bf16 v[26:29], v[154:157], v[170:173], v[26:29]
	v_mfma_f32_16x16x32_bf16 v[18:21], v[146:149], v[178:181], v[18:21]
	v_mfma_f32_16x16x32_bf16 v[10:13], v[154:157], v[178:181], v[10:13]
	v_mfma_f32_16x16x32_bf16 v[6:9], v[146:149], v[202:205], v[6:9]
	v_mfma_f32_16x16x32_bf16 v[2:5], v[154:157], v[202:205], v[2:5]
	v_mfma_f32_16x16x32_bf16 v[46:49], v[150:153], v[166:169], v[46:49]
	v_mfma_f32_16x16x32_bf16 v[38:41], v[158:161], v[166:169], v[38:41]
	v_mfma_f32_16x16x32_bf16 v[30:33], v[150:153], v[174:177], v[30:33]
	v_mfma_f32_16x16x32_bf16 v[26:29], v[158:161], v[174:177], v[26:29]
	v_mfma_f32_16x16x32_bf16 v[18:21], v[150:153], v[198:201], v[18:21]
	v_mfma_f32_16x16x32_bf16 v[10:13], v[158:161], v[198:201], v[10:13]
	v_mfma_f32_16x16x32_bf16 v[6:9], v[150:153], v[206:209], v[6:9]
	v_mfma_f32_16x16x32_bf16 v[2:5], v[158:161], v[206:209], v[2:5]
	s_setprio 0
	s_barrier
	s_add_i32 s72, s72, 2
	s_add_u32 s8, s8, 0x100
	s_addc_u32 s9, s9, 0
	s_add_u32 s53, s53, 0x100
	s_addc_u32 s55, s55, 0
	s_cmp_gt_u32 s72, 13
	s_cbranch_scc0 .LBB0_1752
	s_andn2_b64 vcc, exec, s[40:41]
	s_cbranch_vccnz .LBB0_1755

.LBB0_1882:
	ds_read_b128 v[128:131], v203
	ds_read_b128 v[132:135], v203 offset:1024
	ds_read_b128 v[136:139], v203 offset:2048
	ds_read_b128 v[140:143], v203 offset:3072
	ds_read_b128 v[144:147], v204
	ds_read_b128 v[148:151], v204 offset:1024
	ds_read_b128 v[152:155], v204 offset:2048
	ds_read_b128 v[172:175], v204 offset:3072
	s_add_u32 s2, s22, 0x100
	s_addc_u32 s3, s23, 0
	s_cmp_eq_u32 s58, 40
	s_cselect_b32 s29, s21, s3
	s_cselect_b32 s28, s20, s2
	s_cselect_b32 s25, s5, s57
	s_cselect_b32 s24, s4, s56
	v_lshl_add_u64 v[214:215], s[22:23], 0, v[164:165]
	s_add_i32 m0, s39, 0xc000
	ds_read_b128 v[176:179], v205
	ds_read_b128 v[180:183], v205 offset:1024
	ds_read_b128 v[184:187], v205 offset:2048
	ds_read_b128 v[188:191], v205 offset:3072
	ds_read_b128 v[192:195], v205 offset:4096
	ds_read_b128 v[196:199], v205 offset:5120
	ds_read_b128 v[206:209], v205 offset:6144
	ds_read_b128 v[210:213], v205 offset:7168
	global_load_lds_dwordx4 v[214:215], off
	v_lshl_add_u64 v[214:215], s[22:23], 0, v[166:167]
	s_add_i32 m0, s39, 0xe000
	s_nop 0
	global_load_lds_dwordx4 v[214:215], off
	s_waitcnt vmcnt(8)
	s_waitcnt lgkmcnt(0)
	s_barrier
	s_setprio 1
	s_waitcnt lgkmcnt(0)
	v_mfma_f32_16x16x32_bf16 v[124:127], v[128:131], v[176:179], v[124:127]
	v_mfma_f32_16x16x32_bf16 v[120:123], v[136:139], v[176:179], v[120:123]
	v_mfma_f32_16x16x32_bf16 v[108:111], v[128:131], v[184:187], v[108:111]
	v_mfma_f32_16x16x32_bf16 v[104:107], v[136:139], v[184:187], v[104:107]
	v_mfma_f32_16x16x32_bf16 v[92:95], v[128:131], v[192:195], v[92:95]
	v_mfma_f32_16x16x32_bf16 v[88:91], v[136:139], v[192:195], v[88:91]
	v_mfma_f32_16x16x32_bf16 v[76:79], v[128:131], v[206:209], v[76:79]
	v_mfma_f32_16x16x32_bf16 v[72:75], v[136:139], v[206:209], v[72:75]
	v_mfma_f32_16x16x32_bf16 v[124:127], v[132:135], v[180:183], v[124:127]
	v_mfma_f32_16x16x32_bf16 v[120:123], v[140:143], v[180:183], v[120:123]
	v_mfma_f32_16x16x32_bf16 v[108:111], v[132:135], v[188:191], v[108:111]
	v_mfma_f32_16x16x32_bf16 v[104:107], v[140:143], v[188:191], v[104:107]
	v_mfma_f32_16x16x32_bf16 v[92:95], v[132:135], v[196:199], v[92:95]
	v_mfma_f32_16x16x32_bf16 v[88:91], v[140:143], v[196:199], v[88:91]
	v_mfma_f32_16x16x32_bf16 v[76:79], v[132:135], v[210:213], v[76:79]
	v_mfma_f32_16x16x32_bf16 v[72:75], v[140:143], v[210:213], v[72:75]
	v_mfma_f32_16x16x32_bf16 v[116:119], v[144:147], v[176:179], v[116:119]
	v_mfma_f32_16x16x32_bf16 v[112:115], v[152:155], v[176:179], v[112:115]
	v_mfma_f32_16x16x32_bf16 v[100:103], v[144:147], v[184:187], v[100:103]
	v_mfma_f32_16x16x32_bf16 v[96:99], v[152:155], v[184:187], v[96:99]
	v_mfma_f32_16x16x32_bf16 v[84:87], v[144:147], v[192:195], v[84:87]
	v_mfma_f32_16x16x32_bf16 v[80:83], v[152:155], v[192:195], v[80:83]
	v_mfma_f32_16x16x32_bf16 v[68:71], v[144:147], v[206:209], v[68:71]
	v_mfma_f32_16x16x32_bf16 v[64:67], v[152:155], v[206:209], v[64:67]
	v_mfma_f32_16x16x32_bf16 v[116:119], v[148:151], v[180:183], v[116:119]
	v_mfma_f32_16x16x32_bf16 v[112:115], v[172:175], v[180:183], v[112:115]
	v_mfma_f32_16x16x32_bf16 v[100:103], v[148:151], v[188:191], v[100:103]
	v_mfma_f32_16x16x32_bf16 v[96:99], v[172:175], v[188:191], v[96:99]
	v_mfma_f32_16x16x32_bf16 v[84:87], v[148:151], v[196:199], v[84:87]
	v_mfma_f32_16x16x32_bf16 v[80:83], v[172:175], v[196:199], v[80:83]
	v_mfma_f32_16x16x32_bf16 v[68:71], v[148:151], v[210:213], v[68:71]
	v_mfma_f32_16x16x32_bf16 v[64:67], v[172:175], v[210:213], v[64:67]
	s_setprio 0
	s_barrier
	s_add_i32 s22, s48, s38
	v_lshl_add_u64 v[214:215], s[24:25], 0, v[158:159]
	s_mov_b32 m0, s22
	ds_read_b128 v[176:179], v205 offset:16384
	ds_read_b128 v[180:183], v205 offset:17408
	ds_read_b128 v[184:187], v205 offset:18432
	ds_read_b128 v[188:191], v205 offset:19456
	ds_read_b128 v[192:195], v205 offset:20480
	ds_read_b128 v[196:199], v205 offset:21504
	ds_read_b128 v[206:209], v205 offset:22528
	ds_read_b128 v[210:213], v205 offset:23552
	global_load_lds_dwordx4 v[214:215], off
	s_add_i32 m0, s22, 0x2000
	s_add_u32 s22, s24, 0xb0000
	v_lshl_add_u64 v[216:217], s[24:25], 0, v[162:163]
	s_addc_u32 s23, s25, 0
	s_add_i32 s59, s49, s38
	global_load_lds_dwordx4 v[216:217], off
	v_lshl_add_u64 v[218:219], s[22:23], 0, v[158:159]
	s_mov_b32 m0, s59
	v_lshl_add_u64 v[220:221], s[28:29], 0, v[160:161]
	global_load_lds_dwordx4 v[218:219], off
	v_lshl_add_u64 v[218:219], s[22:23], 0, v[162:163]
	s_add_i32 m0, s59, 0x2000
	s_nop 0
	global_load_lds_dwordx4 v[218:219], off
	v_lshl_add_u64 v[218:219], s[28:29], 0, v[156:157]
	s_mov_b32 m0, s39
	s_nop 0
	global_load_lds_dwordx4 v[218:219], off
	s_mov_b32 m0, s40
	s_nop 0
	global_load_lds_dwordx4 v[220:221], off
	s_waitcnt vmcnt(8)
	s_waitcnt lgkmcnt(0)
	s_barrier
	s_setprio 1
	s_waitcnt lgkmcnt(0)
	v_mfma_f32_16x16x32_bf16 v[60:63], v[128:131], v[176:179], v[60:63]
	v_mfma_f32_16x16x32_bf16 v[56:59], v[136:139], v[176:179], v[56:59]
	v_mfma_f32_16x16x32_bf16 v[44:47], v[128:131], v[184:187], v[44:47]
	v_mfma_f32_16x16x32_bf16 v[40:43], v[136:139], v[184:187], v[40:43]
	v_mfma_f32_16x16x32_bf16 v[28:31], v[128:131], v[192:195], v[28:31]
	v_mfma_f32_16x16x32_bf16 v[24:27], v[136:139], v[192:195], v[24:27]
	v_mfma_f32_16x16x32_bf16 v[12:15], v[128:131], v[206:209], v[12:15]
	v_mfma_f32_16x16x32_bf16 v[8:11], v[136:139], v[206:209], v[8:11]
	v_mfma_f32_16x16x32_bf16 v[60:63], v[132:135], v[180:183], v[60:63]
	v_mfma_f32_16x16x32_bf16 v[56:59], v[140:143], v[180:183], v[56:59]
	v_mfma_f32_16x16x32_bf16 v[44:47], v[132:135], v[188:191], v[44:47]
	v_mfma_f32_16x16x32_bf16 v[40:43], v[140:143], v[188:191], v[40:43]
	v_mfma_f32_16x16x32_bf16 v[28:31], v[132:135], v[196:199], v[28:31]
	v_mfma_f32_16x16x32_bf16 v[24:27], v[140:143], v[196:199], v[24:27]
	v_mfma_f32_16x16x32_bf16 v[12:15], v[132:135], v[210:213], v[12:15]
	v_mfma_f32_16x16x32_bf16 v[8:11], v[140:143], v[210:213], v[8:11]
	v_mfma_f32_16x16x32_bf16 v[52:55], v[144:147], v[176:179], v[52:55]
	v_mfma_f32_16x16x32_bf16 v[48:51], v[152:155], v[176:179], v[48:51]
	v_mfma_f32_16x16x32_bf16 v[36:39], v[144:147], v[184:187], v[36:39]
	v_mfma_f32_16x16x32_bf16 v[32:35], v[152:155], v[184:187], v[32:35]
	v_mfma_f32_16x16x32_bf16 v[20:23], v[144:147], v[192:195], v[20:23]
	v_mfma_f32_16x16x32_bf16 v[16:19], v[152:155], v[192:195], v[16:19]
	v_mfma_f32_16x16x32_bf16 v[4:7], v[144:147], v[206:209], v[4:7]
	v_mfma_f32_16x16x32_bf16 v[0:3], v[152:155], v[206:209], v[0:3]
	v_mfma_f32_16x16x32_bf16 v[52:55], v[148:151], v[180:183], v[52:55]
	v_mfma_f32_16x16x32_bf16 v[48:51], v[172:175], v[180:183], v[48:51]
	v_mfma_f32_16x16x32_bf16 v[36:39], v[148:151], v[188:191], v[36:39]
	v_mfma_f32_16x16x32_bf16 v[32:35], v[172:175], v[188:191], v[32:35]
	v_mfma_f32_16x16x32_bf16 v[20:23], v[148:151], v[196:199], v[20:23]
	v_mfma_f32_16x16x32_bf16 v[16:19], v[172:175], v[196:199], v[16:19]
	v_mfma_f32_16x16x32_bf16 v[4:7], v[148:151], v[210:213], v[4:7]
	v_mfma_f32_16x16x32_bf16 v[0:3], v[172:175], v[210:213], v[0:3]
	s_setprio 0
	s_barrier
	s_add_i32 s59, 0, 0x18000
	s_add_i32 s60, 0, 0x1c000
	v_add_u32_e32 v140, s59, v201
	v_add_u32_e32 v172, s60, v201
	ds_read_b128 v[128:131], v140
	ds_read_b128 v[132:135], v140 offset:1024
	ds_read_b128 v[136:139], v140 offset:2048
	ds_read_b128 v[140:143], v140 offset:3072
	ds_read_b128 v[144:147], v172
	ds_read_b128 v[148:151], v172 offset:1024
	ds_read_b128 v[152:155], v172 offset:2048
	ds_read_b128 v[172:175], v172 offset:3072
	s_add_u32 s22, s28, 0xb0000
	s_addc_u32 s23, s29, 0
	s_mov_b32 m0, s41
	v_lshl_add_u64 v[222:223], s[22:23], 0, v[156:157]
	ds_read_b128 v[176:179], v205 offset:32768
	ds_read_b128 v[180:183], v205 offset:33792
	ds_read_b128 v[184:187], v205 offset:34816
	ds_read_b128 v[188:191], v205 offset:35840
	ds_read_b128 v[192:195], v205 offset:36864
	ds_read_b128 v[196:199], v205 offset:37888
	ds_read_b128 v[206:209], v205 offset:38912
	ds_read_b128 v[210:213], v205 offset:39936
	global_load_lds_dwordx4 v[222:223], off
	v_lshl_add_u64 v[222:223], s[22:23], 0, v[160:161]
	s_mov_b32 m0, s42
	s_nop 0
	global_load_lds_dwordx4 v[222:223], off
	s_waitcnt vmcnt(8)
	s_waitcnt lgkmcnt(0)
	s_barrier
	s_setprio 1
	s_waitcnt lgkmcnt(0)
	v_mfma_f32_16x16x32_bf16 v[124:127], v[128:131], v[176:179], v[124:127]
	v_mfma_f32_16x16x32_bf16 v[120:123], v[136:139], v[176:179], v[120:123]
	v_mfma_f32_16x16x32_bf16 v[108:111], v[128:131], v[184:187], v[108:111]
	v_mfma_f32_16x16x32_bf16 v[104:107], v[136:139], v[184:187], v[104:107]
	v_mfma_f32_16x16x32_bf16 v[92:95], v[128:131], v[192:195], v[92:95]
	v_mfma_f32_16x16x32_bf16 v[88:91], v[136:139], v[192:195], v[88:91]
	v_mfma_f32_16x16x32_bf16 v[76:79], v[128:131], v[206:209], v[76:79]
	v_mfma_f32_16x16x32_bf16 v[72:75], v[136:139], v[206:209], v[72:75]
	v_mfma_f32_16x16x32_bf16 v[124:127], v[132:135], v[180:183], v[124:127]
	v_mfma_f32_16x16x32_bf16 v[120:123], v[140:143], v[180:183], v[120:123]
	v_mfma_f32_16x16x32_bf16 v[108:111], v[132:135], v[188:191], v[108:111]
	v_mfma_f32_16x16x32_bf16 v[104:107], v[140:143], v[188:191], v[104:107]
	v_mfma_f32_16x16x32_bf16 v[92:95], v[132:135], v[196:199], v[92:95]
	v_mfma_f32_16x16x32_bf16 v[88:91], v[140:143], v[196:199], v[88:91]
	v_mfma_f32_16x16x32_bf16 v[76:79], v[132:135], v[210:213], v[76:79]
	v_mfma_f32_16x16x32_bf16 v[72:75], v[140:143], v[210:213], v[72:75]
	v_mfma_f32_16x16x32_bf16 v[116:119], v[144:147], v[176:179], v[116:119]
	v_mfma_f32_16x16x32_bf16 v[112:115], v[152:155], v[176:179], v[112:115]
	v_mfma_f32_16x16x32_bf16 v[100:103], v[144:147], v[184:187], v[100:103]
	v_mfma_f32_16x16x32_bf16 v[96:99], v[152:155], v[184:187], v[96:99]
	v_mfma_f32_16x16x32_bf16 v[84:87], v[144:147], v[192:195], v[84:87]
	v_mfma_f32_16x16x32_bf16 v[80:83], v[152:155], v[192:195], v[80:83]
	v_mfma_f32_16x16x32_bf16 v[68:71], v[144:147], v[206:209], v[68:71]
	v_mfma_f32_16x16x32_bf16 v[64:67], v[152:155], v[206:209], v[64:67]
	v_mfma_f32_16x16x32_bf16 v[116:119], v[148:151], v[180:183], v[116:119]
	v_mfma_f32_16x16x32_bf16 v[112:115], v[172:175], v[180:183], v[112:115]
	v_mfma_f32_16x16x32_bf16 v[100:103], v[148:151], v[188:191], v[100:103]
	v_mfma_f32_16x16x32_bf16 v[96:99], v[172:175], v[188:191], v[96:99]
	v_mfma_f32_16x16x32_bf16 v[84:87], v[148:151], v[196:199], v[84:87]
	v_mfma_f32_16x16x32_bf16 v[80:83], v[172:175], v[196:199], v[80:83]
	v_mfma_f32_16x16x32_bf16 v[68:71], v[148:151], v[210:213], v[68:71]
	v_mfma_f32_16x16x32_bf16 v[64:67], v[172:175], v[210:213], v[64:67]
	s_setprio 0
	s_barrier
	s_add_i32 s22, s59, s38
	v_lshl_add_u64 v[214:215], v[214:215], 0, s[6:7]
	s_mov_b32 m0, s22
	ds_read_b128 v[176:179], v205 offset:49152
	ds_read_b128 v[180:183], v205 offset:50176
	ds_read_b128 v[184:187], v205 offset:51200
	ds_read_b128 v[188:191], v205 offset:52224
	ds_read_b128 v[192:195], v205 offset:53248
	ds_read_b128 v[196:199], v205 offset:54272
	ds_read_b128 v[206:209], v205 offset:55296
	ds_read_b128 v[210:213], v205 offset:56320
	global_load_lds_dwordx4 v[214:215], off
	s_add_i32 m0, s22, 0x2000
	s_add_u32 s22, s24, 0xb0080
	v_lshl_add_u64 v[214:215], v[216:217], 0, s[6:7]
	s_addc_u32 s23, s25, 0
	s_add_i32 s24, s60, s38
	global_load_lds_dwordx4 v[214:215], off
	v_lshl_add_u64 v[214:215], s[22:23], 0, v[158:159]
	s_mov_b32 m0, s24
	s_nop 0
	global_load_lds_dwordx4 v[214:215], off
	v_lshl_add_u64 v[214:215], s[22:23], 0, v[162:163]
	s_add_i32 m0, s24, 0x2000
	s_nop 0
	global_load_lds_dwordx4 v[214:215], off
	v_lshl_add_u64 v[214:215], v[218:219], 0, s[6:7]
	s_mov_b32 m0, s44
	s_nop 0
	global_load_lds_dwordx4 v[214:215], off
	v_lshl_add_u64 v[214:215], v[220:221], 0, s[6:7]
	s_mov_b32 m0, s45
	s_nop 0
	global_load_lds_dwordx4 v[214:215], off
	s_waitcnt vmcnt(8)
	s_waitcnt lgkmcnt(0)
	s_barrier
	s_setprio 1
	s_waitcnt lgkmcnt(0)
	v_mfma_f32_16x16x32_bf16 v[60:63], v[128:131], v[176:179], v[60:63]
	v_mfma_f32_16x16x32_bf16 v[56:59], v[136:139], v[176:179], v[56:59]
	v_mfma_f32_16x16x32_bf16 v[44:47], v[128:131], v[184:187], v[44:47]
	v_mfma_f32_16x16x32_bf16 v[40:43], v[136:139], v[184:187], v[40:43]
	v_mfma_f32_16x16x32_bf16 v[28:31], v[128:131], v[192:195], v[28:31]
	v_mfma_f32_16x16x32_bf16 v[24:27], v[136:139], v[192:195], v[24:27]
	v_mfma_f32_16x16x32_bf16 v[12:15], v[128:131], v[206:209], v[12:15]
	v_mfma_f32_16x16x32_bf16 v[8:11], v[136:139], v[206:209], v[8:11]
	v_mfma_f32_16x16x32_bf16 v[60:63], v[132:135], v[180:183], v[60:63]
	v_mfma_f32_16x16x32_bf16 v[56:59], v[140:143], v[180:183], v[56:59]
	v_mfma_f32_16x16x32_bf16 v[44:47], v[132:135], v[188:191], v[44:47]
	v_mfma_f32_16x16x32_bf16 v[40:43], v[140:143], v[188:191], v[40:43]
	v_mfma_f32_16x16x32_bf16 v[28:31], v[132:135], v[196:199], v[28:31]
	v_mfma_f32_16x16x32_bf16 v[24:27], v[140:143], v[196:199], v[24:27]
	v_mfma_f32_16x16x32_bf16 v[12:15], v[132:135], v[210:213], v[12:15]
	v_mfma_f32_16x16x32_bf16 v[8:11], v[140:143], v[210:213], v[8:11]
	v_mfma_f32_16x16x32_bf16 v[52:55], v[144:147], v[176:179], v[52:55]
	v_mfma_f32_16x16x32_bf16 v[48:51], v[152:155], v[176:179], v[48:51]
	v_mfma_f32_16x16x32_bf16 v[36:39], v[144:147], v[184:187], v[36:39]
	v_mfma_f32_16x16x32_bf16 v[32:35], v[152:155], v[184:187], v[32:35]
	v_mfma_f32_16x16x32_bf16 v[20:23], v[144:147], v[192:195], v[20:23]
	v_mfma_f32_16x16x32_bf16 v[16:19], v[152:155], v[192:195], v[16:19]
	v_mfma_f32_16x16x32_bf16 v[4:7], v[144:147], v[206:209], v[4:7]
	v_mfma_f32_16x16x32_bf16 v[0:3], v[152:155], v[206:209], v[0:3]
	v_mfma_f32_16x16x32_bf16 v[52:55], v[148:151], v[180:183], v[52:55]
	v_mfma_f32_16x16x32_bf16 v[48:51], v[172:175], v[180:183], v[48:51]
	v_mfma_f32_16x16x32_bf16 v[36:39], v[148:151], v[188:191], v[36:39]
	v_mfma_f32_16x16x32_bf16 v[32:35], v[172:175], v[188:191], v[32:35]
	v_mfma_f32_16x16x32_bf16 v[20:23], v[148:151], v[196:199], v[20:23]
	v_mfma_f32_16x16x32_bf16 v[16:19], v[172:175], v[196:199], v[16:19]
	v_mfma_f32_16x16x32_bf16 v[4:7], v[148:151], v[210:213], v[4:7]
	v_mfma_f32_16x16x32_bf16 v[0:3], v[172:175], v[210:213], v[0:3]
	s_setprio 0
	s_barrier
	s_add_i32 s58, s58, 2
	s_add_u32 s56, s56, 0x100
	s_addc_u32 s57, s57, 0
	s_cmp_gt_u32 s58, 41
	s_mov_b64 s[22:23], s[2:3]
	s_cbranch_scc0 .LBB0_1882
	v_lshl_add_u32 v174, s55, 8, v200
	v_lshl_or_b32 v172, s54, 8, v202
	v_ashrrev_i32_e32 v175, 31, v174
	v_ashrrev_i32_e32 v173, 31, v172
	v_lshlrev_b64 v[128:129], 10, v[174:175]
	v_lshl_add_u64 v[198:199], v[128:129], 0, v[172:173]
	v_lshlrev_b64 v[128:129], 1, v[198:199]
	v_lshl_add_u64 v[196:197], s[34:35], 0, v[128:129]
	v_or_b32_e32 v128, 0x100, v128
	v_lshl_add_u64 v[194:195], s[34:35], 0, v[128:129]
	v_or_b32_e32 v128, 16, v174
	v_ashrrev_i32_e32 v129, 31, v128
	v_lshlrev_b64 v[128:129], 10, v[128:129]
	v_lshl_add_u64 v[192:193], v[128:129], 0, v[172:173]
	v_lshlrev_b64 v[128:129], 1, v[192:193]
	v_lshl_add_u64 v[190:191], s[34:35], 0, v[128:129]
	v_or_b32_e32 v128, 0x100, v128
	v_lshl_add_u64 v[188:189], s[34:35], 0, v[128:129]
	v_or_b32_e32 v128, 32, v174
	v_ashrrev_i32_e32 v129, 31, v128
	v_lshlrev_b64 v[128:129], 10, v[128:129]
	v_lshl_add_u64 v[186:187], v[128:129], 0, v[172:173]
	v_lshlrev_b64 v[128:129], 1, v[186:187]
	v_lshl_add_u64 v[184:185], s[34:35], 0, v[128:129]
	v_or_b32_e32 v128, 0x100, v128
	v_lshl_add_u64 v[182:183], s[34:35], 0, v[128:129]
	v_or_b32_e32 v128, 48, v174
	v_ashrrev_i32_e32 v129, 31, v128
	v_lshlrev_b64 v[128:129], 10, v[128:129]
	v_lshl_add_u64 v[180:181], v[128:129], 0, v[172:173]
	v_lshlrev_b64 v[128:129], 1, v[180:181]
	global_load_dwordx4 v[206:209], v[196:197], off
	global_load_dwordx4 v[152:155], v[194:195], off
	v_lshl_add_u64 v[178:179], s[34:35], 0, v[128:129]
	v_or_b32_e32 v128, 0x100, v128
	global_load_dwordx4 v[148:151], v[190:191], off
	global_load_dwordx4 v[144:147], v[188:189], off
	global_load_dwordx4 v[140:143], v[184:185], off
	global_load_dwordx4 v[136:139], v[182:183], off
	v_lshl_add_u64 v[176:177], s[34:35], 0, v[128:129]
	global_load_dwordx4 v[132:135], v[178:179], off
	global_load_dwordx4 v[128:131], v[176:177], off
	v_cndmask_b32_e64 v210, 0, 1, s[8:9]
	v_cmp_ne_u32_e64 s[2:3], 1, v210
	s_andn2_b64 vcc, exec, s[8:9]
	v_lshl_add_u64 v[198:199], v[198:199], 2, s[26:27]
	s_waitcnt vmcnt(0)
	v_lshlrev_b32_e32 v210, 16, v206
	v_and_b32_e32 v211, 0xffff0000, v206
	v_lshlrev_b32_e32 v206, 16, v207
	v_and_b32_e32 v207, 0xffff0000, v207
	v_lshlrev_b32_e32 v212, 16, v208
	v_and_b32_e32 v213, 0xffff0000, v208
	v_lshlrev_b32_e32 v208, 16, v209
	v_and_b32_e32 v209, 0xffff0000, v209
	v_pk_add_f32 v[126:127], v[126:127], v[206:207]
	v_pk_add_f32 v[124:125], v[124:125], v[210:211]
	v_pk_add_f32 v[122:123], v[122:123], v[208:209]
	v_pk_add_f32 v[120:121], v[120:121], v[212:213]
	s_cbranch_vccnz .LBB0_1930
	global_store_dwordx4 v[198:199], v[124:127], off nt
	global_store_dwordx4 v[198:199], v[120:123], off offset:16 nt
	s_cbranch_execnz .LBB0_1886
